# combined: SGPR-base LDS-DMA loads in all GEMM K-loops, pipelined final K-step (FFN-up), scan MFMA reschedule, early head waits removed, nx prefetch + stagger
# speedup vs baseline: 1.0029x; 1.0029x over previous
.LBB0_149:
	s_or_b64 exec, exec, s[4:5]
	s_and_b64 s[4:5], exec, s[28:29]
	s_cselect_b32 s4, 0x8000, 0
	s_add_i32 s4, s66, s4
	v_mov_b32_e32 v10, v132
	s_ashr_i32 s5, s4, 31
	s_lshl_b64 s[4:5], s[4:5], 11
	v_lshlrev_b32_e32 v1, 4, v10
	v_and_b32_e32 v0, 32, v10
	v_lshrrev_b32_e32 v2, 1, v10
	v_bitop3_b32 v0, v1, v0, 48 bitop3:0x6c
	s_add_u32 s42, s6, s4
	v_bfe_u32 v11, v10, 2, 4
	v_and_b32_e32 v12, 32, v2
	v_lshrrev_b32_e32 v13, 1, v0
	v_ashrrev_i32_e32 v14, 3, v10
	s_addc_u32 s43, s36, s5
	v_or_b32_e32 v4, v13, v12
	v_and_or_b32 v0, v14, s48, v11
	s_add_u32 s38, s42, 0x2400000
	v_and_b32_e32 v3, 0xfffffc00, v1
	v_lshl_or_b32 v134, v0, 10, v4
	v_add_u32_e32 v0, 0x2000, v1
	v_add_u32_e32 v2, 0x4000, v1
	v_add_u32_e32 v1, 0x6000, v1
	s_addc_u32 s39, s43, 0
	s_ashr_i32 s27, s26, 31
	v_ashrrev_i32_e32 v15, 7, v0
	v_ashrrev_i32_e32 v16, 7, v2
	v_ashrrev_i32_e32 v17, 7, v1
	s_lshl_b64 s[4:5], s[26:27], 19
	v_and_or_b32 v0, v15, s48, v11
	v_and_or_b32 v2, v16, s48, v11
	v_and_or_b32 v1, v17, s48, v11
	v_add_u32_e32 v148, 0, v3
	s_add_u32 s4, s6, s4
	v_lshl_or_b32 v0, v0, 10, v4
	v_lshl_or_b32 v2, v2, 10, v4
	v_lshl_or_b32 v4, v1, 10, v4
	v_add_u32_e32 v1, 0x8000, v148
	v_lshlrev_b64 v[6:7], 1, v[134:135]
	v_readfirstlane_b32 s27, v148
	s_addc_u32 s5, s36, s5
	v_lshl_add_u64 v[8:9], s[38:39], 0, v[6:7]
	s_mov_b32 m0, s27
	v_readfirstlane_b32 s27, v1
	v_mov_b32_e32 v1, v135
	v_add_u32_e32 v3, 0x2000, v148
	global_load_lds_dwordx4 v[8:9], off
	v_lshl_add_u64 v[6:7], s[4:5], 0, v[6:7]
	s_mov_b32 m0, s27
	v_lshlrev_b64 v[0:1], 1, v[0:1]
	v_readfirstlane_b32 s27, v3
	v_add_u32_e32 v3, 0xa000, v148
	global_load_lds_dwordx4 v[6:7], off
	v_lshl_add_u64 v[6:7], s[38:39], 0, v[0:1]
	s_mov_b32 m0, s27
	v_readfirstlane_b32 s27, v3
	global_load_lds_dwordx4 v[6:7], off
	v_lshl_add_u64 v[0:1], s[4:5], 0, v[0:1]
	s_mov_b32 m0, s27
	v_mov_b32_e32 v3, v135
	v_add_u32_e32 v5, 0x4000, v148
	global_load_lds_dwordx4 v[0:1], off
	v_lshlrev_b64 v[0:1], 1, v[2:3]
	v_readfirstlane_b32 s27, v5
	v_lshl_add_u64 v[2:3], s[38:39], 0, v[0:1]
	s_mov_b32 m0, s27
	v_lshl_add_u64 v[0:1], s[4:5], 0, v[0:1]
	global_load_lds_dwordx4 v[2:3], off
	v_add_u32_e32 v2, 0xc000, v148
	v_mov_b32_e32 v5, v135
	v_readfirstlane_b32 s27, v2
	s_mov_b32 m0, s27
	v_lshlrev_b32_e32 v6, 10, v11
	global_load_lds_dwordx4 v[0:1], off
	v_lshlrev_b64 v[0:1], 1, v[4:5]
	v_add_u32_e32 v4, 0x6000, v148
	v_lshl_add_u64 v[2:3], s[38:39], 0, v[0:1]
	v_readfirstlane_b32 s27, v4
	s_mov_b32 m0, s27
	v_lshl_add_u64 v[0:1], s[4:5], 0, v[0:1]
	global_load_lds_dwordx4 v[2:3], off
	v_add_u32_e32 v2, 0xe000, v148
	v_lshlrev_b32_e32 v4, 10, v15
	v_readfirstlane_b32 s27, v2
	s_mov_b32 m0, s27
	v_lshlrev_b32_e32 v2, 2, v10
	global_load_lds_dwordx4 v[0:1], off
	v_and_b32_e32 v0, 15, v10
	v_and_b32_e32 v1, 48, v10
	v_lshlrev_b32_e32 v0, 6, v0
	v_and_b32_e32 v2, 32, v2
	v_bitop3_b32 v149, v0, v2, v1 bitop3:0x36
	v_lshlrev_b32_e32 v0, 7, v10
	v_and_b32_e32 v150, 0x6000, v0
	v_lshlrev_b32_e32 v0, 6, v10
	v_and_b32_e32 v151, 0xffffc000, v0
	v_and_b32_e32 v0, 0x3c0, v0
	v_bitop3_b32 v153, v0, v2, v1 bitop3:0x36
	v_lshlrev_b32_e32 v0, 10, v17
	v_and_or_b32 v0, v0, s49, v13
	v_lshlrev_b32_e32 v2, 10, v16
	v_or3_b32 v134, v0, v6, v12
	v_and_or_b32 v2, v2, s49, v13
	v_lshlrev_b64 v[0:1], 1, v[134:135]
	v_or3_b32 v134, v2, v6, v12
	v_and_or_b32 v4, v4, s49, v13
	v_lshlrev_b32_e32 v7, 10, v14
	v_lshlrev_b64 v[2:3], 1, v[134:135]
	v_or3_b32 v134, v4, v6, v12
	v_and_or_b32 v7, v7, s49, v13
	s_add_u32 s4, s4, 0x80
	v_lshlrev_b64 v[4:5], 1, v[134:135]
	v_or3_b32 v134, v7, v6, v12
	s_addc_u32 s5, s5, 0
	v_lshlrev_b64 v[6:7], 1, v[134:135]
	s_nop 0
	v_lshl_add_u64 v[128:129], s[4:5], 0, v[0:1]
	v_lshl_add_u64 v[130:131], s[4:5], 0, v[2:3]
	v_lshl_add_u64 v[136:137], s[4:5], 0, v[4:5]
	v_lshl_add_u64 v[138:139], s[4:5], 0, v[6:7]
	s_add_u32 s4, s42, 0x2400080
	s_addc_u32 s5, s43, 0
	v_mov_b32_e32 v8, 0
	s_mov_b32 s37, 0
	v_or_b32_e32 v152, 0x800, v151
	v_or_b32_e32 v154, 0x1000, v151
	v_or_b32_e32 v155, 0x1800, v151
	v_or_b32_e32 v156, 0x2000, v151
	v_or_b32_e32 v157, 0x2800, v151
	v_or_b32_e32 v158, 0x3000, v151
	v_or_b32_e32 v159, 0x3800, v151
	v_lshl_add_u64 v[140:141], s[4:5], 0, v[0:1]
	v_lshl_add_u64 v[142:143], s[4:5], 0, v[2:3]
	v_lshl_add_u64 v[144:145], s[4:5], 0, v[4:5]
	v_lshl_add_u64 v[146:147], s[4:5], 0, v[6:7]
	s_mov_b64 s[4:5], 0
	v_mov_b32_e32 v9, v8
	v_mov_b32_e32 v10, v8
	v_mov_b32_e32 v11, v8
	v_mov_b32_e32 v20, v8
	v_mov_b32_e32 v21, v8
	v_mov_b32_e32 v22, v8
	v_mov_b32_e32 v23, v8
	v_mov_b32_e32 v28, v8
	v_mov_b32_e32 v29, v8
	v_mov_b32_e32 v30, v8
	v_mov_b32_e32 v31, v8
	v_mov_b32_e32 v36, v8
	v_mov_b32_e32 v37, v8
	v_mov_b32_e32 v38, v8
	v_mov_b32_e32 v39, v8
	v_mov_b32_e32 v0, v8
	v_mov_b32_e32 v1, v8
	v_mov_b32_e32 v2, v8
	v_mov_b32_e32 v3, v8
	v_mov_b32_e32 v4, v8
	v_mov_b32_e32 v5, v8
	v_mov_b32_e32 v6, v8
	v_mov_b32_e32 v7, v8
	v_mov_b32_e32 v12, v8
	v_mov_b32_e32 v13, v8
	v_mov_b32_e32 v14, v8
	v_mov_b32_e32 v15, v8
	v_mov_b32_e32 v16, v8
	v_mov_b32_e32 v17, v8
	v_mov_b32_e32 v18, v8
	v_mov_b32_e32 v19, v8
	v_mov_b32_e32 v24, v8
	v_mov_b32_e32 v25, v8
	v_mov_b32_e32 v26, v8
	v_mov_b32_e32 v27, v8
	v_mov_b32_e32 v32, v8
	v_mov_b32_e32 v33, v8
	v_mov_b32_e32 v34, v8
	v_mov_b32_e32 v35, v8
	v_mov_b32_e32 v40, v8
	v_mov_b32_e32 v41, v8
	v_mov_b32_e32 v42, v8
	v_mov_b32_e32 v43, v8
	v_mov_b32_e32 v44, v8
	v_mov_b32_e32 v45, v8
	v_mov_b32_e32 v46, v8
	v_mov_b32_e32 v47, v8
	v_mov_b32_e32 v48, v8
	v_mov_b32_e32 v49, v8
	v_mov_b32_e32 v50, v8
	v_mov_b32_e32 v51, v8
	v_mov_b32_e32 v52, v8
	v_mov_b32_e32 v53, v8
	v_mov_b32_e32 v54, v8
	v_mov_b32_e32 v55, v8
	v_mov_b32_e32 v56, v8
	v_mov_b32_e32 v57, v8
	v_mov_b32_e32 v58, v8
	v_mov_b32_e32 v59, v8
	v_mov_b32_e32 v60, v8
	v_mov_b32_e32 v61, v8
	v_mov_b32_e32 v62, v8
	v_mov_b32_e32 v63, v8
	v_mov_b32_e32 v64, v8
	v_mov_b32_e32 v65, v8
	v_mov_b32_e32 v66, v8
	v_mov_b32_e32 v67, v8
	v_mov_b32_e32 v68, v8
	v_mov_b32_e32 v69, v8
	v_mov_b32_e32 v70, v8
	v_mov_b32_e32 v71, v8
	v_mov_b32_e32 v72, v8
	v_mov_b32_e32 v73, v8
	v_mov_b32_e32 v74, v8
	v_mov_b32_e32 v75, v8
	v_mov_b32_e32 v76, v8
	v_mov_b32_e32 v77, v8
	v_mov_b32_e32 v78, v8
	v_mov_b32_e32 v79, v8
	v_mov_b32_e32 v80, v8
	v_mov_b32_e32 v81, v8
	v_mov_b32_e32 v82, v8
	v_mov_b32_e32 v83, v8
	v_mov_b32_e32 v84, v8
	v_mov_b32_e32 v85, v8
	v_mov_b32_e32 v86, v8
	v_mov_b32_e32 v87, v8
	v_mov_b32_e32 v88, v8
	v_mov_b32_e32 v89, v8
	v_mov_b32_e32 v90, v8
	v_mov_b32_e32 v91, v8
	v_mov_b32_e32 v92, v8
	v_mov_b32_e32 v93, v8
	v_mov_b32_e32 v94, v8
	v_mov_b32_e32 v95, v8
	v_mov_b32_e32 v96, v8
	v_mov_b32_e32 v97, v8
	v_mov_b32_e32 v98, v8
	v_mov_b32_e32 v99, v8
	v_mov_b32_e32 v100, v8
	v_mov_b32_e32 v101, v8
	v_mov_b32_e32 v102, v8
	v_mov_b32_e32 v103, v8
	v_mov_b32_e32 v104, v8
	v_mov_b32_e32 v105, v8
	v_mov_b32_e32 v106, v8
	v_mov_b32_e32 v107, v8
	v_mov_b32_e32 v108, v8
	v_mov_b32_e32 v109, v8
	v_mov_b32_e32 v110, v8
	v_mov_b32_e32 v111, v8
	v_mov_b32_e32 v112, v8
	v_mov_b32_e32 v113, v8
	v_mov_b32_e32 v114, v8
	v_mov_b32_e32 v115, v8
	v_mov_b32_e32 v116, v8
	v_mov_b32_e32 v117, v8
	v_mov_b32_e32 v118, v8
	v_mov_b32_e32 v119, v8
	v_mov_b32_e32 v120, v8
	v_mov_b32_e32 v121, v8
	v_mov_b32_e32 v122, v8
	v_mov_b32_e32 v123, v8
	v_mov_b32_e32 v124, v8
	v_mov_b32_e32 v125, v8
	v_mov_b32_e32 v126, v8
	v_mov_b32_e32 v127, v8
	s_waitcnt vmcnt(0) lgkmcnt(0)
	s_barrier
	v_readfirstlane_b32 s100, v148
	s_and_b32 s27, s37, 0x10000
	s_xor_b32 s38, s27, 0x10000
	s_add_i32 s27, s27, 0
	v_add3_u32 v134, s27, v149, v150
	v_add3_u32 v196, s27, v149, v151
	v_add3_u32 v197, s27, v153, v152
	v_add3_u32 v198, s27, v153, v154
	v_add3_u32 v199, s27, v153, v155
	v_add3_u32 v200, s27, v153, v156
	v_add3_u32 v201, s27, v153, v157
	v_add3_u32 v202, s27, v153, v158
	v_add3_u32 v203, s27, v153, v159
	ds_read_b128 v[180:183], v134 offset:32768
	ds_read_b128 v[160:163], v196
	ds_read_b128 v[168:171], v197
	ds_read_b128 v[172:175], v198
	ds_read_b128 v[176:179], v199
	ds_read_b128 v[184:187], v134 offset:34816
	ds_read_b128 v[188:191], v134 offset:36864
	ds_read_b128 v[192:195], v134 offset:38912
	s_add_i32 s101, s100, s38
	v_readfirstlane_b32 s98, v146
	v_readfirstlane_b32 s99, v147
	v_readfirstlane_b32 vcc_lo, v138
	v_readfirstlane_b32 vcc_hi, v139
	s_sub_u32 s98, s98, 0x1000000
	s_subb_u32 s99, s99, 0
	s_sub_u32 vcc_lo, vcc_lo, 0x1000000
	s_subb_u32 vcc_hi, vcc_hi, 0
	v_subrev_u32_e32 v146, s98, v146
	v_subrev_u32_e32 v138, vcc_lo, v138
	v_subrev_u32_e32 v144, s98, v144
	v_subrev_u32_e32 v136, vcc_lo, v136
	v_subrev_u32_e32 v142, s98, v142
	v_subrev_u32_e32 v130, vcc_lo, v130
	v_subrev_u32_e32 v140, s98, v140
	v_subrev_u32_e32 v128, vcc_lo, v128
	s_mov_b32 m0, s101
	s_nop 0
	global_load_lds_dwordx4 v146, s[98:99]
	s_add_i32 m0, s101, 0x8000
	s_nop 0
	global_load_lds_dwordx4 v138, vcc
	s_add_i32 m0, s101, 0x2000
	s_nop 0
	global_load_lds_dwordx4 v144, s[98:99]
	s_add_i32 m0, s101, 0xa000
	s_nop 0
	global_load_lds_dwordx4 v136, vcc
	s_add_i32 m0, s101, 0x4000
	s_nop 0
	global_load_lds_dwordx4 v142, s[98:99]
	s_add_i32 m0, s101, 0xc000
	s_nop 0
	global_load_lds_dwordx4 v130, vcc
	s_add_i32 m0, s101, 0x6000
	s_nop 0
	global_load_lds_dwordx4 v140, s[98:99]
	s_add_i32 m0, s101, 0xe000
	s_nop 0
	global_load_lds_dwordx4 v128, vcc

.LBB0_163:
	s_cmp_lg_u32 s67, 5
	s_cselect_b64 s[4:5], -1, 0
	s_and_b32 s6, s26, -10
	s_cmp_lg_u32 s6, 4
	s_cselect_b64 s[30:31], -1, 0
	v_mov_b32_e32 v0, s19
	s_and_b64 s[34:35], s[30:31], s[4:5]
	ds_read_b64 v[0:1], v0
	s_and_b64 s[4:5], exec, s[28:29]
	s_cselect_b32 s4, 0x8000, 0
	s_add_i32 s4, s66, s4
	s_ashr_i32 s5, s4, 31
	s_lshl_b64 s[4:5], s[4:5], 11
	s_waitcnt lgkmcnt(0)
	v_readfirstlane_b32 s38, v0
	v_readfirstlane_b32 s39, v1
	v_lshl_add_u64 v[0:1], v[0:1], 0, s[4:5]
	v_lshl_add_u64 v[128:129], v[0:1], 0, s[8:9]
	s_mov_b64 s[30:31], -1
	s_and_b64 vcc, exec, s[34:35]
	s_cbranch_vccz .LBB0_175
	v_mov_b32_e32 v10, v132
	s_ashr_i32 s27, s26, 31
	v_lshlrev_b32_e32 v1, 4, v10
	v_and_b32_e32 v0, 32, v10
	v_lshrrev_b32_e32 v2, 1, v10
	v_bitop3_b32 v0, v1, v0, 48 bitop3:0x6c
	v_bfe_u32 v11, v10, 2, 4
	v_and_b32_e32 v12, 32, v2
	v_lshrrev_b32_e32 v13, 1, v0
	v_ashrrev_i32_e32 v14, 3, v10
	v_or_b32_e32 v4, v13, v12
	v_and_or_b32 v0, v14, s48, v11
	v_and_b32_e32 v3, 0xfffffc00, v1
	v_lshl_or_b32 v134, v0, 10, v4
	v_add_u32_e32 v0, 0x2000, v1
	v_add_u32_e32 v2, 0x4000, v1
	v_add_u32_e32 v1, 0x6000, v1
	v_ashrrev_i32_e32 v15, 7, v0
	v_ashrrev_i32_e32 v16, 7, v2
	v_ashrrev_i32_e32 v17, 7, v1
	s_lshl_b64 s[30:31], s[26:27], 19
	v_and_or_b32 v0, v15, s48, v11
	v_and_or_b32 v2, v16, s48, v11
	v_and_or_b32 v1, v17, s48, v11
	v_add_u32_e32 v150, 0, v3
	s_add_u32 s30, s38, s30
	v_lshl_or_b32 v0, v0, 10, v4
	v_lshl_or_b32 v2, v2, 10, v4
	v_lshl_or_b32 v4, v1, 10, v4
	v_add_u32_e32 v1, 0x8000, v150
	v_lshlrev_b64 v[6:7], 1, v[134:135]
	v_readfirstlane_b32 s6, v150
	s_addc_u32 s31, s39, s31
	v_lshl_add_u64 v[8:9], v[128:129], 0, v[6:7]
	s_mov_b32 m0, s6
	v_readfirstlane_b32 s6, v1
	v_mov_b32_e32 v1, v135
	v_add_u32_e32 v3, 0x2000, v150
	global_load_lds_dwordx4 v[8:9], off
	v_lshl_add_u64 v[6:7], s[30:31], 0, v[6:7]
	s_mov_b32 m0, s6
	v_lshlrev_b64 v[0:1], 1, v[0:1]
	v_readfirstlane_b32 s6, v3
	v_add_u32_e32 v3, 0xa000, v150
	global_load_lds_dwordx4 v[6:7], off
	v_lshl_add_u64 v[6:7], v[128:129], 0, v[0:1]
	s_mov_b32 m0, s6
	v_readfirstlane_b32 s6, v3
	global_load_lds_dwordx4 v[6:7], off
	v_lshl_add_u64 v[0:1], s[30:31], 0, v[0:1]
	s_mov_b32 m0, s6
	v_mov_b32_e32 v3, v135
	v_add_u32_e32 v5, 0x4000, v150
	global_load_lds_dwordx4 v[0:1], off
	v_lshlrev_b64 v[0:1], 1, v[2:3]
	v_readfirstlane_b32 s6, v5
	v_lshl_add_u64 v[2:3], v[128:129], 0, v[0:1]
	s_mov_b32 m0, s6
	v_lshl_add_u64 v[0:1], s[30:31], 0, v[0:1]
	global_load_lds_dwordx4 v[2:3], off
	v_add_u32_e32 v2, 0xc000, v150
	v_mov_b32_e32 v5, v135
	v_readfirstlane_b32 s6, v2
	s_mov_b32 m0, s6
	v_and_b32_e32 v18, 15, v10
	global_load_lds_dwordx4 v[0:1], off
	v_lshlrev_b64 v[0:1], 1, v[4:5]
	v_add_u32_e32 v4, 0x6000, v150
	v_lshl_add_u64 v[2:3], v[128:129], 0, v[0:1]
	v_readfirstlane_b32 s6, v4
	s_mov_b32 m0, s6
	v_lshl_add_u64 v[0:1], s[30:31], 0, v[0:1]
	global_load_lds_dwordx4 v[2:3], off
	v_add_u32_e32 v2, 0xe000, v150
	v_lshlrev_b32_e32 v6, 10, v11
	v_readfirstlane_b32 s6, v2
	s_mov_b32 m0, s6
	v_lshlrev_b32_e32 v2, 2, v10
	global_load_lds_dwordx4 v[0:1], off
	v_and_b32_e32 v0, 48, v10
	v_lshlrev_b32_e32 v1, 6, v18
	v_and_b32_e32 v2, 32, v2
	v_bitop3_b32 v151, v1, v2, v0 bitop3:0x36
	v_lshlrev_b32_e32 v1, 7, v10
	v_and_b32_e32 v152, 0x6000, v1
	v_lshlrev_b32_e32 v1, 6, v10
	v_and_b32_e32 v153, 0xffffc000, v1
	v_and_b32_e32 v1, 0x3c0, v1
	v_bitop3_b32 v155, v1, v2, v0 bitop3:0x36
	v_lshlrev_b32_e32 v0, 10, v17
	v_and_or_b32 v0, v0, s49, v13
	v_lshlrev_b32_e32 v2, 10, v16
	v_or3_b32 v134, v0, v6, v12
	v_and_or_b32 v2, v2, s49, v13
	v_lshlrev_b32_e32 v4, 10, v15
	v_lshlrev_b64 v[0:1], 1, v[134:135]
	s_add_u32 s30, s30, 0x80
	v_or3_b32 v134, v2, v6, v12
	v_and_or_b32 v4, v4, s49, v13
	v_lshlrev_b32_e32 v7, 10, v14
	s_addc_u32 s31, s31, 0
	v_lshlrev_b64 v[2:3], 1, v[134:135]
	v_or3_b32 v134, v4, v6, v12
	v_and_or_b32 v7, v7, s49, v13
	v_lshlrev_b64 v[4:5], 1, v[134:135]
	v_or3_b32 v134, v7, v6, v12
	s_add_u32 s6, s38, s4
	v_lshlrev_b64 v[6:7], 1, v[134:135]
	s_addc_u32 s27, s39, s5
	v_lshl_add_u64 v[130:131], s[30:31], 0, v[0:1]
	v_lshl_add_u64 v[136:137], s[30:31], 0, v[2:3]
	v_lshl_add_u64 v[138:139], s[30:31], 0, v[4:5]
	v_lshl_add_u64 v[140:141], s[30:31], 0, v[6:7]
	s_add_u32 s30, s6, 0x2400080
	s_nop 0
	s_addc_u32 s31, s27, 0
	v_lshl_add_u64 v[142:143], s[30:31], 0, v[0:1]
	v_mov_b32_e32 v0, 0
	v_or_b32_e32 v154, 0x800, v153
	v_or_b32_e32 v156, 0x1000, v153
	v_or_b32_e32 v157, 0x1800, v153
	v_or_b32_e32 v158, 0x2000, v153
	v_or_b32_e32 v159, 0x2800, v153
	v_or_b32_e32 v160, 0x3000, v153
	v_or_b32_e32 v161, 0x3800, v153
	v_lshl_add_u64 v[144:145], s[30:31], 0, v[2:3]
	v_lshl_add_u64 v[146:147], s[30:31], 0, v[4:5]
	v_lshl_add_u64 v[148:149], s[30:31], 0, v[6:7]
	s_mov_b32 s6, 0
	s_mov_b64 s[30:31], 0
	v_mov_b32_e32 v1, v0
	v_mov_b32_e32 v2, v0
	v_mov_b32_e32 v3, v0
	v_mov_b32_e32 v4, v0
	v_mov_b32_e32 v5, v0
	v_mov_b32_e32 v6, v0
	v_mov_b32_e32 v7, v0
	v_mov_b32_e32 v8, v0
	v_mov_b32_e32 v9, v0
	v_mov_b32_e32 v10, v0
	v_mov_b32_e32 v11, v0
	v_mov_b32_e32 v12, v0
	v_mov_b32_e32 v13, v0
	v_mov_b32_e32 v14, v0
	v_mov_b32_e32 v15, v0
	v_mov_b32_e32 v16, v0
	v_mov_b32_e32 v17, v0
	v_mov_b32_e32 v18, v0
	v_mov_b32_e32 v19, v0
	v_mov_b32_e32 v20, v0
	v_mov_b32_e32 v21, v0
	v_mov_b32_e32 v22, v0
	v_mov_b32_e32 v23, v0
	v_mov_b32_e32 v24, v0
	v_mov_b32_e32 v25, v0
	v_mov_b32_e32 v26, v0
	v_mov_b32_e32 v27, v0
	v_mov_b32_e32 v28, v0
	v_mov_b32_e32 v29, v0
	v_mov_b32_e32 v30, v0
	v_mov_b32_e32 v31, v0
	v_mov_b32_e32 v32, v0
	v_mov_b32_e32 v33, v0
	v_mov_b32_e32 v34, v0
	v_mov_b32_e32 v35, v0
	v_mov_b32_e32 v36, v0
	v_mov_b32_e32 v37, v0
	v_mov_b32_e32 v38, v0
	v_mov_b32_e32 v39, v0
	v_mov_b32_e32 v40, v0
	v_mov_b32_e32 v41, v0
	v_mov_b32_e32 v42, v0
	v_mov_b32_e32 v43, v0
	v_mov_b32_e32 v44, v0
	v_mov_b32_e32 v45, v0
	v_mov_b32_e32 v46, v0
	v_mov_b32_e32 v47, v0
	v_mov_b32_e32 v48, v0
	v_mov_b32_e32 v49, v0
	v_mov_b32_e32 v50, v0
	v_mov_b32_e32 v51, v0
	v_mov_b32_e32 v52, v0
	v_mov_b32_e32 v53, v0
	v_mov_b32_e32 v54, v0
	v_mov_b32_e32 v55, v0
	v_mov_b32_e32 v56, v0
	v_mov_b32_e32 v57, v0
	v_mov_b32_e32 v58, v0
	v_mov_b32_e32 v59, v0
	v_mov_b32_e32 v60, v0
	v_mov_b32_e32 v61, v0
	v_mov_b32_e32 v62, v0
	v_mov_b32_e32 v63, v0
	v_mov_b32_e32 v64, v0
	v_mov_b32_e32 v65, v0
	v_mov_b32_e32 v66, v0
	v_mov_b32_e32 v67, v0
	v_mov_b32_e32 v68, v0
	v_mov_b32_e32 v69, v0
	v_mov_b32_e32 v70, v0
	v_mov_b32_e32 v71, v0
	v_mov_b32_e32 v72, v0
	v_mov_b32_e32 v73, v0
	v_mov_b32_e32 v74, v0
	v_mov_b32_e32 v75, v0
	v_mov_b32_e32 v76, v0
	v_mov_b32_e32 v77, v0
	v_mov_b32_e32 v78, v0
	v_mov_b32_e32 v79, v0
	v_mov_b32_e32 v80, v0
	v_mov_b32_e32 v81, v0
	v_mov_b32_e32 v82, v0
	v_mov_b32_e32 v83, v0
	v_mov_b32_e32 v84, v0
	v_mov_b32_e32 v85, v0
	v_mov_b32_e32 v86, v0
	v_mov_b32_e32 v87, v0
	v_mov_b32_e32 v88, v0
	v_mov_b32_e32 v89, v0
	v_mov_b32_e32 v90, v0
	v_mov_b32_e32 v91, v0
	v_mov_b32_e32 v92, v0
	v_mov_b32_e32 v93, v0
	v_mov_b32_e32 v94, v0
	v_mov_b32_e32 v95, v0
	v_mov_b32_e32 v96, v0
	v_mov_b32_e32 v97, v0
	v_mov_b32_e32 v98, v0
	v_mov_b32_e32 v99, v0
	v_mov_b32_e32 v100, v0
	v_mov_b32_e32 v101, v0
	v_mov_b32_e32 v102, v0
	v_mov_b32_e32 v103, v0
	v_mov_b32_e32 v104, v0
	v_mov_b32_e32 v105, v0
	v_mov_b32_e32 v106, v0
	v_mov_b32_e32 v107, v0
	v_mov_b32_e32 v108, v0
	v_mov_b32_e32 v109, v0
	v_mov_b32_e32 v110, v0
	v_mov_b32_e32 v111, v0
	v_mov_b32_e32 v112, v0
	v_mov_b32_e32 v113, v0
	v_mov_b32_e32 v114, v0
	v_mov_b32_e32 v115, v0
	v_mov_b32_e32 v116, v0
	v_mov_b32_e32 v117, v0
	v_mov_b32_e32 v118, v0
	v_mov_b32_e32 v119, v0
	v_mov_b32_e32 v120, v0
	v_mov_b32_e32 v121, v0
	v_mov_b32_e32 v122, v0
	v_mov_b32_e32 v123, v0
	v_mov_b32_e32 v124, v0
	v_mov_b32_e32 v125, v0
	v_mov_b32_e32 v126, v0
	v_mov_b32_e32 v127, v0
	s_waitcnt vmcnt(0) lgkmcnt(0)
	s_barrier
	v_readfirstlane_b32 s100, v150
	s_and_b32 s27, s6, 0x10000
	s_xor_b32 s34, s27, 0x10000
	s_add_i32 s27, s27, 0
	v_add3_u32 v134, s27, v151, v152
	v_add3_u32 v162, s27, v151, v153
	v_add3_u32 v163, s27, v155, v154
	v_add3_u32 v200, s27, v155, v156
	v_add3_u32 v201, s27, v155, v157
	v_add3_u32 v202, s27, v155, v158
	v_add3_u32 v203, s27, v155, v159
	v_add3_u32 v204, s27, v155, v160
	v_add3_u32 v205, s27, v155, v161
	ds_read_b128 v[184:187], v134 offset:32768
	ds_read_b128 v[168:171], v162
	ds_read_b128 v[172:175], v163
	ds_read_b128 v[176:179], v200
	ds_read_b128 v[180:183], v201
	ds_read_b128 v[188:191], v134 offset:34816
	ds_read_b128 v[192:195], v134 offset:36864
	ds_read_b128 v[196:199], v134 offset:38912
	s_add_i32 s101, s100, s34
	v_readfirstlane_b32 s98, v148
	v_readfirstlane_b32 s99, v149
	v_readfirstlane_b32 vcc_lo, v140
	v_readfirstlane_b32 vcc_hi, v141
	s_sub_u32 s98, s98, 0x1000000
	s_subb_u32 s99, s99, 0
	s_sub_u32 vcc_lo, vcc_lo, 0x1000000
	s_subb_u32 vcc_hi, vcc_hi, 0
	v_subrev_u32_e32 v148, s98, v148
	v_subrev_u32_e32 v140, vcc_lo, v140
	v_subrev_u32_e32 v146, s98, v146
	v_subrev_u32_e32 v138, vcc_lo, v138
	v_subrev_u32_e32 v144, s98, v144
	v_subrev_u32_e32 v136, vcc_lo, v136
	v_subrev_u32_e32 v142, s98, v142
	v_subrev_u32_e32 v130, vcc_lo, v130
	s_mov_b32 m0, s101
	s_nop 0
	global_load_lds_dwordx4 v148, s[98:99]
	s_add_i32 m0, s101, 0x8000
	s_nop 0
	global_load_lds_dwordx4 v140, vcc
	s_add_i32 m0, s101, 0x2000
	s_nop 0
	global_load_lds_dwordx4 v146, s[98:99]
	s_add_i32 m0, s101, 0xa000
	s_nop 0
	global_load_lds_dwordx4 v138, vcc
	s_add_i32 m0, s101, 0x4000
	s_nop 0
	global_load_lds_dwordx4 v144, s[98:99]
	s_add_i32 m0, s101, 0xc000
	s_nop 0
	global_load_lds_dwordx4 v136, vcc
	s_add_i32 m0, s101, 0x6000
	s_nop 0
	global_load_lds_dwordx4 v142, s[98:99]
	s_add_i32 m0, s101, 0xe000
	s_nop 0
	global_load_lds_dwordx4 v130, vcc

.LBB0_175:
	s_and_b64 vcc, exec, s[30:31]
	s_cbranch_vccz .LBB0_179
	v_mov_b32_e32 v10, v132
	s_lshl_b32 s6, s26, 19
	v_lshlrev_b32_e32 v1, 4, v10
	v_and_b32_e32 v0, 32, v10
	v_lshrrev_b32_e32 v2, 1, v10
	v_bitop3_b32 v0, v1, v0, 48 bitop3:0x6c
	v_bfe_u32 v11, v10, 2, 4
	v_and_b32_e32 v12, 32, v2
	v_lshrrev_b32_e32 v13, 1, v0
	v_ashrrev_i32_e32 v14, 3, v10
	v_or_b32_e32 v4, v13, v12
	v_and_or_b32 v0, v14, s48, v11
	v_and_b32_e32 v3, 0xfffffc00, v1
	v_lshl_or_b32 v134, v0, 10, v4
	v_add_u32_e32 v0, 0x2000, v1
	v_add_u32_e32 v2, 0x4000, v1
	v_add_u32_e32 v1, 0x6000, v1
	v_ashrrev_i32_e32 v15, 7, v0
	v_ashrrev_i32_e32 v16, 7, v2
	v_ashrrev_i32_e32 v17, 7, v1
	v_and_or_b32 v0, v15, s48, v11
	v_and_or_b32 v2, v16, s48, v11
	v_and_or_b32 v1, v17, s48, v11
	v_add_u32_e32 v148, 0, v3
	s_add_u32 s30, s38, s6
	v_lshl_or_b32 v0, v0, 10, v4
	v_lshl_or_b32 v2, v2, 10, v4
	v_lshl_or_b32 v4, v1, 10, v4
	v_add_u32_e32 v1, 0x8000, v148
	v_lshlrev_b64 v[6:7], 1, v[134:135]
	v_readfirstlane_b32 s6, v148
	s_addc_u32 s31, s39, 0
	v_lshl_add_u64 v[8:9], v[128:129], 0, v[6:7]
	s_mov_b32 m0, s6
	v_readfirstlane_b32 s6, v1
	v_mov_b32_e32 v1, v135
	v_add_u32_e32 v3, 0x2000, v148
	global_load_lds_dwordx4 v[8:9], off
	v_lshl_add_u64 v[6:7], s[30:31], 0, v[6:7]
	s_mov_b32 m0, s6
	v_lshlrev_b64 v[0:1], 1, v[0:1]
	v_readfirstlane_b32 s6, v3
	v_add_u32_e32 v3, 0xa000, v148
	global_load_lds_dwordx4 v[6:7], off
	v_lshl_add_u64 v[6:7], v[128:129], 0, v[0:1]
	s_mov_b32 m0, s6
	v_readfirstlane_b32 s6, v3
	global_load_lds_dwordx4 v[6:7], off
	v_lshl_add_u64 v[0:1], s[30:31], 0, v[0:1]
	s_mov_b32 m0, s6
	v_mov_b32_e32 v3, v135
	v_add_u32_e32 v5, 0x4000, v148
	global_load_lds_dwordx4 v[0:1], off
	v_lshlrev_b64 v[0:1], 1, v[2:3]
	v_readfirstlane_b32 s6, v5
	v_lshl_add_u64 v[2:3], v[128:129], 0, v[0:1]
	s_mov_b32 m0, s6
	v_lshl_add_u64 v[0:1], s[30:31], 0, v[0:1]
	global_load_lds_dwordx4 v[2:3], off
	v_add_u32_e32 v2, 0xc000, v148
	v_mov_b32_e32 v5, v135
	v_readfirstlane_b32 s6, v2
	s_mov_b32 m0, s6
	v_lshlrev_b32_e32 v6, 10, v11
	global_load_lds_dwordx4 v[0:1], off
	v_lshlrev_b64 v[0:1], 1, v[4:5]
	v_add_u32_e32 v4, 0x6000, v148
	v_lshl_add_u64 v[2:3], v[128:129], 0, v[0:1]
	v_readfirstlane_b32 s6, v4
	s_mov_b32 m0, s6
	v_lshl_add_u64 v[0:1], s[30:31], 0, v[0:1]
	global_load_lds_dwordx4 v[2:3], off
	v_add_u32_e32 v2, 0xe000, v148
	s_add_u32 s30, s30, 0x80
	v_readfirstlane_b32 s6, v2
	s_mov_b32 m0, s6
	v_lshlrev_b32_e32 v2, 2, v10
	global_load_lds_dwordx4 v[0:1], off
	v_and_b32_e32 v0, 15, v10
	v_and_b32_e32 v1, 48, v10
	v_lshlrev_b32_e32 v0, 6, v0
	v_and_b32_e32 v2, 32, v2
	v_bitop3_b32 v149, v0, v2, v1 bitop3:0x36
	v_lshlrev_b32_e32 v0, 7, v10
	v_and_b32_e32 v150, 0x6000, v0
	v_lshlrev_b32_e32 v0, 6, v10
	v_and_b32_e32 v151, 0xffffc000, v0
	v_and_b32_e32 v0, 0x3c0, v0
	v_bitop3_b32 v153, v0, v2, v1 bitop3:0x36
	v_lshlrev_b32_e32 v0, 10, v17
	v_and_or_b32 v0, v0, s49, v13
	s_addc_u32 s31, s31, 0
	v_lshlrev_b32_e32 v2, 10, v16
	v_or3_b32 v134, v0, v6, v12
	v_and_or_b32 v2, v2, s49, v13
	v_lshlrev_b32_e32 v4, 10, v15
	s_add_u32 s4, s38, s4
	v_lshlrev_b64 v[0:1], 1, v[134:135]
	v_or3_b32 v134, v2, v6, v12
	v_and_or_b32 v4, v4, s49, v13
	v_lshlrev_b32_e32 v7, 10, v14
	s_addc_u32 s5, s39, s5
	v_lshlrev_b64 v[2:3], 1, v[134:135]
	v_or3_b32 v134, v4, v6, v12
	v_and_or_b32 v7, v7, s49, v13
	s_add_u32 s4, s4, 0x2400080
	s_nop 0
	v_lshlrev_b64 v[4:5], 1, v[134:135]
	v_or3_b32 v134, v7, v6, v12
	s_addc_u32 s5, s5, 0
	v_lshl_add_u64 v[128:129], s[30:31], 0, v[0:1]
	v_lshlrev_b64 v[6:7], 1, v[134:135]
	v_lshl_add_u64 v[140:141], s[4:5], 0, v[0:1]
	v_mov_b32_e32 v0, 0
	v_or_b32_e32 v152, 0x800, v151
	v_or_b32_e32 v154, 0x1000, v151
	v_or_b32_e32 v155, 0x1800, v151
	v_or_b32_e32 v156, 0x2000, v151
	v_or_b32_e32 v157, 0x2800, v151
	v_or_b32_e32 v158, 0x3000, v151
	v_or_b32_e32 v159, 0x3800, v151
	v_lshl_add_u64 v[130:131], s[30:31], 0, v[2:3]
	v_lshl_add_u64 v[136:137], s[30:31], 0, v[4:5]
	v_lshl_add_u64 v[138:139], s[30:31], 0, v[6:7]
	v_lshl_add_u64 v[142:143], s[4:5], 0, v[2:3]
	v_lshl_add_u64 v[144:145], s[4:5], 0, v[4:5]
	v_lshl_add_u64 v[146:147], s[4:5], 0, v[6:7]
	s_mov_b32 s6, 0
	s_mov_b64 s[4:5], 0
	v_mov_b32_e32 v1, v0
	v_mov_b32_e32 v2, v0
	v_mov_b32_e32 v3, v0
	v_mov_b32_e32 v4, v0
	v_mov_b32_e32 v5, v0
	v_mov_b32_e32 v6, v0
	v_mov_b32_e32 v7, v0
	v_mov_b32_e32 v8, v0
	v_mov_b32_e32 v9, v0
	v_mov_b32_e32 v10, v0
	v_mov_b32_e32 v11, v0
	v_mov_b32_e32 v12, v0
	v_mov_b32_e32 v13, v0
	v_mov_b32_e32 v14, v0
	v_mov_b32_e32 v15, v0
	v_mov_b32_e32 v16, v0
	v_mov_b32_e32 v17, v0
	v_mov_b32_e32 v18, v0
	v_mov_b32_e32 v19, v0
	v_mov_b32_e32 v20, v0
	v_mov_b32_e32 v21, v0
	v_mov_b32_e32 v22, v0
	v_mov_b32_e32 v23, v0
	v_mov_b32_e32 v24, v0
	v_mov_b32_e32 v25, v0
	v_mov_b32_e32 v26, v0
	v_mov_b32_e32 v27, v0
	v_mov_b32_e32 v28, v0
	v_mov_b32_e32 v29, v0
	v_mov_b32_e32 v30, v0
	v_mov_b32_e32 v31, v0
	v_mov_b32_e32 v32, v0
	v_mov_b32_e32 v33, v0
	v_mov_b32_e32 v34, v0
	v_mov_b32_e32 v35, v0
	v_mov_b32_e32 v36, v0
	v_mov_b32_e32 v37, v0
	v_mov_b32_e32 v38, v0
	v_mov_b32_e32 v39, v0
	v_mov_b32_e32 v40, v0
	v_mov_b32_e32 v41, v0
	v_mov_b32_e32 v42, v0
	v_mov_b32_e32 v43, v0
	v_mov_b32_e32 v44, v0
	v_mov_b32_e32 v45, v0
	v_mov_b32_e32 v46, v0
	v_mov_b32_e32 v47, v0
	v_mov_b32_e32 v48, v0
	v_mov_b32_e32 v49, v0
	v_mov_b32_e32 v50, v0
	v_mov_b32_e32 v51, v0
	v_mov_b32_e32 v52, v0
	v_mov_b32_e32 v53, v0
	v_mov_b32_e32 v54, v0
	v_mov_b32_e32 v55, v0
	v_mov_b32_e32 v56, v0
	v_mov_b32_e32 v57, v0
	v_mov_b32_e32 v58, v0
	v_mov_b32_e32 v59, v0
	v_mov_b32_e32 v60, v0
	v_mov_b32_e32 v61, v0
	v_mov_b32_e32 v62, v0
	v_mov_b32_e32 v63, v0
	v_mov_b32_e32 v64, v0
	v_mov_b32_e32 v65, v0
	v_mov_b32_e32 v66, v0
	v_mov_b32_e32 v67, v0
	v_mov_b32_e32 v68, v0
	v_mov_b32_e32 v69, v0
	v_mov_b32_e32 v70, v0
	v_mov_b32_e32 v71, v0
	v_mov_b32_e32 v72, v0
	v_mov_b32_e32 v73, v0
	v_mov_b32_e32 v74, v0
	v_mov_b32_e32 v75, v0
	v_mov_b32_e32 v76, v0
	v_mov_b32_e32 v77, v0
	v_mov_b32_e32 v78, v0
	v_mov_b32_e32 v79, v0
	v_mov_b32_e32 v80, v0
	v_mov_b32_e32 v81, v0
	v_mov_b32_e32 v82, v0
	v_mov_b32_e32 v83, v0
	v_mov_b32_e32 v84, v0
	v_mov_b32_e32 v85, v0
	v_mov_b32_e32 v86, v0
	v_mov_b32_e32 v87, v0
	v_mov_b32_e32 v88, v0
	v_mov_b32_e32 v89, v0
	v_mov_b32_e32 v90, v0
	v_mov_b32_e32 v91, v0
	v_mov_b32_e32 v92, v0
	v_mov_b32_e32 v93, v0
	v_mov_b32_e32 v94, v0
	v_mov_b32_e32 v95, v0
	v_mov_b32_e32 v96, v0
	v_mov_b32_e32 v97, v0
	v_mov_b32_e32 v98, v0
	v_mov_b32_e32 v99, v0
	v_mov_b32_e32 v100, v0
	v_mov_b32_e32 v101, v0
	v_mov_b32_e32 v102, v0
	v_mov_b32_e32 v103, v0
	v_mov_b32_e32 v104, v0
	v_mov_b32_e32 v105, v0
	v_mov_b32_e32 v106, v0
	v_mov_b32_e32 v107, v0
	v_mov_b32_e32 v108, v0
	v_mov_b32_e32 v109, v0
	v_mov_b32_e32 v110, v0
	v_mov_b32_e32 v111, v0
	v_mov_b32_e32 v112, v0
	v_mov_b32_e32 v113, v0
	v_mov_b32_e32 v114, v0
	v_mov_b32_e32 v115, v0
	v_mov_b32_e32 v116, v0
	v_mov_b32_e32 v117, v0
	v_mov_b32_e32 v118, v0
	v_mov_b32_e32 v119, v0
	v_mov_b32_e32 v120, v0
	v_mov_b32_e32 v121, v0
	v_mov_b32_e32 v122, v0
	v_mov_b32_e32 v123, v0
	v_mov_b32_e32 v124, v0
	v_mov_b32_e32 v125, v0
	v_mov_b32_e32 v126, v0
	v_mov_b32_e32 v127, v0
	s_waitcnt vmcnt(0) lgkmcnt(0)
	s_barrier
	v_readfirstlane_b32 s100, v148
	s_and_b32 s27, s6, 0x10000
	s_xor_b32 s30, s27, 0x10000
	s_add_i32 s27, s27, 0
	v_add3_u32 v134, s27, v149, v150
	v_add3_u32 v196, s27, v149, v151
	v_add3_u32 v197, s27, v153, v152
	v_add3_u32 v198, s27, v153, v154
	v_add3_u32 v199, s27, v153, v155
	v_add3_u32 v200, s27, v153, v156
	v_add3_u32 v201, s27, v153, v157
	v_add3_u32 v202, s27, v153, v158
	v_add3_u32 v203, s27, v153, v159
	ds_read_b128 v[180:183], v134 offset:32768
	ds_read_b128 v[160:163], v196
	ds_read_b128 v[168:171], v197
	ds_read_b128 v[172:175], v198
	ds_read_b128 v[176:179], v199
	ds_read_b128 v[184:187], v134 offset:34816
	ds_read_b128 v[188:191], v134 offset:36864
	ds_read_b128 v[192:195], v134 offset:38912
	s_add_i32 s101, s100, s30
	v_readfirstlane_b32 s98, v146
	v_readfirstlane_b32 s99, v147
	v_readfirstlane_b32 vcc_lo, v138
	v_readfirstlane_b32 vcc_hi, v139
	s_sub_u32 s98, s98, 0x1000000
	s_subb_u32 s99, s99, 0
	s_sub_u32 vcc_lo, vcc_lo, 0x1000000
	s_subb_u32 vcc_hi, vcc_hi, 0
	v_subrev_u32_e32 v146, s98, v146
	v_subrev_u32_e32 v138, vcc_lo, v138
	v_subrev_u32_e32 v144, s98, v144
	v_subrev_u32_e32 v136, vcc_lo, v136
	v_subrev_u32_e32 v142, s98, v142
	v_subrev_u32_e32 v130, vcc_lo, v130
	v_subrev_u32_e32 v140, s98, v140
	v_subrev_u32_e32 v128, vcc_lo, v128
	s_mov_b32 m0, s101
	s_nop 0
	global_load_lds_dwordx4 v146, s[98:99]
	s_add_i32 m0, s101, 0x8000
	s_nop 0
	global_load_lds_dwordx4 v138, vcc
	s_add_i32 m0, s101, 0x2000
	s_nop 0
	global_load_lds_dwordx4 v144, s[98:99]
	s_add_i32 m0, s101, 0xa000
	s_nop 0
	global_load_lds_dwordx4 v136, vcc
	s_add_i32 m0, s101, 0x4000
	s_nop 0
	global_load_lds_dwordx4 v142, s[98:99]
	s_add_i32 m0, s101, 0xc000
	s_nop 0
	global_load_lds_dwordx4 v130, vcc
	s_add_i32 m0, s101, 0x6000
	s_nop 0
	global_load_lds_dwordx4 v140, s[98:99]
	s_add_i32 m0, s101, 0xe000
	s_nop 0
	global_load_lds_dwordx4 v128, vcc

.LBB0_180:
	s_nop 0
	v_mov_b32_e32 v0, s19
	v_mov_b32_e32 v16, v132
	ds_read_b64 v[128:129], v0
	s_and_b64 s[4:5], exec, s[28:29]
	v_lshlrev_b32_e32 v7, 4, v16
	v_and_b32_e32 v6, 32, v16
	v_lshrrev_b32_e32 v8, 1, v16
	v_bitop3_b32 v6, v7, v6, 48 bitop3:0x6c
	s_cselect_b32 s4, 0x8000, 0
	v_bfe_u32 v17, v16, 2, 4
	v_and_b32_e32 v18, 32, v8
	v_lshrrev_b32_e32 v19, 1, v6
	v_ashrrev_i32_e32 v20, 3, v16
	s_add_i32 s4, s66, s4
	v_or_b32_e32 v10, v19, v18
	v_and_or_b32 v6, v20, s48, v17
	s_ashr_i32 s5, s4, 31
	v_and_b32_e32 v9, 0xfffffc00, v7
	v_lshl_or_b32 v134, v6, 10, v10
	v_add_u32_e32 v6, 0x2000, v7
	v_add_u32_e32 v8, 0x4000, v7
	v_add_u32_e32 v7, 0x6000, v7
	s_lshl_b64 s[4:5], s[4:5], 11
	s_ashr_i32 s27, s26, 31
	v_ashrrev_i32_e32 v21, 7, v6
	v_ashrrev_i32_e32 v22, 7, v8
	v_ashrrev_i32_e32 v23, 7, v7
	s_waitcnt lgkmcnt(0)
	v_lshl_add_u64 v[0:1], v[128:129], 0, s[4:5]
	s_lshl_b64 s[4:5], s[26:27], 19
	v_and_or_b32 v6, v21, s48, v17
	v_and_or_b32 v8, v22, s48, v17
	v_and_or_b32 v7, v23, s48, v17
	v_add_u32_e32 v150, 0, v9
	v_lshl_add_u64 v[2:3], v[0:1], 0, s[8:9]
	v_lshl_add_u64 v[4:5], v[128:129], 0, s[4:5]
	v_lshl_or_b32 v6, v6, 10, v10
	v_lshl_or_b32 v8, v8, 10, v10
	v_lshl_or_b32 v10, v7, 10, v10
	v_add_u32_e32 v7, 0x8000, v150
	v_lshlrev_b64 v[12:13], 1, v[134:135]
	v_readfirstlane_b32 s4, v150
	v_lshl_add_u64 v[14:15], v[2:3], 0, v[12:13]
	s_mov_b32 m0, s4
	v_readfirstlane_b32 s4, v7
	v_mov_b32_e32 v7, v135
	v_add_u32_e32 v9, 0x2000, v150
	global_load_lds_dwordx4 v[14:15], off
	v_lshl_add_u64 v[12:13], v[4:5], 0, v[12:13]
	s_mov_b32 m0, s4
	v_lshlrev_b64 v[6:7], 1, v[6:7]
	v_readfirstlane_b32 s4, v9
	v_add_u32_e32 v9, 0xa000, v150
	global_load_lds_dwordx4 v[12:13], off
	v_lshl_add_u64 v[12:13], v[2:3], 0, v[6:7]
	s_mov_b32 m0, s4
	v_readfirstlane_b32 s4, v9
	global_load_lds_dwordx4 v[12:13], off
	v_lshl_add_u64 v[6:7], v[4:5], 0, v[6:7]
	s_mov_b32 m0, s4
	v_mov_b32_e32 v9, v135
	v_add_u32_e32 v11, 0x4000, v150
	global_load_lds_dwordx4 v[6:7], off
	v_lshlrev_b64 v[6:7], 1, v[8:9]
	v_readfirstlane_b32 s4, v11
	v_lshl_add_u64 v[8:9], v[2:3], 0, v[6:7]
	s_mov_b32 m0, s4
	v_lshl_add_u64 v[6:7], v[4:5], 0, v[6:7]
	global_load_lds_dwordx4 v[8:9], off
	v_add_u32_e32 v8, 0xc000, v150
	v_mov_b32_e32 v11, v135
	v_readfirstlane_b32 s4, v8
	s_mov_b32 m0, s4
	v_add_u32_e32 v8, 0x6000, v150
	global_load_lds_dwordx4 v[6:7], off
	v_lshlrev_b64 v[6:7], 1, v[10:11]
	v_readfirstlane_b32 s4, v8
	v_lshl_add_u64 v[2:3], v[2:3], 0, v[6:7]
	s_mov_b32 m0, s4
	v_and_b32_e32 v24, 15, v16
	global_load_lds_dwordx4 v[2:3], off
	v_lshl_add_u64 v[2:3], v[4:5], 0, v[6:7]
	v_add_u32_e32 v6, 0xe000, v150
	v_lshlrev_b32_e32 v10, 10, v17
	v_readfirstlane_b32 s4, v6
	s_mov_b32 m0, s4
	v_lshlrev_b32_e32 v6, 2, v16
	global_load_lds_dwordx4 v[2:3], off
	v_and_b32_e32 v2, 48, v16
	v_lshlrev_b32_e32 v3, 6, v24
	v_and_b32_e32 v6, 32, v6
	v_bitop3_b32 v151, v3, v6, v2 bitop3:0x36
	v_lshlrev_b32_e32 v3, 7, v16
	v_and_b32_e32 v152, 0x6000, v3
	v_lshlrev_b32_e32 v3, 6, v16
	v_and_b32_e32 v153, 0xffffc000, v3
	v_and_b32_e32 v3, 0x3c0, v3
	v_bitop3_b32 v154, v3, v6, v2 bitop3:0x36
	v_lshlrev_b32_e32 v2, 10, v23
	v_and_or_b32 v2, v2, s49, v19
	v_lshlrev_b32_e32 v6, 10, v22
	v_or3_b32 v134, v2, v10, v18
	v_and_or_b32 v6, v6, s49, v19
	v_lshlrev_b32_e32 v8, 10, v21
	v_lshlrev_b64 v[2:3], 1, v[134:135]
	v_or3_b32 v134, v6, v10, v18
	v_and_or_b32 v8, v8, s49, v19
	v_lshlrev_b32_e32 v11, 10, v20
	v_lshlrev_b64 v[6:7], 1, v[134:135]
	v_or3_b32 v134, v8, v10, v18
	v_and_or_b32 v11, v11, s49, v19
	s_nop 0
	v_lshl_add_u64 v[4:5], v[4:5], 0, s[10:11]
	v_lshlrev_b64 v[8:9], 1, v[134:135]
	v_or3_b32 v134, v11, v10, v18
	v_lshl_add_u64 v[0:1], v[0:1], 0, s[12:13]
	v_lshl_add_u64 v[138:139], v[4:5], 0, v[8:9]
	v_lshlrev_b64 v[10:11], 1, v[134:135]
	v_lshl_add_u64 v[146:147], v[0:1], 0, v[8:9]
	v_mov_b32_e32 v8, 0
	s_mov_b32 s6, 0
	v_lshl_add_u64 v[130:131], v[4:5], 0, v[2:3]
	v_lshl_add_u64 v[136:137], v[4:5], 0, v[6:7]
	v_lshl_add_u64 v[140:141], v[4:5], 0, v[10:11]
	v_lshl_add_u64 v[142:143], v[0:1], 0, v[2:3]
	v_lshl_add_u64 v[144:145], v[0:1], 0, v[6:7]
	v_lshl_add_u64 v[148:149], v[0:1], 0, v[10:11]
	s_mov_b64 s[4:5], 0
	v_mov_b32_e32 v9, v8
	v_mov_b32_e32 v10, v8
	v_mov_b32_e32 v11, v8
	v_mov_b32_e32 v20, v8
	v_mov_b32_e32 v21, v8
	v_mov_b32_e32 v22, v8
	v_mov_b32_e32 v23, v8
	v_mov_b32_e32 v28, v8
	v_mov_b32_e32 v29, v8
	v_mov_b32_e32 v30, v8
	v_mov_b32_e32 v31, v8
	v_mov_b32_e32 v36, v8
	v_mov_b32_e32 v37, v8
	v_mov_b32_e32 v38, v8
	v_mov_b32_e32 v39, v8
	v_mov_b32_e32 v0, v8
	v_mov_b32_e32 v1, v8
	v_mov_b32_e32 v2, v8
	v_mov_b32_e32 v3, v8
	v_mov_b32_e32 v4, v8
	v_mov_b32_e32 v5, v8
	v_mov_b32_e32 v6, v8
	v_mov_b32_e32 v7, v8
	v_mov_b32_e32 v12, v8
	v_mov_b32_e32 v13, v8
	v_mov_b32_e32 v14, v8
	v_mov_b32_e32 v15, v8
	v_mov_b32_e32 v16, v8
	v_mov_b32_e32 v17, v8
	v_mov_b32_e32 v18, v8
	v_mov_b32_e32 v19, v8
	v_mov_b32_e32 v24, v8
	v_mov_b32_e32 v25, v8
	v_mov_b32_e32 v26, v8
	v_mov_b32_e32 v27, v8
	v_mov_b32_e32 v32, v8
	v_mov_b32_e32 v33, v8
	v_mov_b32_e32 v34, v8
	v_mov_b32_e32 v35, v8
	v_mov_b32_e32 v40, v8
	v_mov_b32_e32 v41, v8
	v_mov_b32_e32 v42, v8
	v_mov_b32_e32 v43, v8
	v_mov_b32_e32 v44, v8
	v_mov_b32_e32 v45, v8
	v_mov_b32_e32 v46, v8
	v_mov_b32_e32 v47, v8
	v_mov_b32_e32 v48, v8
	v_mov_b32_e32 v49, v8
	v_mov_b32_e32 v50, v8
	v_mov_b32_e32 v51, v8
	v_mov_b32_e32 v52, v8
	v_mov_b32_e32 v53, v8
	v_mov_b32_e32 v54, v8
	v_mov_b32_e32 v55, v8
	v_mov_b32_e32 v56, v8
	v_mov_b32_e32 v57, v8
	v_mov_b32_e32 v58, v8
	v_mov_b32_e32 v59, v8
	v_mov_b32_e32 v60, v8
	v_mov_b32_e32 v61, v8
	v_mov_b32_e32 v62, v8
	v_mov_b32_e32 v63, v8
	v_mov_b32_e32 v64, v8
	v_mov_b32_e32 v65, v8
	v_mov_b32_e32 v66, v8
	v_mov_b32_e32 v67, v8
	v_mov_b32_e32 v68, v8
	v_mov_b32_e32 v69, v8
	v_mov_b32_e32 v70, v8
	v_mov_b32_e32 v71, v8
	v_mov_b32_e32 v72, v8
	v_mov_b32_e32 v73, v8
	v_mov_b32_e32 v74, v8
	v_mov_b32_e32 v75, v8
	v_mov_b32_e32 v76, v8
	v_mov_b32_e32 v77, v8
	v_mov_b32_e32 v78, v8
	v_mov_b32_e32 v79, v8
	v_mov_b32_e32 v80, v8
	v_mov_b32_e32 v81, v8
	v_mov_b32_e32 v82, v8
	v_mov_b32_e32 v83, v8
	v_mov_b32_e32 v84, v8
	v_mov_b32_e32 v85, v8
	v_mov_b32_e32 v86, v8
	v_mov_b32_e32 v87, v8
	v_mov_b32_e32 v88, v8
	v_mov_b32_e32 v89, v8
	v_mov_b32_e32 v90, v8
	v_mov_b32_e32 v91, v8
	v_mov_b32_e32 v92, v8
	v_mov_b32_e32 v93, v8
	v_mov_b32_e32 v94, v8
	v_mov_b32_e32 v95, v8
	v_mov_b32_e32 v96, v8
	v_mov_b32_e32 v97, v8
	v_mov_b32_e32 v98, v8
	v_mov_b32_e32 v99, v8
	v_mov_b32_e32 v100, v8
	v_mov_b32_e32 v101, v8
	v_mov_b32_e32 v102, v8
	v_mov_b32_e32 v103, v8
	v_mov_b32_e32 v104, v8
	v_mov_b32_e32 v105, v8
	v_mov_b32_e32 v106, v8
	v_mov_b32_e32 v107, v8
	v_mov_b32_e32 v108, v8
	v_mov_b32_e32 v109, v8
	v_mov_b32_e32 v110, v8
	v_mov_b32_e32 v111, v8
	v_mov_b32_e32 v112, v8
	v_mov_b32_e32 v113, v8
	v_mov_b32_e32 v114, v8
	v_mov_b32_e32 v115, v8
	v_mov_b32_e32 v116, v8
	v_mov_b32_e32 v117, v8
	v_mov_b32_e32 v118, v8
	v_mov_b32_e32 v119, v8
	v_mov_b32_e32 v120, v8
	v_mov_b32_e32 v121, v8
	v_mov_b32_e32 v122, v8
	v_mov_b32_e32 v123, v8
	v_mov_b32_e32 v124, v8
	v_mov_b32_e32 v125, v8
	v_mov_b32_e32 v126, v8
	v_mov_b32_e32 v127, v8
	v_or_b32_e32 v134, 0x800, v153
	v_or_b32_e32 v155, 0x1000, v153
	v_or_b32_e32 v156, 0x1800, v153
	v_or_b32_e32 v157, 0x2000, v153
	v_or_b32_e32 v158, 0x2800, v153
	v_or_b32_e32 v159, 0x3000, v153
	v_or_b32_e32 v160, 0x3800, v153
	s_waitcnt vmcnt(0) lgkmcnt(0)
	s_barrier
	v_readfirstlane_b32 s100, v150
	s_and_b32 s27, s6, 0x10000
	s_xor_b32 s28, s27, 0x10000
	s_add_i32 s27, s27, 0
	v_add3_u32 v161, s27, v151, v152
	v_add3_u32 v162, s27, v151, v153
	v_add3_u32 v163, s27, v154, v134
	v_add3_u32 v200, s27, v154, v155
	v_add3_u32 v201, s27, v154, v156
	v_add3_u32 v202, s27, v154, v157
	v_add3_u32 v203, s27, v154, v158
	v_add3_u32 v204, s27, v154, v159
	v_add3_u32 v205, s27, v154, v160
	ds_read_b128 v[184:187], v161 offset:32768
	ds_read_b128 v[168:171], v162
	ds_read_b128 v[172:175], v163
	ds_read_b128 v[176:179], v200
	ds_read_b128 v[180:183], v201
	ds_read_b128 v[188:191], v161 offset:34816
	ds_read_b128 v[192:195], v161 offset:36864
	ds_read_b128 v[196:199], v161 offset:38912
	s_add_i32 s101, s100, s28
	v_readfirstlane_b32 s98, v148
	v_readfirstlane_b32 s99, v149
	v_readfirstlane_b32 vcc_lo, v140
	v_readfirstlane_b32 vcc_hi, v141
	s_sub_u32 s98, s98, 0x1000000
	s_subb_u32 s99, s99, 0
	s_sub_u32 vcc_lo, vcc_lo, 0x1000000
	s_subb_u32 vcc_hi, vcc_hi, 0
	v_subrev_u32_e32 v148, s98, v148
	v_subrev_u32_e32 v140, vcc_lo, v140
	v_subrev_u32_e32 v146, s98, v146
	v_subrev_u32_e32 v138, vcc_lo, v138
	v_subrev_u32_e32 v144, s98, v144
	v_subrev_u32_e32 v136, vcc_lo, v136
	v_subrev_u32_e32 v142, s98, v142
	v_subrev_u32_e32 v130, vcc_lo, v130
	s_mov_b32 m0, s101
	s_nop 0
	global_load_lds_dwordx4 v148, s[98:99]
	s_add_i32 m0, s101, 0x8000
	s_nop 0
	global_load_lds_dwordx4 v140, vcc
	s_add_i32 m0, s101, 0x2000
	s_nop 0
	global_load_lds_dwordx4 v146, s[98:99]
	s_add_i32 m0, s101, 0xa000
	s_nop 0
	global_load_lds_dwordx4 v138, vcc
	s_add_i32 m0, s101, 0x4000
	s_nop 0
	global_load_lds_dwordx4 v144, s[98:99]
	s_add_i32 m0, s101, 0xc000
	s_nop 0
	global_load_lds_dwordx4 v136, vcc
	s_add_i32 m0, s101, 0x6000
	s_nop 0
	global_load_lds_dwordx4 v142, s[98:99]
	s_add_i32 m0, s101, 0xe000
	s_nop 0
	global_load_lds_dwordx4 v130, vcc

.LBB0_792:
	s_ashr_i32 s0, s52, 31
	s_lshr_b32 s0, s0, 26
	s_add_i32 s0, s52, s0
	s_and_b32 s28, s0, 0xffc0
	s_sub_i32 s28, s52, s28
	s_bfe_i32 s29, s28, 0x80000
	s_bfe_u32 s29, s29, 0x4000b
	s_add_i32 s29, s28, s29
	v_mov_b32_e32 v150, v132
	s_bfe_i32 s30, s29, 0x80000
	s_and_b32 s29, s29, 0xf0
	ds_read_b128 v[0:3], v133
	s_sub_i32 s28, s28, s29
	s_sext_i32_i8 s28, s28
	s_lshl_b32 s0, s0, 6
	s_and_b32 s0, s0, 0xfffff000
	s_lshl_b32 s28, s28, 8
	s_sext_i32_i16 s30, s30
	s_add_i32 s28, s28, s0
	v_mov_b32_e32 v12, v132
	s_lshl_b32 s0, s30, 4
	s_waitcnt lgkmcnt(0)
	v_readfirstlane_b32 s31, v3
	v_readfirstlane_b32 s53, v2
	s_ashr_i32 s29, s28, 31
	s_and_b32 s30, s0, 0xffffff00
	v_lshlrev_b32_e32 v3, 4, v12
	v_and_b32_e32 v2, 32, v12
	s_lshl_b64 s[36:37], s[28:29], 11
	v_lshrrev_b32_e32 v4, 1, v12
	v_bitop3_b32 v2, v3, v2, 48 bitop3:0x6c
	s_add_u32 s54, s53, s36
	v_bfe_u32 v13, v12, 2, 4
	v_and_b32_e32 v14, 32, v4
	v_lshrrev_b32_e32 v15, 1, v2
	v_ashrrev_i32_e32 v16, 3, v12
	s_addc_u32 s55, s31, s37
	v_or_b32_e32 v6, v15, v14
	v_and_or_b32 v2, v16, s44, v13
	s_add_u32 s42, s54, 0x2400000
	v_and_b32_e32 v5, 0xfffffc00, v3
	v_lshl_or_b32 v130, v2, 10, v6
	v_add_u32_e32 v2, 0x2000, v3
	v_add_u32_e32 v4, 0x4000, v3
	v_add_u32_e32 v3, 0x6000, v3
	s_addc_u32 s43, s55, 0
	s_add_i32 s0, s30, 0x1200
	v_ashrrev_i32_e32 v17, 7, v2
	v_ashrrev_i32_e32 v18, 7, v4
	v_ashrrev_i32_e32 v19, 7, v3
	s_lshl_b64 s[38:39], s[0:1], 11
	v_and_or_b32 v2, v17, s44, v13
	v_and_or_b32 v4, v18, s44, v13
	v_and_or_b32 v3, v19, s44, v13
	v_add_u32_e32 v151, 0, v5
	s_add_u32 s38, s53, s38
	v_lshl_or_b32 v2, v2, 10, v6
	v_lshl_or_b32 v4, v4, 10, v6
	v_lshl_or_b32 v6, v3, 10, v6
	v_add_u32_e32 v3, 0x8000, v151
	v_lshlrev_b64 v[8:9], 1, v[130:131]
	v_readfirstlane_b32 s0, v151
	s_addc_u32 s39, s31, s39
	v_lshl_add_u64 v[10:11], s[42:43], 0, v[8:9]
	s_mov_b32 m0, s0
	v_readfirstlane_b32 s0, v3
	v_mov_b32_e32 v3, v131
	v_add_u32_e32 v5, 0x2000, v151
	global_load_lds_dwordx4 v[10:11], off
	v_lshl_add_u64 v[8:9], s[38:39], 0, v[8:9]
	s_mov_b32 m0, s0
	v_lshlrev_b64 v[2:3], 1, v[2:3]
	v_readfirstlane_b32 s0, v5
	v_add_u32_e32 v5, 0xa000, v151
	global_load_lds_dwordx4 v[8:9], off
	v_lshl_add_u64 v[8:9], s[42:43], 0, v[2:3]
	s_mov_b32 m0, s0
	v_readfirstlane_b32 s0, v5
	global_load_lds_dwordx4 v[8:9], off
	v_lshl_add_u64 v[2:3], s[38:39], 0, v[2:3]
	s_mov_b32 m0, s0
	v_mov_b32_e32 v5, v131
	v_add_u32_e32 v7, 0x4000, v151
	global_load_lds_dwordx4 v[2:3], off
	v_lshlrev_b64 v[2:3], 1, v[4:5]
	v_readfirstlane_b32 s0, v7
	v_lshl_add_u64 v[4:5], s[42:43], 0, v[2:3]
	s_mov_b32 m0, s0
	v_lshl_add_u64 v[2:3], s[38:39], 0, v[2:3]
	global_load_lds_dwordx4 v[4:5], off
	v_add_u32_e32 v4, 0xc000, v151
	v_mov_b32_e32 v7, v131
	v_readfirstlane_b32 s0, v4
	s_mov_b32 m0, s0
	v_and_b32_e32 v20, 15, v12
	global_load_lds_dwordx4 v[2:3], off
	v_lshlrev_b64 v[2:3], 1, v[6:7]
	v_add_u32_e32 v6, 0x6000, v151
	v_lshl_add_u64 v[4:5], s[42:43], 0, v[2:3]
	v_readfirstlane_b32 s0, v6
	s_mov_b32 m0, s0
	v_lshl_add_u64 v[2:3], s[38:39], 0, v[2:3]
	global_load_lds_dwordx4 v[4:5], off
	v_add_u32_e32 v4, 0xe000, v151
	v_lshlrev_b32_e32 v8, 10, v13
	v_readfirstlane_b32 s0, v4
	s_mov_b32 m0, s0
	v_lshlrev_b32_e32 v4, 2, v12
	global_load_lds_dwordx4 v[2:3], off
	v_and_b32_e32 v2, 48, v12
	v_lshlrev_b32_e32 v3, 6, v20
	v_and_b32_e32 v4, 32, v4
	v_bitop3_b32 v152, v3, v4, v2 bitop3:0x36
	v_lshlrev_b32_e32 v3, 7, v12
	v_and_b32_e32 v153, 0x6000, v3
	v_lshlrev_b32_e32 v3, 6, v12
	v_and_b32_e32 v154, 0xffffc000, v3
	v_and_b32_e32 v3, 0x3c0, v3
	v_bitop3_b32 v156, v3, v4, v2 bitop3:0x36
	v_lshlrev_b32_e32 v2, 10, v19
	v_and_or_b32 v2, v2, s45, v15
	v_lshlrev_b32_e32 v4, 10, v18
	v_or3_b32 v130, v2, v8, v14
	v_and_or_b32 v4, v4, s45, v15
	v_lshlrev_b32_e32 v6, 10, v17
	v_lshlrev_b64 v[2:3], 1, v[130:131]
	v_or3_b32 v130, v4, v8, v14
	v_and_or_b32 v6, v6, s45, v15
	v_lshlrev_b32_e32 v9, 10, v16
	v_lshlrev_b64 v[4:5], 1, v[130:131]
	v_or3_b32 v130, v6, v8, v14
	v_and_or_b32 v9, v9, s45, v15
	s_add_u32 s38, s38, 0x80
	v_lshlrev_b64 v[6:7], 1, v[130:131]
	v_or3_b32 v130, v9, v8, v14
	s_addc_u32 s39, s39, 0
	v_lshlrev_b64 v[8:9], 1, v[130:131]
	s_nop 0
	v_lshl_add_u64 v[134:135], s[38:39], 0, v[2:3]
	v_lshl_add_u64 v[136:137], s[38:39], 0, v[4:5]
	v_lshl_add_u64 v[138:139], s[38:39], 0, v[6:7]
	v_lshl_add_u64 v[140:141], s[38:39], 0, v[8:9]
	s_add_u32 s38, s54, 0x2400080
	s_addc_u32 s39, s55, 0
	v_or_b32_e32 v155, 0x800, v154
	v_or_b32_e32 v157, 0x1000, v154
	v_or_b32_e32 v158, 0x1800, v154
	v_or_b32_e32 v159, 0x2000, v154
	v_or_b32_e32 v160, 0x2800, v154
	v_or_b32_e32 v161, 0x3000, v154
	v_or_b32_e32 v162, 0x3800, v154
	v_lshl_add_u64 v[142:143], s[38:39], 0, v[2:3]
	v_lshl_add_u64 v[144:145], s[38:39], 0, v[4:5]
	v_lshl_add_u64 v[146:147], s[38:39], 0, v[6:7]
	v_lshl_add_u64 v[148:149], s[38:39], 0, v[8:9]
	s_mov_b64 s[38:39], 0
	s_mov_b32 s0, 0
	v_mov_b32_e32 v14, 0
	v_mov_b32_e32 v15, v131
	v_mov_b32_e32 v16, v131
	v_mov_b32_e32 v17, v131
	v_mov_b32_e32 v22, 0
	v_mov_b32_e32 v23, v131
	v_mov_b32_e32 v24, v131
	v_mov_b32_e32 v25, v131
	v_mov_b32_e32 v30, 0
	v_mov_b32_e32 v31, v131
	v_mov_b32_e32 v32, v131
	v_mov_b32_e32 v33, v131
	v_mov_b32_e32 v38, 0
	v_mov_b32_e32 v39, v131
	v_mov_b32_e32 v40, v131
	v_mov_b32_e32 v41, v131
	v_mov_b32_e32 v2, 0
	v_mov_b32_e32 v3, v131
	v_mov_b32_e32 v4, v131
	v_mov_b32_e32 v5, v131
	v_mov_b32_e32 v6, 0
	v_mov_b32_e32 v7, v131
	v_mov_b32_e32 v8, v131
	v_mov_b32_e32 v9, v131
	v_mov_b32_e32 v10, 0
	v_mov_b32_e32 v11, v131
	v_mov_b32_e32 v12, v131
	v_mov_b32_e32 v13, v131
	v_mov_b32_e32 v18, 0
	v_mov_b32_e32 v19, v131
	v_mov_b32_e32 v20, v131
	v_mov_b32_e32 v21, v131
	v_mov_b32_e32 v26, 0
	v_mov_b32_e32 v27, v131
	v_mov_b32_e32 v28, v131
	v_mov_b32_e32 v29, v131
	v_mov_b32_e32 v34, 0
	v_mov_b32_e32 v35, v131
	v_mov_b32_e32 v36, v131
	v_mov_b32_e32 v37, v131
	v_mov_b32_e32 v42, 0
	v_mov_b32_e32 v43, v131
	v_mov_b32_e32 v44, v131
	v_mov_b32_e32 v45, v131
	v_mov_b32_e32 v46, 0
	v_mov_b32_e32 v47, v131
	v_mov_b32_e32 v48, v131
	v_mov_b32_e32 v49, v131
	v_mov_b32_e32 v50, 0
	v_mov_b32_e32 v51, v131
	v_mov_b32_e32 v52, v131
	v_mov_b32_e32 v53, v131
	v_mov_b32_e32 v54, 0
	v_mov_b32_e32 v55, v131
	v_mov_b32_e32 v56, v131
	v_mov_b32_e32 v57, v131
	v_mov_b32_e32 v58, 0
	v_mov_b32_e32 v59, v131
	v_mov_b32_e32 v60, v131
	v_mov_b32_e32 v61, v131
	v_mov_b32_e32 v62, 0
	v_mov_b32_e32 v63, v131
	v_mov_b32_e32 v64, v131
	v_mov_b32_e32 v65, v131
	v_mov_b32_e32 v66, 0
	v_mov_b32_e32 v67, v131
	v_mov_b32_e32 v68, v131
	v_mov_b32_e32 v69, v131
	v_mov_b32_e32 v70, 0
	v_mov_b32_e32 v71, v131
	v_mov_b32_e32 v72, v131
	v_mov_b32_e32 v73, v131
	v_mov_b32_e32 v74, 0
	v_mov_b32_e32 v75, v131
	v_mov_b32_e32 v76, v131
	v_mov_b32_e32 v77, v131
	v_mov_b32_e32 v78, 0
	v_mov_b32_e32 v79, v131
	v_mov_b32_e32 v80, v131
	v_mov_b32_e32 v81, v131
	v_mov_b32_e32 v82, 0
	v_mov_b32_e32 v83, v131
	v_mov_b32_e32 v84, v131
	v_mov_b32_e32 v85, v131
	v_mov_b32_e32 v86, 0
	v_mov_b32_e32 v87, v131
	v_mov_b32_e32 v88, v131
	v_mov_b32_e32 v89, v131
	v_mov_b32_e32 v90, 0
	v_mov_b32_e32 v91, v131
	v_mov_b32_e32 v92, v131
	v_mov_b32_e32 v93, v131
	v_mov_b32_e32 v94, 0
	v_mov_b32_e32 v95, v131
	v_mov_b32_e32 v96, v131
	v_mov_b32_e32 v97, v131
	v_mov_b32_e32 v98, 0
	v_mov_b32_e32 v99, v131
	v_mov_b32_e32 v100, v131
	v_mov_b32_e32 v101, v131
	v_mov_b32_e32 v102, 0
	v_mov_b32_e32 v103, v131
	v_mov_b32_e32 v104, v131
	v_mov_b32_e32 v105, v131
	v_mov_b32_e32 v106, 0
	v_mov_b32_e32 v107, v131
	v_mov_b32_e32 v108, v131
	v_mov_b32_e32 v109, v131
	v_mov_b32_e32 v110, 0
	v_mov_b32_e32 v111, v131
	v_mov_b32_e32 v112, v131
	v_mov_b32_e32 v113, v131
	v_mov_b32_e32 v114, 0
	v_mov_b32_e32 v115, v131
	v_mov_b32_e32 v116, v131
	v_mov_b32_e32 v117, v131
	v_mov_b32_e32 v118, 0
	v_mov_b32_e32 v119, v131
	v_mov_b32_e32 v120, v131
	v_mov_b32_e32 v121, v131
	v_mov_b32_e32 v122, 0
	v_mov_b32_e32 v123, v131
	v_mov_b32_e32 v124, v131
	v_mov_b32_e32 v125, v131
	v_mov_b32_e32 v126, 0
	v_mov_b32_e32 v127, v131
	v_mov_b32_e32 v128, v131
	v_mov_b32_e32 v129, v131
	s_waitcnt vmcnt(0) lgkmcnt(0)
	s_barrier
	v_readfirstlane_b32 s100, v151
	s_and_b32 s31, s0, 0x10000
	s_xor_b32 s42, s31, 0x10000
	s_add_i32 s31, s31, 0
	v_add3_u32 v130, s31, v152, v153
	v_add3_u32 v163, s31, v152, v154
	v_add3_u32 v196, s31, v156, v155
	v_add3_u32 v197, s31, v156, v157
	v_add3_u32 v198, s31, v156, v158
	v_add3_u32 v199, s31, v156, v159
	v_add3_u32 v200, s31, v156, v160
	v_add3_u32 v201, s31, v156, v161
	v_add3_u32 v202, s31, v156, v162
	ds_read_b128 v[180:183], v130 offset:32768
	ds_read_b128 v[164:167], v163
	ds_read_b128 v[168:171], v196
	ds_read_b128 v[172:175], v197
	ds_read_b128 v[176:179], v198
	ds_read_b128 v[184:187], v130 offset:34816
	ds_read_b128 v[188:191], v130 offset:36864
	ds_read_b128 v[192:195], v130 offset:38912
	s_add_i32 s101, s100, s42
	v_readfirstlane_b32 s98, v148
	v_readfirstlane_b32 s99, v149
	v_readfirstlane_b32 vcc_lo, v140
	v_readfirstlane_b32 vcc_hi, v141
	s_sub_u32 s98, s98, 0x1000000
	s_subb_u32 s99, s99, 0
	s_sub_u32 vcc_lo, vcc_lo, 0x1000000
	s_subb_u32 vcc_hi, vcc_hi, 0
	v_subrev_u32_e32 v148, s98, v148
	v_subrev_u32_e32 v140, vcc_lo, v140
	v_subrev_u32_e32 v146, s98, v146
	v_subrev_u32_e32 v138, vcc_lo, v138
	v_subrev_u32_e32 v144, s98, v144
	v_subrev_u32_e32 v136, vcc_lo, v136
	v_subrev_u32_e32 v142, s98, v142
	v_subrev_u32_e32 v134, vcc_lo, v134
	s_mov_b32 m0, s101
	s_nop 0
	global_load_lds_dwordx4 v148, s[98:99]
	s_add_i32 m0, s101, 0x8000
	s_nop 0
	global_load_lds_dwordx4 v140, vcc
	s_add_i32 m0, s101, 0x2000
	s_nop 0
	global_load_lds_dwordx4 v146, s[98:99]
	s_add_i32 m0, s101, 0xa000
	s_nop 0
	global_load_lds_dwordx4 v138, vcc
	s_add_i32 m0, s101, 0x4000
	s_nop 0
	global_load_lds_dwordx4 v144, s[98:99]
	s_add_i32 m0, s101, 0xc000
	s_nop 0
	global_load_lds_dwordx4 v136, vcc
	s_add_i32 m0, s101, 0x6000
	s_nop 0
	global_load_lds_dwordx4 v142, s[98:99]
	s_add_i32 m0, s101, 0xe000
	s_nop 0
	global_load_lds_dwordx4 v134, vcc

.Lex_793:
	s_waitcnt lgkmcnt(0)
	v_add3_u32 v130, s46, v156, v162
	v_add3_u32 v151, s46, v156, v161
	v_add3_u32 v202, s46, v156, v160
	v_add3_u32 v198, s46, v156, v159
	v_add3_u32 v186, s46, v156, v158
	v_add3_u32 v187, s46, v156, v157
	v_add3_u32 v188, s46, v156, v155
	v_add3_u32 v189, s46, v152, v154
	v_add3_u32 v190, s47, v152, v153
	ds_read_b128 v[134:137], v130
	ds_read_b128 v[138:141], v151
	ds_read_b128 v[142:145], v202
	ds_read_b128 v[146:149], v198
	ds_read_b128 v[158:161], v186
	ds_read_b128 v[162:165], v187
	ds_read_b128 v[166:169], v188
	ds_read_b128 v[154:157], v189
	ds_read_b128 v[170:173], v190
	s_waitcnt lgkmcnt(0)
	v_mfma_f32_16x16x32_bf16 v[18:21], v[170:173], v[138:141], v[18:21]
	v_mfma_f32_16x16x32_bf16 v[174:177], v[170:173], v[134:137], v[38:41]
	s_nop 2
	ds_read_b128 v[38:41], v190 offset:2048
	s_waitcnt lgkmcnt(0)
	v_mfma_f32_16x16x32_bf16 v[10:13], v[38:41], v[138:141], v[10:13]
	v_mfma_f32_16x16x32_bf16 v[62:65], v[170:173], v[146:149], v[62:65]
	v_mfma_f32_16x16x32_bf16 v[30:33], v[38:41], v[134:137], v[30:33]
	v_mfma_f32_16x16x32_bf16 v[58:61], v[38:41], v[146:149], v[58:61]
	ds_read_b128 v[178:181], v190 offset:4096
	s_waitcnt lgkmcnt(0)
	v_mfma_f32_16x16x32_bf16 v[182:185], v[178:181], v[134:137], v[22:25]
	v_mfma_f32_16x16x32_bf16 v[54:57], v[178:181], v[146:149], v[54:57]
	s_nop 1
	ds_read_b128 v[22:25], v190 offset:6144
	s_waitcnt lgkmcnt(0)
	v_mfma_f32_16x16x32_bf16 v[134:137], v[22:25], v[134:137], v[14:17]
	v_mfma_f32_16x16x32_bf16 v[14:17], v[22:25], v[154:157], v[114:117]
	v_mfma_f32_16x16x32_bf16 v[114:117], v[22:25], v[158:161], v[66:69]
	v_mfma_f32_16x16x32_bf16 v[66:69], v[178:181], v[154:157], v[118:121]
	v_mfma_f32_16x16x32_bf16 v[118:121], v[178:181], v[158:161], v[70:73]
	v_mfma_f32_16x16x32_bf16 v[70:73], v[38:41], v[154:157], v[122:125]
	v_mfma_f32_16x16x32_bf16 v[122:125], v[38:41], v[158:161], v[74:77]
	v_mfma_f32_16x16x32_bf16 v[74:77], v[170:173], v[154:157], v[126:129]
	v_mfma_f32_16x16x32_bf16 v[126:129], v[170:173], v[158:161], v[78:81]
	v_mfma_f32_16x16x32_bf16 v[50:53], v[22:25], v[146:149], v[50:53]
	v_mfma_f32_16x16x32_bf16 v[146:149], v[170:173], v[142:145], v[46:49]
	v_mfma_f32_16x16x32_bf16 v[152:155], v[38:41], v[142:145], v[42:45]
	v_mfma_f32_16x16x32_bf16 v[156:159], v[178:181], v[142:145], v[34:37]
	v_mfma_f32_16x16x32_bf16 v[26:29], v[22:25], v[142:145], v[26:29]
	v_mfma_f32_16x16x32_bf16 v[142:145], v[178:181], v[138:141], v[6:9]
	v_mfma_f32_16x16x32_bf16 v[110:113], v[170:173], v[166:169], v[110:113]
	v_mfma_f32_16x16x32_bf16 v[94:97], v[170:173], v[162:165], v[94:97]
	v_mfma_f32_16x16x32_bf16 v[106:109], v[38:41], v[166:169], v[106:109]
	v_mfma_f32_16x16x32_bf16 v[90:93], v[38:41], v[162:165], v[90:93]
	v_mfma_f32_16x16x32_bf16 v[102:105], v[178:181], v[166:169], v[102:105]
	v_mfma_f32_16x16x32_bf16 v[86:89], v[178:181], v[162:165], v[86:89]
	v_mfma_f32_16x16x32_bf16 v[98:101], v[22:25], v[166:169], v[98:101]
	v_mfma_f32_16x16x32_bf16 v[82:85], v[22:25], v[162:165], v[82:85]
	v_mfma_f32_16x16x32_bf16 v[22:25], v[22:25], v[138:141], v[2:5]
	ds_read_b128 v[138:141], v190 offset:1024
	ds_read_b128 v[160:163], v190 offset:3072
	ds_read_b128 v[164:167], v190 offset:5120
	ds_read_b128 v[168:171], v190 offset:7168
	ds_read_b128 v[2:5], v189 offset:1024
	ds_read_b128 v[6:9], v188 offset:1024
	ds_read_b128 v[34:37], v187 offset:1024
	ds_read_b128 v[38:41], v186 offset:1024
	s_waitcnt lgkmcnt(3)
	v_mfma_f32_16x16x32_bf16 v[178:181], v[138:141], v[2:5], v[74:77]
	v_mfma_f32_16x16x32_bf16 v[186:189], v[160:163], v[2:5], v[70:73]
	v_mfma_f32_16x16x32_bf16 v[190:193], v[164:167], v[2:5], v[66:69]
	v_mfma_f32_16x16x32_bf16 v[194:197], v[168:171], v[2:5], v[14:17]
	ds_read_b128 v[2:5], v198 offset:1024
	s_waitcnt lgkmcnt(3)
	v_mfma_f32_16x16x32_bf16 v[110:113], v[138:141], v[6:9], v[110:113]
	v_mfma_f32_16x16x32_bf16 v[106:109], v[160:163], v[6:9], v[106:109]
	v_mfma_f32_16x16x32_bf16 v[102:105], v[164:167], v[6:9], v[102:105]
	v_mfma_f32_16x16x32_bf16 v[198:201], v[168:171], v[6:9], v[98:101]
	ds_read_b128 v[6:9], v202 offset:1024
	s_waitcnt lgkmcnt(3)
	v_mfma_f32_16x16x32_bf16 v[66:69], v[138:141], v[34:37], v[94:97]
	v_mfma_f32_16x16x32_bf16 v[70:73], v[160:163], v[34:37], v[90:93]
	v_mfma_f32_16x16x32_bf16 v[74:77], v[164:167], v[34:37], v[86:89]
	v_mfma_f32_16x16x32_bf16 v[78:81], v[168:171], v[34:37], v[82:85]
	ds_read_b128 v[14:17], v151 offset:1024
	s_waitcnt lgkmcnt(3)
	v_mfma_f32_16x16x32_bf16 v[82:85], v[138:141], v[38:41], v[126:129]
	v_mfma_f32_16x16x32_bf16 v[86:89], v[160:163], v[38:41], v[122:125]
	v_mfma_f32_16x16x32_bf16 v[90:93], v[164:167], v[38:41], v[118:121]
	v_mfma_f32_16x16x32_bf16 v[94:97], v[168:171], v[38:41], v[114:117]
	ds_read_b128 v[98:101], v130 offset:1024
	s_waitcnt lgkmcnt(3)
	v_mfma_f32_16x16x32_bf16 v[34:37], v[138:141], v[2:5], v[62:65]
	v_mfma_f32_16x16x32_bf16 v[38:41], v[160:163], v[2:5], v[58:61]
	v_mfma_f32_16x16x32_bf16 v[42:45], v[164:167], v[2:5], v[54:57]
	v_mfma_f32_16x16x32_bf16 v[46:49], v[168:171], v[2:5], v[50:53]
	s_waitcnt lgkmcnt(2)
	v_mfma_f32_16x16x32_bf16 v[50:53], v[138:141], v[6:9], v[146:149]
	v_mfma_f32_16x16x32_bf16 v[54:57], v[160:163], v[6:9], v[152:155]
	v_mfma_f32_16x16x32_bf16 v[58:61], v[164:167], v[6:9], v[156:159]
	v_mfma_f32_16x16x32_bf16 v[62:65], v[168:171], v[6:9], v[26:29]
	s_waitcnt lgkmcnt(1)
	v_mfma_f32_16x16x32_bf16 v[2:5], v[138:141], v[14:17], v[18:21]
	v_mfma_f32_16x16x32_bf16 v[6:9], v[160:163], v[14:17], v[10:13]
	v_mfma_f32_16x16x32_bf16 v[10:13], v[164:167], v[14:17], v[142:145]
	v_mfma_f32_16x16x32_bf16 v[14:17], v[168:171], v[14:17], v[22:25]
	s_waitcnt lgkmcnt(0)
	v_mfma_f32_16x16x32_bf16 v[18:21], v[138:141], v[98:101], v[174:177]
	v_mfma_f32_16x16x32_bf16 v[22:25], v[160:163], v[98:101], v[30:33]
	v_mfma_f32_16x16x32_bf16 v[26:29], v[164:167], v[98:101], v[182:185]
	v_mfma_f32_16x16x32_bf16 v[30:33], v[168:171], v[98:101], v[134:137]
	v_lshrrev_b32_e32 v98, 6, v150
	v_mul_lo_u32 v98, v98, s48
	v_add_u32_e32 v101, s46, v98
	v_lshlrev_b32_e32 v98, 2, v150
	v_and_b32_e32 v100, 15, v150
	v_and_b32_e32 v115, 60, v98
	v_ashrrev_i32_e32 v98, 1, v150
	v_bfe_u32 v99, v150, 4, 2
	v_and_b32_e32 v114, 48, v150
	v_and_b32_e32 v116, 0xffffff80, v98
	v_lshlrev_b32_e32 v98, 2, v115
	v_mul_u32_u24_e32 v117, 0x110, v99
	v_mul_u32_u24_e32 v100, 0x110, v100
	v_add3_u32 v98, v101, v98, v117
	v_add3_u32 v101, v101, v114, v100
	s_waitcnt vmcnt(0)
	s_barrier
	ds_write_b128 v101, v[178:181]
	ds_write_b128 v101, v[186:189] offset:64
	ds_write_b128 v101, v[190:193] offset:128
	ds_write_b128 v101, v[194:197] offset:192
	ds_write_b128 v101, v[110:113] offset:4352
	ds_write_b128 v101, v[106:109] offset:4416
	ds_write_b128 v101, v[102:105] offset:4480
	ds_write_b128 v101, v[198:201] offset:4544
	ds_read_b128 v[102:105], v98
	v_add_u32_e32 v100, s28, v116
	s_ashr_i32 s31, s30, 31
	v_and_or_b32 v106, v150, s49, v115
	s_lshl_b64 s[38:39], s[30:31], 1
	s_waitcnt lgkmcnt(0)
	v_mul_f32_e32 v102, 0xbfb8aa3b, v102
	v_mul_f32_e32 v103, 0xbfb8aa3b, v103
	v_mul_f32_e32 v104, 0xbfb8aa3b, v104
	v_mul_f32_e32 v105, 0xbfb8aa3b, v105
	v_exp_f32_e32 v102, v102
	v_exp_f32_e32 v103, v103
	v_exp_f32_e32 v104, v104
	v_exp_f32_e32 v105, v105
	v_add_f32_e32 v102, 1.0, v102
	v_add_f32_e32 v103, 1.0, v103
	v_add_f32_e32 v104, 1.0, v104
	v_add_f32_e32 v105, 1.0, v105
	v_rcp_f32_e32 v102, v102
	v_rcp_f32_e32 v103, v103
	v_rcp_f32_e32 v104, v104
	v_rcp_f32_e32 v105, v105
	v_lshl_add_u64 v[0:1], v[0:1], 0, s[38:39]
	v_cvt_pk_bf16_f32 v102, v102, v103
	v_lshlrev_b32_e32 v130, 1, v106
	v_cvt_pk_bf16_f32 v103, v104, v105
	v_or_b32_e32 v104, v100, v99
	v_ashrrev_i32_e32 v105, 31, v104
	v_lshl_add_u64 v[0:1], v[0:1], 0, v[130:131]
	v_lshlrev_b64 v[104:105], 11, v[104:105]
	v_lshl_add_u64 v[104:105], v[0:1], 0, v[104:105]
	flat_store_dwordx2 v[104:105], v[102:103]
	ds_read_b128 v[102:105], v98 offset:1088
	s_lshl_b64 s[42:43], s[28:29], 10
	s_mov_b32 s29, 0
	s_waitcnt lgkmcnt(0)
	v_mul_f32_e32 v102, 0xbfb8aa3b, v102
	v_exp_f32_e32 v102, v102
	v_mul_f32_e32 v103, 0xbfb8aa3b, v103
	v_exp_f32_e32 v103, v103
	v_add_f32_e32 v102, 1.0, v102
	v_rcp_f32_e32 v106, v102
	v_add_f32_e32 v102, 1.0, v103
	v_mul_f32_e32 v103, 0xbfb8aa3b, v104
	v_exp_f32_e32 v103, v103
	v_mul_f32_e32 v104, 0xbfb8aa3b, v105
	v_exp_f32_e32 v104, v104
	v_rcp_f32_e32 v105, v102
	v_add_f32_e32 v102, 1.0, v103
	v_rcp_f32_e32 v103, v102
	v_add_f32_e32 v102, 1.0, v104
	v_rcp_f32_e32 v107, v102
	v_or_b32_e32 v102, 4, v99
	v_cvt_pk_bf16_f32 v104, v106, v105
	v_or_b32_e32 v106, v100, v102
	v_cvt_pk_bf16_f32 v105, v103, v107
	v_ashrrev_i32_e32 v107, 31, v106
	v_lshlrev_b64 v[106:107], 11, v[106:107]
	v_lshl_add_u64 v[106:107], v[0:1], 0, v[106:107]
	flat_store_dwordx2 v[106:107], v[104:105]
	ds_read_b128 v[104:107], v98 offset:2176
	s_waitcnt lgkmcnt(0)
	v_mul_f32_e32 v103, 0xbfb8aa3b, v104
	v_exp_f32_e32 v103, v103
	v_mul_f32_e32 v104, 0xbfb8aa3b, v105
	v_exp_f32_e32 v104, v104
	v_add_f32_e32 v103, 1.0, v103
	v_rcp_f32_e32 v105, v103
	v_add_f32_e32 v103, 1.0, v104
	v_mul_f32_e32 v104, 0xbfb8aa3b, v106
	v_exp_f32_e32 v104, v104
	v_mul_f32_e32 v106, 0xbfb8aa3b, v107
	v_exp_f32_e32 v106, v106
	v_rcp_f32_e32 v107, v103
	v_add_f32_e32 v103, 1.0, v104
	v_rcp_f32_e32 v108, v103
	v_add_f32_e32 v103, 1.0, v106
	v_rcp_f32_e32 v106, v103
	v_or_b32_e32 v103, 8, v99
	v_cvt_pk_bf16_f32 v104, v105, v107
	v_cvt_pk_bf16_f32 v105, v108, v106
	v_or_b32_e32 v106, v100, v103
	v_ashrrev_i32_e32 v107, 31, v106
	v_lshlrev_b64 v[106:107], 11, v[106:107]
	v_lshl_add_u64 v[106:107], v[0:1], 0, v[106:107]
	flat_store_dwordx2 v[106:107], v[104:105]
	ds_read_b128 v[104:107], v98 offset:3264
	s_waitcnt lgkmcnt(0)
	v_mul_f32_e32 v104, 0xbfb8aa3b, v104
	v_exp_f32_e32 v104, v104
	v_mul_f32_e32 v105, 0xbfb8aa3b, v105
	v_exp_f32_e32 v105, v105
	v_add_f32_e32 v104, 1.0, v104
	v_rcp_f32_e32 v108, v104
	v_add_f32_e32 v104, 1.0, v105
	v_mul_f32_e32 v105, 0xbfb8aa3b, v106
	v_exp_f32_e32 v105, v105
	v_mul_f32_e32 v106, 0xbfb8aa3b, v107
	v_exp_f32_e32 v106, v106
	v_rcp_f32_e32 v107, v104
	v_add_f32_e32 v104, 1.0, v105
	v_rcp_f32_e32 v105, v104
	v_add_f32_e32 v104, 1.0, v106
	v_rcp_f32_e32 v109, v104
	v_or_b32_e32 v104, 12, v99
	v_cvt_pk_bf16_f32 v106, v108, v107
	v_or_b32_e32 v108, v100, v104
	v_cvt_pk_bf16_f32 v107, v105, v109
	v_ashrrev_i32_e32 v109, 31, v108
	v_lshlrev_b64 v[108:109], 11, v[108:109]
	v_lshl_add_u64 v[108:109], v[0:1], 0, v[108:109]
	flat_store_dwordx2 v[108:109], v[106:107]
	ds_read_b128 v[106:109], v98 offset:4352
	s_waitcnt lgkmcnt(0)
	v_mul_f32_e32 v105, 0xbfb8aa3b, v106
	v_exp_f32_e32 v105, v105
	v_mul_f32_e32 v106, 0xbfb8aa3b, v107
	v_exp_f32_e32 v106, v106
	v_add_f32_e32 v105, 1.0, v105
	v_rcp_f32_e32 v107, v105
	v_add_f32_e32 v105, 1.0, v106
	v_mul_f32_e32 v106, 0xbfb8aa3b, v108
	v_exp_f32_e32 v106, v106
	v_mul_f32_e32 v108, 0xbfb8aa3b, v109
	v_exp_f32_e32 v108, v108
	v_rcp_f32_e32 v109, v105
	v_add_f32_e32 v105, 1.0, v106
	v_rcp_f32_e32 v110, v105
	v_add_f32_e32 v105, 1.0, v108
	v_rcp_f32_e32 v108, v105
	v_or_b32_e32 v105, 16, v99
	v_cvt_pk_bf16_f32 v106, v107, v109
	v_cvt_pk_bf16_f32 v107, v110, v108
	v_or_b32_e32 v108, v100, v105
	v_ashrrev_i32_e32 v109, 31, v108
	v_lshlrev_b64 v[108:109], 11, v[108:109]
	v_lshl_add_u64 v[108:109], v[0:1], 0, v[108:109]
	flat_store_dwordx2 v[108:109], v[106:107]
	ds_read_b128 v[106:109], v98 offset:5440
	s_waitcnt lgkmcnt(0)
	v_mul_f32_e32 v106, 0xbfb8aa3b, v106
	v_exp_f32_e32 v106, v106
	v_mul_f32_e32 v107, 0xbfb8aa3b, v107
	v_exp_f32_e32 v107, v107
	v_add_f32_e32 v106, 1.0, v106
	v_rcp_f32_e32 v110, v106
	v_add_f32_e32 v106, 1.0, v107
	v_mul_f32_e32 v107, 0xbfb8aa3b, v108
	v_exp_f32_e32 v107, v107
	v_mul_f32_e32 v108, 0xbfb8aa3b, v109
	v_exp_f32_e32 v108, v108
	v_rcp_f32_e32 v109, v106
	v_add_f32_e32 v106, 1.0, v107
	v_rcp_f32_e32 v107, v106
	v_add_f32_e32 v106, 1.0, v108
	v_rcp_f32_e32 v111, v106
	v_or_b32_e32 v106, 20, v99
	v_cvt_pk_bf16_f32 v108, v110, v109
	v_or_b32_e32 v110, v100, v106
	v_cvt_pk_bf16_f32 v109, v107, v111
	v_ashrrev_i32_e32 v111, 31, v110
	v_lshlrev_b64 v[110:111], 11, v[110:111]
	v_lshl_add_u64 v[110:111], v[0:1], 0, v[110:111]
	flat_store_dwordx2 v[110:111], v[108:109]
	ds_read_b128 v[108:111], v98 offset:6528
	s_waitcnt lgkmcnt(0)
	v_mul_f32_e32 v107, 0xbfb8aa3b, v108
	v_exp_f32_e32 v107, v107
	v_mul_f32_e32 v108, 0xbfb8aa3b, v109
	v_exp_f32_e32 v108, v108
	v_add_f32_e32 v107, 1.0, v107
	v_rcp_f32_e32 v109, v107
	v_add_f32_e32 v107, 1.0, v108
	v_mul_f32_e32 v108, 0xbfb8aa3b, v110
	v_exp_f32_e32 v108, v108
	v_mul_f32_e32 v110, 0xbfb8aa3b, v111
	v_exp_f32_e32 v110, v110
	v_rcp_f32_e32 v111, v107
	v_add_f32_e32 v107, 1.0, v108
	v_rcp_f32_e32 v112, v107
	v_add_f32_e32 v107, 1.0, v110
	v_rcp_f32_e32 v110, v107
	v_or_b32_e32 v107, 24, v99
	v_cvt_pk_bf16_f32 v108, v109, v111
	v_cvt_pk_bf16_f32 v109, v112, v110
	v_or_b32_e32 v110, v100, v107
	v_ashrrev_i32_e32 v111, 31, v110
	v_lshlrev_b64 v[110:111], 11, v[110:111]
	v_lshl_add_u64 v[110:111], v[0:1], 0, v[110:111]
	flat_store_dwordx2 v[110:111], v[108:109]
	ds_read_b128 v[108:111], v98 offset:7616
	s_waitcnt lgkmcnt(0)
	v_mul_f32_e32 v108, 0xbfb8aa3b, v108
	v_exp_f32_e32 v108, v108
	v_mul_f32_e32 v109, 0xbfb8aa3b, v109
	v_exp_f32_e32 v109, v109
	v_add_f32_e32 v108, 1.0, v108
	v_rcp_f32_e32 v112, v108
	v_add_f32_e32 v108, 1.0, v109
	v_mul_f32_e32 v109, 0xbfb8aa3b, v110
	v_exp_f32_e32 v109, v109
	v_mul_f32_e32 v110, 0xbfb8aa3b, v111
	v_exp_f32_e32 v110, v110
	v_rcp_f32_e32 v111, v108
	v_add_f32_e32 v108, 1.0, v109
	v_rcp_f32_e32 v109, v108
	v_add_f32_e32 v108, 1.0, v110
	v_rcp_f32_e32 v113, v108
	v_or_b32_e32 v108, 28, v99
	v_cvt_pk_bf16_f32 v110, v112, v111
	v_or_b32_e32 v112, v100, v108
	v_cvt_pk_bf16_f32 v111, v109, v113
	v_ashrrev_i32_e32 v113, 31, v112
	v_lshlrev_b64 v[112:113], 11, v[112:113]
	v_lshl_add_u64 v[112:113], v[0:1], 0, v[112:113]
	flat_store_dwordx2 v[112:113], v[110:111]
	ds_write_b128 v101, v[66:69]
	ds_write_b128 v101, v[70:73] offset:64
	ds_write_b128 v101, v[74:77] offset:128
	ds_write_b128 v101, v[78:81] offset:192
	ds_write_b128 v101, v[82:85] offset:4352
	ds_write_b128 v101, v[86:89] offset:4416
	ds_write_b128 v101, v[90:93] offset:4480
	ds_write_b128 v101, v[94:97] offset:4544
	ds_read_b128 v[66:69], v98
	v_or_b32_e32 v70, 32, v100
	s_waitcnt lgkmcnt(0)
	v_mul_f32_e32 v66, 0xbfb8aa3b, v66
	v_mul_f32_e32 v67, 0xbfb8aa3b, v67
	v_mul_f32_e32 v68, 0xbfb8aa3b, v68
	v_mul_f32_e32 v69, 0xbfb8aa3b, v69
	v_exp_f32_e32 v66, v66
	v_exp_f32_e32 v67, v67
	v_exp_f32_e32 v68, v68
	v_exp_f32_e32 v69, v69
	v_add_f32_e32 v66, 1.0, v66
	v_add_f32_e32 v67, 1.0, v67
	v_add_f32_e32 v68, 1.0, v68
	v_add_f32_e32 v69, 1.0, v69
	v_rcp_f32_e32 v66, v66
	v_rcp_f32_e32 v67, v67
	v_rcp_f32_e32 v68, v68
	v_rcp_f32_e32 v69, v69
	v_cvt_pk_bf16_f32 v66, v66, v67
	v_cvt_pk_bf16_f32 v67, v68, v69
	v_or_b32_e32 v68, v70, v99
	v_ashrrev_i32_e32 v69, 31, v68
	v_lshlrev_b64 v[68:69], 11, v[68:69]
	v_lshl_add_u64 v[68:69], v[0:1], 0, v[68:69]
	flat_store_dwordx2 v[68:69], v[66:67]
	ds_read_b128 v[66:69], v98 offset:1088
	s_waitcnt lgkmcnt(0)
	v_mul_f32_e32 v66, 0xbfb8aa3b, v66
	v_mul_f32_e32 v67, 0xbfb8aa3b, v67
	v_mul_f32_e32 v68, 0xbfb8aa3b, v68
	v_mul_f32_e32 v69, 0xbfb8aa3b, v69
	v_exp_f32_e32 v66, v66
	v_exp_f32_e32 v67, v67
	v_exp_f32_e32 v68, v68
	v_exp_f32_e32 v69, v69
	v_add_f32_e32 v66, 1.0, v66
	v_add_f32_e32 v67, 1.0, v67
	v_add_f32_e32 v68, 1.0, v68
	v_add_f32_e32 v69, 1.0, v69
	v_rcp_f32_e32 v66, v66
	v_rcp_f32_e32 v67, v67
	v_rcp_f32_e32 v68, v68
	v_rcp_f32_e32 v69, v69
	v_cvt_pk_bf16_f32 v66, v66, v67
	v_cvt_pk_bf16_f32 v67, v68, v69
	v_or_b32_e32 v68, v70, v102
	v_ashrrev_i32_e32 v69, 31, v68
	v_lshlrev_b64 v[68:69], 11, v[68:69]
	v_lshl_add_u64 v[68:69], v[0:1], 0, v[68:69]
	flat_store_dwordx2 v[68:69], v[66:67]
	ds_read_b128 v[66:69], v98 offset:2176
	s_waitcnt lgkmcnt(0)
	v_mul_f32_e32 v66, 0xbfb8aa3b, v66
	v_mul_f32_e32 v67, 0xbfb8aa3b, v67
	v_mul_f32_e32 v68, 0xbfb8aa3b, v68
	v_mul_f32_e32 v69, 0xbfb8aa3b, v69
	v_exp_f32_e32 v66, v66
	v_exp_f32_e32 v67, v67
	v_exp_f32_e32 v68, v68
	v_exp_f32_e32 v69, v69
	v_add_f32_e32 v66, 1.0, v66
	v_add_f32_e32 v67, 1.0, v67
	v_add_f32_e32 v68, 1.0, v68
	v_add_f32_e32 v69, 1.0, v69
	v_rcp_f32_e32 v66, v66
	v_rcp_f32_e32 v67, v67
	v_rcp_f32_e32 v68, v68
	v_rcp_f32_e32 v69, v69
	v_cvt_pk_bf16_f32 v66, v66, v67
	v_cvt_pk_bf16_f32 v67, v68, v69
	v_or_b32_e32 v68, v70, v103
	v_ashrrev_i32_e32 v69, 31, v68
	v_lshlrev_b64 v[68:69], 11, v[68:69]
	v_lshl_add_u64 v[68:69], v[0:1], 0, v[68:69]
	flat_store_dwordx2 v[68:69], v[66:67]
	ds_read_b128 v[66:69], v98 offset:3264
	s_waitcnt lgkmcnt(0)
	v_mul_f32_e32 v66, 0xbfb8aa3b, v66
	v_mul_f32_e32 v67, 0xbfb8aa3b, v67
	v_mul_f32_e32 v68, 0xbfb8aa3b, v68
	v_mul_f32_e32 v69, 0xbfb8aa3b, v69
	v_exp_f32_e32 v66, v66
	v_exp_f32_e32 v67, v67
	v_exp_f32_e32 v68, v68
	v_exp_f32_e32 v69, v69
	v_add_f32_e32 v66, 1.0, v66
	v_add_f32_e32 v67, 1.0, v67
	v_add_f32_e32 v68, 1.0, v68
	v_add_f32_e32 v69, 1.0, v69
	v_rcp_f32_e32 v66, v66
	v_rcp_f32_e32 v67, v67
	v_rcp_f32_e32 v68, v68
	v_rcp_f32_e32 v69, v69
	v_cvt_pk_bf16_f32 v66, v66, v67
	v_cvt_pk_bf16_f32 v67, v68, v69
	v_or_b32_e32 v68, v70, v104
	v_ashrrev_i32_e32 v69, 31, v68
	v_lshlrev_b64 v[68:69], 11, v[68:69]
	v_lshl_add_u64 v[68:69], v[0:1], 0, v[68:69]
	flat_store_dwordx2 v[68:69], v[66:67]
	ds_read_b128 v[66:69], v98 offset:4352
	s_waitcnt lgkmcnt(0)
	v_mul_f32_e32 v66, 0xbfb8aa3b, v66
	v_mul_f32_e32 v67, 0xbfb8aa3b, v67
	v_mul_f32_e32 v68, 0xbfb8aa3b, v68
	v_mul_f32_e32 v69, 0xbfb8aa3b, v69
	v_exp_f32_e32 v66, v66
	v_exp_f32_e32 v67, v67
	v_exp_f32_e32 v68, v68
	v_exp_f32_e32 v69, v69
	v_add_f32_e32 v66, 1.0, v66
	v_add_f32_e32 v67, 1.0, v67
	v_add_f32_e32 v68, 1.0, v68
	v_add_f32_e32 v69, 1.0, v69
	v_rcp_f32_e32 v66, v66
	v_rcp_f32_e32 v67, v67
	v_rcp_f32_e32 v68, v68
	v_rcp_f32_e32 v69, v69
	v_cvt_pk_bf16_f32 v66, v66, v67
	v_cvt_pk_bf16_f32 v67, v68, v69
	v_or_b32_e32 v68, v70, v105
	v_ashrrev_i32_e32 v69, 31, v68
	v_lshlrev_b64 v[68:69], 11, v[68:69]
	v_lshl_add_u64 v[68:69], v[0:1], 0, v[68:69]
	flat_store_dwordx2 v[68:69], v[66:67]
	ds_read_b128 v[66:69], v98 offset:5440
	s_waitcnt lgkmcnt(0)
	v_mul_f32_e32 v66, 0xbfb8aa3b, v66
	v_mul_f32_e32 v67, 0xbfb8aa3b, v67
	v_mul_f32_e32 v68, 0xbfb8aa3b, v68
	v_mul_f32_e32 v69, 0xbfb8aa3b, v69
	v_exp_f32_e32 v66, v66
	v_exp_f32_e32 v67, v67
	v_exp_f32_e32 v68, v68
	v_exp_f32_e32 v69, v69
	v_add_f32_e32 v66, 1.0, v66
	v_add_f32_e32 v67, 1.0, v67
	v_add_f32_e32 v68, 1.0, v68
	v_add_f32_e32 v69, 1.0, v69
	v_rcp_f32_e32 v66, v66
	v_rcp_f32_e32 v67, v67
	v_rcp_f32_e32 v68, v68
	v_rcp_f32_e32 v69, v69
	v_cvt_pk_bf16_f32 v66, v66, v67
	v_cvt_pk_bf16_f32 v67, v68, v69
	v_or_b32_e32 v68, v70, v106
	v_ashrrev_i32_e32 v69, 31, v68
	v_lshlrev_b64 v[68:69], 11, v[68:69]
	v_lshl_add_u64 v[68:69], v[0:1], 0, v[68:69]
	flat_store_dwordx2 v[68:69], v[66:67]
	ds_read_b128 v[66:69], v98 offset:6528
	s_waitcnt lgkmcnt(0)
	v_mul_f32_e32 v66, 0xbfb8aa3b, v66
	v_mul_f32_e32 v67, 0xbfb8aa3b, v67
	v_mul_f32_e32 v68, 0xbfb8aa3b, v68
	v_mul_f32_e32 v69, 0xbfb8aa3b, v69
	v_exp_f32_e32 v66, v66
	v_exp_f32_e32 v67, v67
	v_exp_f32_e32 v68, v68
	v_exp_f32_e32 v69, v69
	v_add_f32_e32 v66, 1.0, v66
	v_add_f32_e32 v67, 1.0, v67
	v_add_f32_e32 v68, 1.0, v68
	v_add_f32_e32 v69, 1.0, v69
	v_rcp_f32_e32 v66, v66
	v_rcp_f32_e32 v67, v67
	v_rcp_f32_e32 v68, v68
	v_rcp_f32_e32 v69, v69
	v_cvt_pk_bf16_f32 v66, v66, v67
	v_cvt_pk_bf16_f32 v67, v68, v69
	v_or_b32_e32 v68, v70, v107
	v_ashrrev_i32_e32 v69, 31, v68
	v_lshlrev_b64 v[68:69], 11, v[68:69]
	v_lshl_add_u64 v[68:69], v[0:1], 0, v[68:69]
	flat_store_dwordx2 v[68:69], v[66:67]
	ds_read_b128 v[66:69], v98 offset:7616
	s_waitcnt lgkmcnt(0)
	v_mul_f32_e32 v66, 0xbfb8aa3b, v66
	v_mul_f32_e32 v67, 0xbfb8aa3b, v67
	v_mul_f32_e32 v68, 0xbfb8aa3b, v68
	v_mul_f32_e32 v69, 0xbfb8aa3b, v69
	v_exp_f32_e32 v66, v66
	v_exp_f32_e32 v67, v67
	v_exp_f32_e32 v68, v68
	v_exp_f32_e32 v69, v69
	v_add_f32_e32 v66, 1.0, v66
	v_add_f32_e32 v67, 1.0, v67
	v_add_f32_e32 v68, 1.0, v68
	v_add_f32_e32 v69, 1.0, v69
	v_rcp_f32_e32 v66, v66
	v_rcp_f32_e32 v67, v67
	v_rcp_f32_e32 v68, v68
	v_rcp_f32_e32 v69, v69
	v_cvt_pk_bf16_f32 v66, v66, v67
	v_cvt_pk_bf16_f32 v67, v68, v69
	v_or_b32_e32 v68, v70, v108
	v_ashrrev_i32_e32 v69, 31, v68
	v_lshlrev_b64 v[68:69], 11, v[68:69]
	v_lshl_add_u64 v[68:69], v[0:1], 0, v[68:69]
	flat_store_dwordx2 v[68:69], v[66:67]
	ds_write_b128 v101, v[34:37]
	ds_write_b128 v101, v[38:41] offset:64
	ds_write_b128 v101, v[42:45] offset:128
	ds_write_b128 v101, v[46:49] offset:192
	ds_write_b128 v101, v[50:53] offset:4352
	ds_write_b128 v101, v[54:57] offset:4416
	ds_write_b128 v101, v[58:61] offset:4480
	ds_write_b128 v101, v[62:65] offset:4544
	ds_read_b128 v[34:37], v98
	v_or_b32_e32 v38, 64, v100
	s_waitcnt lgkmcnt(0)
	v_mul_f32_e32 v34, 0xbfb8aa3b, v34
	v_mul_f32_e32 v35, 0xbfb8aa3b, v35
	v_mul_f32_e32 v36, 0xbfb8aa3b, v36
	v_mul_f32_e32 v37, 0xbfb8aa3b, v37
	v_exp_f32_e32 v34, v34
	v_exp_f32_e32 v35, v35
	v_exp_f32_e32 v36, v36
	v_exp_f32_e32 v37, v37
	v_add_f32_e32 v34, 1.0, v34
	v_add_f32_e32 v35, 1.0, v35
	v_add_f32_e32 v36, 1.0, v36
	v_add_f32_e32 v37, 1.0, v37
	v_rcp_f32_e32 v34, v34
	v_rcp_f32_e32 v35, v35
	v_rcp_f32_e32 v36, v36
	v_rcp_f32_e32 v37, v37
	v_cvt_pk_bf16_f32 v34, v34, v35
	v_cvt_pk_bf16_f32 v35, v36, v37
	v_or_b32_e32 v36, v38, v99
	v_ashrrev_i32_e32 v37, 31, v36
	v_lshlrev_b64 v[36:37], 11, v[36:37]
	v_lshl_add_u64 v[36:37], v[0:1], 0, v[36:37]
	flat_store_dwordx2 v[36:37], v[34:35]
	ds_read_b128 v[34:37], v98 offset:1088
	s_waitcnt lgkmcnt(0)
	v_mul_f32_e32 v34, 0xbfb8aa3b, v34
	v_mul_f32_e32 v35, 0xbfb8aa3b, v35
	v_mul_f32_e32 v36, 0xbfb8aa3b, v36
	v_mul_f32_e32 v37, 0xbfb8aa3b, v37
	v_exp_f32_e32 v34, v34
	v_exp_f32_e32 v35, v35
	v_exp_f32_e32 v36, v36
	v_exp_f32_e32 v37, v37
	v_add_f32_e32 v34, 1.0, v34
	v_add_f32_e32 v35, 1.0, v35
	v_add_f32_e32 v36, 1.0, v36
	v_add_f32_e32 v37, 1.0, v37
	v_rcp_f32_e32 v34, v34
	v_rcp_f32_e32 v35, v35
	v_rcp_f32_e32 v36, v36
	v_rcp_f32_e32 v37, v37
	v_cvt_pk_bf16_f32 v34, v34, v35
	v_cvt_pk_bf16_f32 v35, v36, v37
	v_or_b32_e32 v36, v38, v102
	v_ashrrev_i32_e32 v37, 31, v36
	v_lshlrev_b64 v[36:37], 11, v[36:37]
	v_lshl_add_u64 v[36:37], v[0:1], 0, v[36:37]
	flat_store_dwordx2 v[36:37], v[34:35]
	ds_read_b128 v[34:37], v98 offset:2176
	s_waitcnt lgkmcnt(0)
	v_mul_f32_e32 v34, 0xbfb8aa3b, v34
	v_mul_f32_e32 v35, 0xbfb8aa3b, v35
	v_mul_f32_e32 v36, 0xbfb8aa3b, v36
	v_mul_f32_e32 v37, 0xbfb8aa3b, v37
	v_exp_f32_e32 v34, v34
	v_exp_f32_e32 v35, v35
	v_exp_f32_e32 v36, v36
	v_exp_f32_e32 v37, v37
	v_add_f32_e32 v34, 1.0, v34
	v_add_f32_e32 v35, 1.0, v35
	v_add_f32_e32 v36, 1.0, v36
	v_add_f32_e32 v37, 1.0, v37
	v_rcp_f32_e32 v34, v34
	v_rcp_f32_e32 v35, v35
	v_rcp_f32_e32 v36, v36
	v_rcp_f32_e32 v37, v37
	v_cvt_pk_bf16_f32 v34, v34, v35
	v_cvt_pk_bf16_f32 v35, v36, v37
	v_or_b32_e32 v36, v38, v103
	v_ashrrev_i32_e32 v37, 31, v36
	v_lshlrev_b64 v[36:37], 11, v[36:37]
	v_lshl_add_u64 v[36:37], v[0:1], 0, v[36:37]
	flat_store_dwordx2 v[36:37], v[34:35]
	ds_read_b128 v[34:37], v98 offset:3264
	s_waitcnt lgkmcnt(0)
	v_mul_f32_e32 v34, 0xbfb8aa3b, v34
	v_mul_f32_e32 v35, 0xbfb8aa3b, v35
	v_mul_f32_e32 v36, 0xbfb8aa3b, v36
	v_mul_f32_e32 v37, 0xbfb8aa3b, v37
	v_exp_f32_e32 v34, v34
	v_exp_f32_e32 v35, v35
	v_exp_f32_e32 v36, v36
	v_exp_f32_e32 v37, v37
	v_add_f32_e32 v34, 1.0, v34
	v_add_f32_e32 v35, 1.0, v35
	v_add_f32_e32 v36, 1.0, v36
	v_add_f32_e32 v37, 1.0, v37
	v_rcp_f32_e32 v34, v34
	v_rcp_f32_e32 v35, v35
	v_rcp_f32_e32 v36, v36
	v_rcp_f32_e32 v37, v37
	v_cvt_pk_bf16_f32 v34, v34, v35
	v_cvt_pk_bf16_f32 v35, v36, v37
	v_or_b32_e32 v36, v38, v104
	v_ashrrev_i32_e32 v37, 31, v36
	v_lshlrev_b64 v[36:37], 11, v[36:37]
	v_lshl_add_u64 v[36:37], v[0:1], 0, v[36:37]
	flat_store_dwordx2 v[36:37], v[34:35]
	ds_read_b128 v[34:37], v98 offset:4352
	s_waitcnt lgkmcnt(0)
	v_mul_f32_e32 v34, 0xbfb8aa3b, v34
	v_mul_f32_e32 v35, 0xbfb8aa3b, v35
	v_mul_f32_e32 v36, 0xbfb8aa3b, v36
	v_mul_f32_e32 v37, 0xbfb8aa3b, v37
	v_exp_f32_e32 v34, v34
	v_exp_f32_e32 v35, v35
	v_exp_f32_e32 v36, v36
	v_exp_f32_e32 v37, v37
	v_add_f32_e32 v34, 1.0, v34
	v_add_f32_e32 v35, 1.0, v35
	v_add_f32_e32 v36, 1.0, v36
	v_add_f32_e32 v37, 1.0, v37
	v_rcp_f32_e32 v34, v34
	v_rcp_f32_e32 v35, v35
	v_rcp_f32_e32 v36, v36
	v_rcp_f32_e32 v37, v37
	v_cvt_pk_bf16_f32 v34, v34, v35
	v_cvt_pk_bf16_f32 v35, v36, v37
	v_or_b32_e32 v36, v38, v105
	v_ashrrev_i32_e32 v37, 31, v36
	v_lshlrev_b64 v[36:37], 11, v[36:37]
	v_lshl_add_u64 v[36:37], v[0:1], 0, v[36:37]
	flat_store_dwordx2 v[36:37], v[34:35]
	ds_read_b128 v[34:37], v98 offset:5440
	s_waitcnt lgkmcnt(0)
	v_mul_f32_e32 v34, 0xbfb8aa3b, v34
	v_mul_f32_e32 v35, 0xbfb8aa3b, v35
	v_mul_f32_e32 v36, 0xbfb8aa3b, v36
	v_mul_f32_e32 v37, 0xbfb8aa3b, v37
	v_exp_f32_e32 v34, v34
	v_exp_f32_e32 v35, v35
	v_exp_f32_e32 v36, v36
	v_exp_f32_e32 v37, v37
	v_add_f32_e32 v34, 1.0, v34
	v_add_f32_e32 v35, 1.0, v35
	v_add_f32_e32 v36, 1.0, v36
	v_add_f32_e32 v37, 1.0, v37
	v_rcp_f32_e32 v34, v34
	v_rcp_f32_e32 v35, v35
	v_rcp_f32_e32 v36, v36
	v_rcp_f32_e32 v37, v37
	v_cvt_pk_bf16_f32 v34, v34, v35
	v_cvt_pk_bf16_f32 v35, v36, v37
	v_or_b32_e32 v36, v38, v106
	v_ashrrev_i32_e32 v37, 31, v36
	v_lshlrev_b64 v[36:37], 11, v[36:37]
	v_lshl_add_u64 v[36:37], v[0:1], 0, v[36:37]
	flat_store_dwordx2 v[36:37], v[34:35]
	ds_read_b128 v[34:37], v98 offset:6528
	s_waitcnt lgkmcnt(0)
	v_mul_f32_e32 v34, 0xbfb8aa3b, v34
	v_mul_f32_e32 v35, 0xbfb8aa3b, v35
	v_mul_f32_e32 v36, 0xbfb8aa3b, v36
	v_mul_f32_e32 v37, 0xbfb8aa3b, v37
	v_exp_f32_e32 v34, v34
	v_exp_f32_e32 v35, v35
	v_exp_f32_e32 v36, v36
	v_exp_f32_e32 v37, v37
	v_add_f32_e32 v34, 1.0, v34
	v_add_f32_e32 v35, 1.0, v35
	v_add_f32_e32 v36, 1.0, v36
	v_add_f32_e32 v37, 1.0, v37
	v_rcp_f32_e32 v34, v34
	v_rcp_f32_e32 v35, v35
	v_rcp_f32_e32 v36, v36
	v_rcp_f32_e32 v37, v37
	v_cvt_pk_bf16_f32 v34, v34, v35
	v_cvt_pk_bf16_f32 v35, v36, v37
	v_or_b32_e32 v36, v38, v107
	v_ashrrev_i32_e32 v37, 31, v36
	v_lshlrev_b64 v[36:37], 11, v[36:37]
	v_lshl_add_u64 v[36:37], v[0:1], 0, v[36:37]
	flat_store_dwordx2 v[36:37], v[34:35]
	ds_read_b128 v[34:37], v98 offset:7616
	s_waitcnt lgkmcnt(0)
	v_mul_f32_e32 v34, 0xbfb8aa3b, v34
	v_mul_f32_e32 v35, 0xbfb8aa3b, v35
	v_mul_f32_e32 v36, 0xbfb8aa3b, v36
	v_mul_f32_e32 v37, 0xbfb8aa3b, v37
	v_exp_f32_e32 v34, v34
	v_exp_f32_e32 v35, v35
	v_exp_f32_e32 v36, v36
	v_exp_f32_e32 v37, v37
	v_add_f32_e32 v34, 1.0, v34
	v_add_f32_e32 v35, 1.0, v35
	v_add_f32_e32 v36, 1.0, v36
	v_add_f32_e32 v37, 1.0, v37
	v_rcp_f32_e32 v34, v34
	v_rcp_f32_e32 v35, v35
	v_rcp_f32_e32 v36, v36
	v_rcp_f32_e32 v37, v37
	v_cvt_pk_bf16_f32 v34, v34, v35
	v_cvt_pk_bf16_f32 v35, v36, v37
	v_or_b32_e32 v36, v38, v108
	v_ashrrev_i32_e32 v37, 31, v36
	v_lshlrev_b64 v[36:37], 11, v[36:37]
	v_lshl_add_u64 v[36:37], v[0:1], 0, v[36:37]
	flat_store_dwordx2 v[36:37], v[34:35]
	ds_write_b128 v101, v[2:5]
	ds_write_b128 v101, v[6:9] offset:64
	ds_write_b128 v101, v[10:13] offset:128
	ds_write_b128 v101, v[14:17] offset:192
	ds_write_b128 v101, v[18:21] offset:4352
	ds_write_b128 v101, v[22:25] offset:4416
	ds_write_b128 v101, v[26:29] offset:4480
	ds_write_b128 v101, v[30:33] offset:4544
	ds_read_b128 v[2:5], v98
	v_or_b32_e32 v6, 0x60, v100
	v_mov_b32_e32 v20, v132
	v_mov_b32_e32 v7, v131
	v_mov_b32_e32 v11, v131
	s_waitcnt lgkmcnt(0)
	v_mul_f32_e32 v2, 0xbfb8aa3b, v2
	v_mul_f32_e32 v3, 0xbfb8aa3b, v3
	v_mul_f32_e32 v4, 0xbfb8aa3b, v4
	v_mul_f32_e32 v5, 0xbfb8aa3b, v5
	v_exp_f32_e32 v2, v2
	v_exp_f32_e32 v3, v3
	v_exp_f32_e32 v4, v4
	v_exp_f32_e32 v5, v5
	v_add_f32_e32 v2, 1.0, v2
	v_add_f32_e32 v3, 1.0, v3
	v_add_f32_e32 v4, 1.0, v4
	v_add_f32_e32 v5, 1.0, v5
	v_rcp_f32_e32 v2, v2
	v_rcp_f32_e32 v3, v3
	v_rcp_f32_e32 v4, v4
	v_rcp_f32_e32 v5, v5
	v_mov_b32_e32 v19, v131
	v_cvt_pk_bf16_f32 v2, v2, v3
	v_cvt_pk_bf16_f32 v3, v4, v5
	v_or_b32_e32 v4, v6, v99
	v_ashrrev_i32_e32 v5, 31, v4
	v_lshlrev_b64 v[4:5], 11, v[4:5]
	v_lshl_add_u64 v[4:5], v[0:1], 0, v[4:5]
	flat_store_dwordx2 v[4:5], v[2:3]
	ds_read_b128 v[2:5], v98 offset:1088
	s_waitcnt lgkmcnt(0)
	v_mul_f32_e32 v2, 0xbfb8aa3b, v2
	v_mul_f32_e32 v3, 0xbfb8aa3b, v3
	v_mul_f32_e32 v4, 0xbfb8aa3b, v4
	v_mul_f32_e32 v5, 0xbfb8aa3b, v5
	v_exp_f32_e32 v2, v2
	v_exp_f32_e32 v3, v3
	v_exp_f32_e32 v4, v4
	v_exp_f32_e32 v5, v5
	v_add_f32_e32 v2, 1.0, v2
	v_add_f32_e32 v3, 1.0, v3
	v_add_f32_e32 v4, 1.0, v4
	v_add_f32_e32 v5, 1.0, v5
	v_rcp_f32_e32 v2, v2
	v_rcp_f32_e32 v3, v3
	v_rcp_f32_e32 v4, v4
	v_rcp_f32_e32 v5, v5
	v_cvt_pk_bf16_f32 v2, v2, v3
	v_cvt_pk_bf16_f32 v3, v4, v5
	v_or_b32_e32 v4, v6, v102
	v_ashrrev_i32_e32 v5, 31, v4
	v_lshlrev_b64 v[4:5], 11, v[4:5]
	v_lshl_add_u64 v[4:5], v[0:1], 0, v[4:5]
	flat_store_dwordx2 v[4:5], v[2:3]
	ds_read_b128 v[2:5], v98 offset:2176
	s_waitcnt lgkmcnt(0)
	v_mul_f32_e32 v2, 0xbfb8aa3b, v2
	v_mul_f32_e32 v3, 0xbfb8aa3b, v3
	v_mul_f32_e32 v4, 0xbfb8aa3b, v4
	v_mul_f32_e32 v5, 0xbfb8aa3b, v5
	v_exp_f32_e32 v2, v2
	v_exp_f32_e32 v3, v3
	v_exp_f32_e32 v4, v4
	v_exp_f32_e32 v5, v5
	v_add_f32_e32 v2, 1.0, v2
	v_add_f32_e32 v3, 1.0, v3
	v_add_f32_e32 v4, 1.0, v4
	v_add_f32_e32 v5, 1.0, v5
	v_rcp_f32_e32 v2, v2
	v_rcp_f32_e32 v3, v3
	v_rcp_f32_e32 v4, v4
	v_rcp_f32_e32 v5, v5
	v_cvt_pk_bf16_f32 v2, v2, v3
	v_cvt_pk_bf16_f32 v3, v4, v5
	v_or_b32_e32 v4, v6, v103
	v_ashrrev_i32_e32 v5, 31, v4
	v_lshlrev_b64 v[4:5], 11, v[4:5]
	v_lshl_add_u64 v[4:5], v[0:1], 0, v[4:5]
	flat_store_dwordx2 v[4:5], v[2:3]
	ds_read_b128 v[2:5], v98 offset:3264
	s_waitcnt lgkmcnt(0)
	v_mul_f32_e32 v2, 0xbfb8aa3b, v2
	v_mul_f32_e32 v3, 0xbfb8aa3b, v3
	v_mul_f32_e32 v4, 0xbfb8aa3b, v4
	v_mul_f32_e32 v5, 0xbfb8aa3b, v5
	v_exp_f32_e32 v2, v2
	v_exp_f32_e32 v3, v3
	v_exp_f32_e32 v4, v4
	v_exp_f32_e32 v5, v5
	v_add_f32_e32 v2, 1.0, v2
	v_add_f32_e32 v3, 1.0, v3
	v_add_f32_e32 v4, 1.0, v4
	v_add_f32_e32 v5, 1.0, v5
	v_rcp_f32_e32 v2, v2
	v_rcp_f32_e32 v3, v3
	v_rcp_f32_e32 v4, v4
	v_rcp_f32_e32 v5, v5
	v_cvt_pk_bf16_f32 v2, v2, v3
	v_cvt_pk_bf16_f32 v3, v4, v5
	v_or_b32_e32 v4, v6, v104
	v_ashrrev_i32_e32 v5, 31, v4
	v_lshlrev_b64 v[4:5], 11, v[4:5]
	v_lshl_add_u64 v[4:5], v[0:1], 0, v[4:5]
	flat_store_dwordx2 v[4:5], v[2:3]
	ds_read_b128 v[2:5], v98 offset:4352
	s_waitcnt lgkmcnt(0)
	v_mul_f32_e32 v2, 0xbfb8aa3b, v2
	v_mul_f32_e32 v3, 0xbfb8aa3b, v3
	v_mul_f32_e32 v4, 0xbfb8aa3b, v4
	v_mul_f32_e32 v5, 0xbfb8aa3b, v5
	v_exp_f32_e32 v2, v2
	v_exp_f32_e32 v3, v3
	v_exp_f32_e32 v4, v4
	v_exp_f32_e32 v5, v5
	v_add_f32_e32 v2, 1.0, v2
	v_add_f32_e32 v3, 1.0, v3
	v_add_f32_e32 v4, 1.0, v4
	v_add_f32_e32 v5, 1.0, v5
	v_rcp_f32_e32 v2, v2
	v_rcp_f32_e32 v3, v3
	v_rcp_f32_e32 v4, v4
	v_rcp_f32_e32 v5, v5
	v_cvt_pk_bf16_f32 v2, v2, v3
	v_cvt_pk_bf16_f32 v3, v4, v5
	v_or_b32_e32 v4, v6, v105
	v_ashrrev_i32_e32 v5, 31, v4
	v_lshlrev_b64 v[4:5], 11, v[4:5]
	v_lshl_add_u64 v[4:5], v[0:1], 0, v[4:5]
	flat_store_dwordx2 v[4:5], v[2:3]
	ds_read_b128 v[2:5], v98 offset:5440
	s_waitcnt lgkmcnt(0)
	v_mul_f32_e32 v2, 0xbfb8aa3b, v2
	v_mul_f32_e32 v3, 0xbfb8aa3b, v3
	v_mul_f32_e32 v4, 0xbfb8aa3b, v4
	v_mul_f32_e32 v5, 0xbfb8aa3b, v5
	v_exp_f32_e32 v2, v2
	v_exp_f32_e32 v3, v3
	v_exp_f32_e32 v4, v4
	v_exp_f32_e32 v5, v5
	v_add_f32_e32 v2, 1.0, v2
	v_add_f32_e32 v3, 1.0, v3
	v_add_f32_e32 v4, 1.0, v4
	v_add_f32_e32 v5, 1.0, v5
	v_rcp_f32_e32 v2, v2
	v_rcp_f32_e32 v3, v3
	v_rcp_f32_e32 v4, v4
	v_rcp_f32_e32 v5, v5
	v_cvt_pk_bf16_f32 v2, v2, v3
	v_cvt_pk_bf16_f32 v3, v4, v5
	v_or_b32_e32 v4, v6, v106
	v_ashrrev_i32_e32 v5, 31, v4
	v_lshlrev_b64 v[4:5], 11, v[4:5]
	v_lshl_add_u64 v[4:5], v[0:1], 0, v[4:5]
	flat_store_dwordx2 v[4:5], v[2:3]
	ds_read_b128 v[2:5], v98 offset:6528
	s_waitcnt lgkmcnt(0)
	v_mul_f32_e32 v2, 0xbfb8aa3b, v2
	v_mul_f32_e32 v3, 0xbfb8aa3b, v3
	v_mul_f32_e32 v4, 0xbfb8aa3b, v4
	v_mul_f32_e32 v5, 0xbfb8aa3b, v5
	v_exp_f32_e32 v2, v2
	v_exp_f32_e32 v3, v3
	v_exp_f32_e32 v4, v4
	v_exp_f32_e32 v5, v5
	v_add_f32_e32 v2, 1.0, v2
	v_add_f32_e32 v3, 1.0, v3
	v_add_f32_e32 v4, 1.0, v4
	v_add_f32_e32 v5, 1.0, v5
	v_rcp_f32_e32 v2, v2
	v_rcp_f32_e32 v3, v3
	v_rcp_f32_e32 v4, v4
	v_rcp_f32_e32 v5, v5
	v_cvt_pk_bf16_f32 v2, v2, v3
	v_cvt_pk_bf16_f32 v3, v4, v5
	v_or_b32_e32 v4, v6, v107
	v_ashrrev_i32_e32 v5, 31, v4
	v_lshlrev_b64 v[4:5], 11, v[4:5]
	v_lshl_add_u64 v[4:5], v[0:1], 0, v[4:5]
	flat_store_dwordx2 v[4:5], v[2:3]
	ds_read_b128 v[2:5], v98 offset:7616
	v_mov_b32_e32 v98, v132
	s_waitcnt lgkmcnt(0)
	v_mul_f32_e32 v2, 0xbfb8aa3b, v2
	v_mul_f32_e32 v3, 0xbfb8aa3b, v3
	v_mul_f32_e32 v4, 0xbfb8aa3b, v4
	v_mul_f32_e32 v5, 0xbfb8aa3b, v5
	v_exp_f32_e32 v2, v2
	v_exp_f32_e32 v3, v3
	v_exp_f32_e32 v4, v4
	v_exp_f32_e32 v5, v5
	v_add_f32_e32 v2, 1.0, v2
	v_add_f32_e32 v3, 1.0, v3
	v_add_f32_e32 v4, 1.0, v4
	v_add_f32_e32 v5, 1.0, v5
	v_rcp_f32_e32 v2, v2
	v_rcp_f32_e32 v3, v3
	v_rcp_f32_e32 v4, v4
	v_rcp_f32_e32 v5, v5
	v_cvt_pk_bf16_f32 v2, v2, v3
	v_cvt_pk_bf16_f32 v3, v4, v5
	v_or_b32_e32 v4, v6, v108
	v_ashrrev_i32_e32 v5, 31, v4
	v_lshlrev_b64 v[4:5], 11, v[4:5]
	v_lshl_add_u64 v[0:1], v[0:1], 0, v[4:5]
	flat_store_dwordx2 v[0:1], v[2:3]
	v_mov_b32_e32 v0, s3
	ds_read_b128 v[0:3], v0
	s_waitcnt lgkmcnt(0)
	v_lshl_add_u64 v[4:5], v[2:3], 0, s[42:43]
	s_lshl_b64 s[42:43], s[30:31], 10
	v_lshl_add_u64 v[2:3], v[2:3], 0, s[42:43]
	v_lshl_add_u64 v[16:17], v[2:3], 0, s[12:13]
	v_lshlrev_b32_e32 v2, 4, v20
	v_and_b32_e32 v3, 32, v20
	v_bitop3_b32 v3, v2, v3, 48 bitop3:0x6c
	v_lshl_add_u64 v[14:15], v[4:5], 0, s[10:11]
	v_lshrrev_b32_e32 v5, 1, v20
	v_lshrrev_b32_e32 v3, 1, v3
	v_bfe_u32 v4, v20, 2, 4
	v_and_or_b32 v3, v5, 32, v3
	v_lshrrev_b32_e32 v5, 3, v20
	v_and_or_b32 v5, v5, s50, v4
	v_lshl_or_b32 v130, v5, 9, v3
	v_add_u32_e32 v5, 0x2000, v2
	v_lshrrev_b32_e32 v5, 7, v5
	v_and_or_b32 v5, v5, s50, v4
	v_lshl_or_b32 v6, v5, 9, v3
	v_add_u32_e32 v5, 0x4000, v2
	v_and_b32_e32 v21, 0xfffffc00, v2
	v_lshrrev_b32_e32 v5, 7, v5
	v_add_u32_e32 v2, 0x6000, v2
	v_and_or_b32 v5, v5, s50, v4
	v_lshrrev_b32_e32 v2, 7, v2
	v_add_u32_e32 v45, 0, v21
	v_lshl_or_b32 v10, v5, 9, v3
	v_and_or_b32 v2, v2, s50, v4
	v_add_u32_e32 v44, 0x8000, v45
	v_lshlrev_b64 v[4:5], 1, v[130:131]
	v_readfirstlane_b32 s60, v45
	v_lshl_or_b32 v18, v2, 9, v3
	v_lshl_add_u64 v[2:3], v[14:15], 0, v[4:5]
	s_mov_b32 m0, s60
	v_readfirstlane_b32 s58, v44
	v_add_u32_e32 v46, 0x2000, v45
	global_load_lds_dwordx4 v[2:3], off
	v_lshl_add_u64 v[4:5], v[16:17], 0, v[4:5]
	s_mov_b32 m0, s58
	v_lshlrev_b64 v[8:9], 1, v[6:7]
	v_readfirstlane_b32 s59, v46
	v_add_u32_e32 v47, 0xa000, v45
	global_load_lds_dwordx4 v[4:5], off
	v_lshl_add_u64 v[6:7], v[14:15], 0, v[8:9]
	s_mov_b32 m0, s59
	v_readfirstlane_b32 s61, v47
	v_add_u32_e32 v48, 0x4000, v45
	global_load_lds_dwordx4 v[6:7], off
	v_lshl_add_u64 v[8:9], v[16:17], 0, v[8:9]
	s_mov_b32 m0, s61
	v_lshlrev_b64 v[12:13], 1, v[10:11]
	v_readfirstlane_b32 s62, v48
	v_add_u32_e32 v49, 0xc000, v45
	v_lshlrev_b64 v[18:19], 1, v[18:19]
	v_and_b32_e32 v22, 15, v20
	global_load_lds_dwordx4 v[8:9], off
	v_lshl_add_u64 v[10:11], v[14:15], 0, v[12:13]
	s_mov_b32 m0, s62
	v_lshl_add_u64 v[12:13], v[16:17], 0, v[12:13]
	v_readfirstlane_b32 s63, v49
	v_lshl_add_u64 v[14:15], v[14:15], 0, v[18:19]
	v_add_u32_e32 v50, 0x6000, v45
	v_lshl_add_u64 v[16:17], v[16:17], 0, v[18:19]
	v_lshlrev_b32_e32 v19, 2, v20
	global_load_lds_dwordx4 v[10:11], off
	s_mov_b32 m0, s63
	v_readfirstlane_b32 s64, v50
	v_add_u32_e32 v51, 0xe000, v45
	v_and_b32_e32 v23, 48, v20
	v_lshlrev_b32_e32 v18, 6, v22
	v_and_b32_e32 v22, 32, v19
	global_load_lds_dwordx4 v[12:13], off
	s_mov_b32 m0, s64
	v_readfirstlane_b32 s65, v51
	v_bitop3_b32 v96, v18, v22, v23 bitop3:0x36
	v_lshlrev_b32_e32 v18, 7, v20
	v_add_u32_e32 v37, s46, v21
	global_load_lds_dwordx4 v[14:15], off
	s_mov_b32 m0, s65
	v_and_b32_e32 v97, 0x6000, v18
	v_lshlrev_b32_e32 v18, 6, v20
	v_add_u32_e32 v36, s47, v21
	v_readfirstlane_b32 s53, v37
	global_load_lds_dwordx4 v[16:17], off
	v_and_b32_e32 v99, 0xffffc000, v18
	v_and_b32_e32 v20, 0x3c0, v18
	v_lshl_add_u64 v[18:19], v[2:3], 0, s[6:7]
	s_mov_b32 m0, s53
	v_readfirstlane_b32 s0, v36
	v_add_u32_e32 v38, 0x2000, v37
	s_waitcnt vmcnt(0)
	s_waitcnt vmcnt(0) lgkmcnt(0)
	s_barrier
	global_load_lds_dwordx4 v[18:19], off
	v_lshl_add_u64 v[18:19], v[4:5], 0, s[6:7]
	s_mov_b32 m0, s0
	v_readfirstlane_b32 s42, v38
	v_add_u32_e32 v39, 0x2000, v36
	global_load_lds_dwordx4 v[18:19], off
	v_lshl_add_u64 v[18:19], v[6:7], 0, s[6:7]
	s_mov_b32 m0, s42
	v_readfirstlane_b32 s43, v39
	v_add_u32_e32 v40, 0x4000, v37
	global_load_lds_dwordx4 v[18:19], off
	v_lshl_add_u64 v[18:19], v[8:9], 0, s[6:7]
	s_mov_b32 m0, s43
	v_readfirstlane_b32 s54, v40
	v_add_u32_e32 v41, 0x4000, v36
	global_load_lds_dwordx4 v[18:19], off
	v_lshl_add_u64 v[18:19], v[10:11], 0, s[6:7]
	s_mov_b32 m0, s54
	v_readfirstlane_b32 s55, v41
	v_add_u32_e32 v42, 0x6000, v37
	global_load_lds_dwordx4 v[18:19], off
	v_lshl_add_u64 v[18:19], v[12:13], 0, s[6:7]
	s_mov_b32 m0, s55
	v_readfirstlane_b32 s56, v42
	v_add_u32_e32 v43, 0x6000, v36
	global_load_lds_dwordx4 v[18:19], off
	v_lshl_add_u64 v[18:19], v[14:15], 0, s[6:7]
	s_mov_b32 m0, s56
	v_readfirstlane_b32 s57, v43
	global_load_lds_dwordx4 v[18:19], off
	v_lshl_add_u64 v[18:19], v[16:17], 0, s[6:7]
	s_mov_b32 m0, s57
	v_add_u32_e32 v129, 0, v96
	global_load_lds_dwordx4 v[18:19], off
	v_add_u32_e32 v18, v129, v97
	ds_read_b128 v[24:27], v18 offset:32768
	ds_read_b128 v[56:59], v18 offset:34816
	ds_read_b128 v[64:67], v18 offset:36864
	ds_read_b128 v[72:75], v18 offset:38912
	v_bitop3_b32 v130, v20, v22, v23 bitop3:0x36
	v_add_u32_e32 v23, 0, v130
	v_or_b32_e32 v222, 0x3000, v99
	v_add_u32_e32 v20, v23, v222
	ds_read_b128 v[32:35], v20
	v_or_b32_e32 v223, 0x2800, v99
	v_add_u32_e32 v21, v23, v223
	s_waitcnt lgkmcnt(0)
	v_mfma_f32_16x16x32_bf16 v[76:79], v[24:27], v[32:35], 0
	v_or_b32_e32 v128, 0x3800, v99
	v_or_b32_e32 v218, 0x2000, v99
	v_or_b32_e32 v219, 0x1000, v99
	v_mfma_f32_16x16x32_bf16 v[80:83], v[56:59], v[32:35], 0
	v_or_b32_e32 v220, 0x1800, v99
	v_add_u32_e32 v19, v23, v128
	v_add_u32_e32 v22, v23, v218
	v_mfma_f32_16x16x32_bf16 v[84:87], v[64:67], v[32:35], 0
	ds_read_b128 v[28:31], v19
	ds_read_b128 v[112:115], v22
	v_mfma_f32_16x16x32_bf16 v[88:91], v[72:75], v[32:35], 0
	ds_read_b128 v[32:35], v21
	s_waitcnt lgkmcnt(0)
	v_mfma_f32_16x16x32_bf16 v[92:95], v[24:27], v[32:35], 0
	v_mfma_f32_16x16x32_bf16 v[100:103], v[56:59], v[32:35], 0
	v_mfma_f32_16x16x32_bf16 v[104:107], v[64:67], v[32:35], 0
	v_mfma_f32_16x16x32_bf16 v[108:111], v[72:75], v[32:35], 0
	v_add_u32_e32 v32, v129, v99
	v_or_b32_e32 v129, 0x800, v99
	v_add_u32_e32 v33, v23, v129
	v_add_u32_e32 v34, v23, v219
	v_add_u32_e32 v35, v23, v220
	ds_read_b128 v[134:137], v32
	ds_read_b128 v[150:153], v33
	ds_read_b128 v[166:169], v34
	ds_read_b128 v[182:185], v35
	s_waitcnt lgkmcnt(0)
	v_mfma_f32_16x16x32_bf16 v[178:181], v[64:67], v[166:169], 0
	v_mfma_f32_16x16x32_bf16 v[162:165], v[64:67], v[150:153], 0
	v_mfma_f32_16x16x32_bf16 v[146:149], v[64:67], v[134:137], 0
	v_mfma_f32_16x16x32_bf16 v[68:71], v[64:67], v[28:31], 0
	v_mfma_f32_16x16x32_bf16 v[124:127], v[64:67], v[112:115], 0
	v_mfma_f32_16x16x32_bf16 v[64:67], v[64:67], v[182:185], 0
	v_mfma_f32_16x16x32_bf16 v[174:177], v[56:59], v[166:169], 0
	v_mfma_f32_16x16x32_bf16 v[158:161], v[56:59], v[150:153], 0
	v_mfma_f32_16x16x32_bf16 v[142:145], v[56:59], v[134:137], 0
	v_mfma_f32_16x16x32_bf16 v[60:63], v[56:59], v[28:31], 0
	v_mfma_f32_16x16x32_bf16 v[120:123], v[56:59], v[112:115], 0
	v_mfma_f32_16x16x32_bf16 v[56:59], v[56:59], v[182:185], 0
	v_mfma_f32_16x16x32_bf16 v[170:173], v[24:27], v[166:169], 0
	v_mfma_f32_16x16x32_bf16 v[154:157], v[24:27], v[150:153], 0
	v_mfma_f32_16x16x32_bf16 v[138:141], v[24:27], v[134:137], 0
	v_mfma_f32_16x16x32_bf16 v[52:55], v[24:27], v[28:31], 0
	v_mfma_f32_16x16x32_bf16 v[116:119], v[24:27], v[112:115], 0
	v_mfma_f32_16x16x32_bf16 v[24:27], v[24:27], v[182:185], 0
	v_mfma_f32_16x16x32_bf16 v[166:169], v[72:75], v[166:169], 0
	v_mfma_f32_16x16x32_bf16 v[150:153], v[72:75], v[150:153], 0
	v_mfma_f32_16x16x32_bf16 v[134:137], v[72:75], v[134:137], 0
	v_mfma_f32_16x16x32_bf16 v[28:31], v[72:75], v[28:31], 0
	v_mfma_f32_16x16x32_bf16 v[112:115], v[72:75], v[112:115], 0
	v_mfma_f32_16x16x32_bf16 v[72:75], v[72:75], v[182:185], 0
	ds_read_b128 v[182:185], v18 offset:33792
	ds_read_b128 v[186:189], v18 offset:35840
	ds_read_b128 v[190:193], v18 offset:37888
	ds_read_b128 v[198:201], v18 offset:39936
	ds_read_b128 v[194:197], v32 offset:1024
	ds_read_b128 v[202:205], v33 offset:1024
	ds_read_b128 v[206:209], v34 offset:1024
	ds_read_b128 v[210:213], v35 offset:1024
	s_waitcnt lgkmcnt(0)
	v_mfma_f32_16x16x32_bf16 v[138:141], v[182:185], v[194:197], v[138:141]
	v_mfma_f32_16x16x32_bf16 v[142:145], v[186:189], v[194:197], v[142:145]
	v_mfma_f32_16x16x32_bf16 v[146:149], v[190:193], v[194:197], v[146:149]
	v_mfma_f32_16x16x32_bf16 v[134:137], v[198:201], v[194:197], v[134:137]
	ds_read_b128 v[194:197], v22 offset:1024
	v_mfma_f32_16x16x32_bf16 v[154:157], v[182:185], v[202:205], v[154:157]
	v_mfma_f32_16x16x32_bf16 v[158:161], v[186:189], v[202:205], v[158:161]
	v_mfma_f32_16x16x32_bf16 v[162:165], v[190:193], v[202:205], v[162:165]
	v_mfma_f32_16x16x32_bf16 v[150:153], v[198:201], v[202:205], v[150:153]
	ds_read_b128 v[202:205], v21 offset:1024
	v_mfma_f32_16x16x32_bf16 v[170:173], v[182:185], v[206:209], v[170:173]
	v_mfma_f32_16x16x32_bf16 v[174:177], v[186:189], v[206:209], v[174:177]
	v_mfma_f32_16x16x32_bf16 v[178:181], v[190:193], v[206:209], v[178:181]
	v_mfma_f32_16x16x32_bf16 v[166:169], v[198:201], v[206:209], v[166:169]
	ds_read_b128 v[206:209], v20 offset:1024
	v_mfma_f32_16x16x32_bf16 v[214:217], v[182:185], v[210:213], v[24:27]
	v_mfma_f32_16x16x32_bf16 v[56:59], v[186:189], v[210:213], v[56:59]
	v_mfma_f32_16x16x32_bf16 v[64:67], v[190:193], v[210:213], v[64:67]
	v_mfma_f32_16x16x32_bf16 v[72:75], v[198:201], v[210:213], v[72:75]
	ds_read_b128 v[24:27], v19 offset:1024
	s_waitcnt lgkmcnt(0)
	v_mfma_f32_16x16x32_bf16 v[116:119], v[182:185], v[194:197], v[116:119]
	v_mfma_f32_16x16x32_bf16 v[120:123], v[186:189], v[194:197], v[120:123]
	v_mfma_f32_16x16x32_bf16 v[124:127], v[190:193], v[194:197], v[124:127]
	v_mfma_f32_16x16x32_bf16 v[112:115], v[198:201], v[194:197], v[112:115]
	v_mfma_f32_16x16x32_bf16 v[92:95], v[182:185], v[202:205], v[92:95]
	v_mfma_f32_16x16x32_bf16 v[100:103], v[186:189], v[202:205], v[100:103]
	v_mfma_f32_16x16x32_bf16 v[104:107], v[190:193], v[202:205], v[104:107]
	v_mfma_f32_16x16x32_bf16 v[108:111], v[198:201], v[202:205], v[108:111]
	v_mfma_f32_16x16x32_bf16 v[76:79], v[182:185], v[206:209], v[76:79]
	v_mfma_f32_16x16x32_bf16 v[80:83], v[186:189], v[206:209], v[80:83]
	v_mfma_f32_16x16x32_bf16 v[84:87], v[190:193], v[206:209], v[84:87]
	v_mfma_f32_16x16x32_bf16 v[88:91], v[198:201], v[206:209], v[88:91]
	v_mfma_f32_16x16x32_bf16 v[52:55], v[182:185], v[24:27], v[52:55]
	v_mfma_f32_16x16x32_bf16 v[60:63], v[186:189], v[24:27], v[60:63]
	v_mfma_f32_16x16x32_bf16 v[68:71], v[190:193], v[24:27], v[68:71]
	v_mfma_f32_16x16x32_bf16 v[182:185], v[198:201], v[24:27], v[28:31]
	s_mov_b32 m0, s60
	v_lshl_add_u64 v[24:25], v[2:3], 0, s[14:15]
	s_waitcnt vmcnt(0)
	s_waitcnt vmcnt(0)
	s_barrier
	global_load_lds_dwordx4 v[24:25], off
	v_lshl_add_u64 v[24:25], v[4:5], 0, s[14:15]
	s_mov_b32 m0, s58
	v_add3_u32 v23, s47, v96, v97
	global_load_lds_dwordx4 v[24:25], off
	v_lshl_add_u64 v[24:25], v[6:7], 0, s[14:15]
	s_mov_b32 m0, s59
	s_nop 0
	global_load_lds_dwordx4 v[24:25], off
	v_lshl_add_u64 v[24:25], v[8:9], 0, s[14:15]
	s_mov_b32 m0, s61
	s_nop 0
	global_load_lds_dwordx4 v[24:25], off
	v_lshl_add_u64 v[24:25], v[10:11], 0, s[14:15]
	s_mov_b32 m0, s62
	s_nop 0
	global_load_lds_dwordx4 v[24:25], off
	v_lshl_add_u64 v[24:25], v[12:13], 0, s[14:15]
	s_mov_b32 m0, s63
	s_nop 0
	global_load_lds_dwordx4 v[24:25], off
	v_lshl_add_u64 v[24:25], v[14:15], 0, s[14:15]
	s_mov_b32 m0, s64
	s_nop 0
	global_load_lds_dwordx4 v[24:25], off
	v_lshl_add_u64 v[24:25], v[16:17], 0, s[14:15]
	s_mov_b32 m0, s65
	s_nop 0
	global_load_lds_dwordx4 v[24:25], off
	ds_read_b128 v[186:189], v23
	ds_read_b128 v[190:193], v23 offset:2048
	ds_read_b128 v[194:197], v23 offset:4096
	ds_read_b128 v[198:201], v23 offset:6144
	v_add3_u32 v24, s46, v96, v99
	v_add_u32_e32 v96, s46, v130
	ds_read_b128 v[28:31], v24
	v_add_u32_e32 v25, v96, v129
	v_add_u32_e32 v26, v96, v219
	v_add_u32_e32 v27, v96, v220
	ds_read_b128 v[202:205], v25
	ds_read_b128 v[206:209], v26
	ds_read_b128 v[210:213], v27
	s_waitcnt lgkmcnt(0)
	v_mfma_f32_16x16x32_bf16 v[138:141], v[186:189], v[28:31], v[138:141]
	v_mfma_f32_16x16x32_bf16 v[142:145], v[190:193], v[28:31], v[142:145]
	v_mfma_f32_16x16x32_bf16 v[146:149], v[194:197], v[28:31], v[146:149]
	v_mfma_f32_16x16x32_bf16 v[134:137], v[198:201], v[28:31], v[134:137]
	v_add_u32_e32 v28, v96, v218
	v_add_u32_e32 v29, v96, v223
	v_add_u32_e32 v30, v96, v222
	v_add_u32_e32 v31, v96, v128
	ds_read_b128 v[218:221], v28
	v_mfma_f32_16x16x32_bf16 v[154:157], v[186:189], v[202:205], v[154:157]
	v_mfma_f32_16x16x32_bf16 v[158:161], v[190:193], v[202:205], v[158:161]
	v_mfma_f32_16x16x32_bf16 v[162:165], v[194:197], v[202:205], v[162:165]
	v_mfma_f32_16x16x32_bf16 v[150:153], v[198:201], v[202:205], v[150:153]
	ds_read_b128 v[202:205], v29
	v_mfma_f32_16x16x32_bf16 v[170:173], v[186:189], v[206:209], v[170:173]
	v_mfma_f32_16x16x32_bf16 v[174:177], v[190:193], v[206:209], v[174:177]
	v_mfma_f32_16x16x32_bf16 v[178:181], v[194:197], v[206:209], v[178:181]
	v_mfma_f32_16x16x32_bf16 v[166:169], v[198:201], v[206:209], v[166:169]
	ds_read_b128 v[206:209], v30
	v_mfma_f32_16x16x32_bf16 v[214:217], v[186:189], v[210:213], v[214:217]
	v_mfma_f32_16x16x32_bf16 v[56:59], v[190:193], v[210:213], v[56:59]
	v_mfma_f32_16x16x32_bf16 v[64:67], v[194:197], v[210:213], v[64:67]
	v_mfma_f32_16x16x32_bf16 v[72:75], v[198:201], v[210:213], v[72:75]
	ds_read_b128 v[210:213], v31
	s_waitcnt lgkmcnt(0)
	v_mfma_f32_16x16x32_bf16 v[116:119], v[186:189], v[218:221], v[116:119]
	v_mfma_f32_16x16x32_bf16 v[120:123], v[190:193], v[218:221], v[120:123]
	v_mfma_f32_16x16x32_bf16 v[124:127], v[194:197], v[218:221], v[124:127]
	v_mfma_f32_16x16x32_bf16 v[112:115], v[198:201], v[218:221], v[112:115]
	v_mfma_f32_16x16x32_bf16 v[92:95], v[186:189], v[202:205], v[92:95]
	v_mfma_f32_16x16x32_bf16 v[100:103], v[190:193], v[202:205], v[100:103]
	v_mfma_f32_16x16x32_bf16 v[104:107], v[194:197], v[202:205], v[104:107]
	v_mfma_f32_16x16x32_bf16 v[108:111], v[198:201], v[202:205], v[108:111]
	v_mfma_f32_16x16x32_bf16 v[76:79], v[186:189], v[206:209], v[76:79]
	v_mfma_f32_16x16x32_bf16 v[80:83], v[190:193], v[206:209], v[80:83]
	v_mfma_f32_16x16x32_bf16 v[84:87], v[194:197], v[206:209], v[84:87]
	v_mfma_f32_16x16x32_bf16 v[88:91], v[198:201], v[206:209], v[88:91]
	v_mfma_f32_16x16x32_bf16 v[52:55], v[186:189], v[210:213], v[52:55]
	v_mfma_f32_16x16x32_bf16 v[60:63], v[190:193], v[210:213], v[60:63]
	v_mfma_f32_16x16x32_bf16 v[68:71], v[194:197], v[210:213], v[68:71]
	v_mfma_f32_16x16x32_bf16 v[182:185], v[198:201], v[210:213], v[182:185]
	ds_read_b128 v[186:189], v23 offset:1024
	ds_read_b128 v[190:193], v23 offset:3072
	ds_read_b128 v[194:197], v23 offset:5120
	ds_read_b128 v[202:205], v23 offset:7168
	ds_read_b128 v[198:201], v24 offset:1024
	ds_read_b128 v[206:209], v25 offset:1024
	ds_read_b128 v[210:213], v26 offset:1024
	ds_read_b128 v[218:221], v27 offset:1024
	s_waitcnt lgkmcnt(0)
	v_mfma_f32_16x16x32_bf16 v[138:141], v[186:189], v[198:201], v[138:141]
	v_mfma_f32_16x16x32_bf16 v[142:145], v[190:193], v[198:201], v[142:145]
	v_mfma_f32_16x16x32_bf16 v[146:149], v[194:197], v[198:201], v[146:149]
	v_mfma_f32_16x16x32_bf16 v[134:137], v[202:205], v[198:201], v[134:137]
	ds_read_b128 v[198:201], v28 offset:1024
	v_mfma_f32_16x16x32_bf16 v[154:157], v[186:189], v[206:209], v[154:157]
	v_mfma_f32_16x16x32_bf16 v[158:161], v[190:193], v[206:209], v[158:161]
	v_mfma_f32_16x16x32_bf16 v[162:165], v[194:197], v[206:209], v[162:165]
	v_mfma_f32_16x16x32_bf16 v[150:153], v[202:205], v[206:209], v[150:153]
	ds_read_b128 v[206:209], v29 offset:1024
	v_mfma_f32_16x16x32_bf16 v[170:173], v[186:189], v[210:213], v[170:173]
	v_mfma_f32_16x16x32_bf16 v[174:177], v[190:193], v[210:213], v[174:177]
	v_mfma_f32_16x16x32_bf16 v[178:181], v[194:197], v[210:213], v[178:181]
	v_mfma_f32_16x16x32_bf16 v[166:169], v[202:205], v[210:213], v[166:169]
	ds_read_b128 v[210:213], v30 offset:1024
	v_mfma_f32_16x16x32_bf16 v[214:217], v[186:189], v[218:221], v[214:217]
	v_mfma_f32_16x16x32_bf16 v[56:59], v[190:193], v[218:221], v[56:59]
	v_mfma_f32_16x16x32_bf16 v[64:67], v[194:197], v[218:221], v[64:67]
	v_mfma_f32_16x16x32_bf16 v[72:75], v[202:205], v[218:221], v[72:75]
	ds_read_b128 v[218:221], v31 offset:1024
	s_waitcnt lgkmcnt(0)
	v_mfma_f32_16x16x32_bf16 v[116:119], v[186:189], v[198:201], v[116:119]
	v_mfma_f32_16x16x32_bf16 v[120:123], v[190:193], v[198:201], v[120:123]
	v_mfma_f32_16x16x32_bf16 v[124:127], v[194:197], v[198:201], v[124:127]
	v_mfma_f32_16x16x32_bf16 v[112:115], v[202:205], v[198:201], v[112:115]
	v_mfma_f32_16x16x32_bf16 v[92:95], v[186:189], v[206:209], v[92:95]
	v_mfma_f32_16x16x32_bf16 v[100:103], v[190:193], v[206:209], v[100:103]
	v_mfma_f32_16x16x32_bf16 v[104:107], v[194:197], v[206:209], v[104:107]
	v_mfma_f32_16x16x32_bf16 v[108:111], v[202:205], v[206:209], v[108:111]
	v_mfma_f32_16x16x32_bf16 v[76:79], v[186:189], v[210:213], v[76:79]
	v_mfma_f32_16x16x32_bf16 v[80:83], v[190:193], v[210:213], v[80:83]
	v_mfma_f32_16x16x32_bf16 v[84:87], v[194:197], v[210:213], v[84:87]
	v_mfma_f32_16x16x32_bf16 v[88:91], v[202:205], v[210:213], v[88:91]
	v_mfma_f32_16x16x32_bf16 v[52:55], v[186:189], v[218:221], v[52:55]
	v_mfma_f32_16x16x32_bf16 v[60:63], v[190:193], v[218:221], v[60:63]
	v_mfma_f32_16x16x32_bf16 v[68:71], v[194:197], v[218:221], v[68:71]
	v_mfma_f32_16x16x32_bf16 v[182:185], v[202:205], v[218:221], v[182:185]
	s_mov_b32 m0, s53
	v_lshl_add_u64 v[96:97], v[2:3], 0, s[16:17]
	s_waitcnt vmcnt(0)
	s_waitcnt vmcnt(0)
	s_barrier
	global_load_lds_dwordx4 v[96:97], off
	v_lshl_add_u64 v[96:97], v[4:5], 0, s[16:17]
	s_mov_b32 m0, s0
	s_nop 0
	global_load_lds_dwordx4 v[96:97], off
	v_lshl_add_u64 v[96:97], v[6:7], 0, s[16:17]
	s_mov_b32 m0, s42
	s_nop 0
	global_load_lds_dwordx4 v[96:97], off
	v_lshl_add_u64 v[96:97], v[8:9], 0, s[16:17]
	s_mov_b32 m0, s43
	s_nop 0
	global_load_lds_dwordx4 v[96:97], off
	v_lshl_add_u64 v[96:97], v[10:11], 0, s[16:17]
	s_mov_b32 m0, s54
	s_nop 0
	global_load_lds_dwordx4 v[96:97], off
	v_lshl_add_u64 v[96:97], v[12:13], 0, s[16:17]
	s_mov_b32 m0, s55
	s_nop 0
	global_load_lds_dwordx4 v[96:97], off
	v_lshl_add_u64 v[96:97], v[14:15], 0, s[16:17]
	s_mov_b32 m0, s56
	s_nop 0
	global_load_lds_dwordx4 v[96:97], off
	v_lshl_add_u64 v[96:97], v[16:17], 0, s[16:17]
	s_mov_b32 m0, s57
	s_nop 0
	global_load_lds_dwordx4 v[96:97], off
	ds_read_b128 v[186:189], v18 offset:32768
	ds_read_b128 v[190:193], v18 offset:34816
	ds_read_b128 v[194:197], v18 offset:36864
	ds_read_b128 v[202:205], v18 offset:38912
	ds_read_b128 v[198:201], v32
	ds_read_b128 v[206:209], v33
	ds_read_b128 v[210:213], v34
	ds_read_b128 v[218:221], v35
	s_waitcnt lgkmcnt(0)
	v_mfma_f32_16x16x32_bf16 v[138:141], v[186:189], v[198:201], v[138:141]
	v_mfma_f32_16x16x32_bf16 v[142:145], v[190:193], v[198:201], v[142:145]
	v_mfma_f32_16x16x32_bf16 v[146:149], v[194:197], v[198:201], v[146:149]
	v_mfma_f32_16x16x32_bf16 v[134:137], v[202:205], v[198:201], v[134:137]
	ds_read_b128 v[198:201], v22
	v_mfma_f32_16x16x32_bf16 v[154:157], v[186:189], v[206:209], v[154:157]
	v_mfma_f32_16x16x32_bf16 v[158:161], v[190:193], v[206:209], v[158:161]
	v_mfma_f32_16x16x32_bf16 v[162:165], v[194:197], v[206:209], v[162:165]
	v_mfma_f32_16x16x32_bf16 v[150:153], v[202:205], v[206:209], v[150:153]
	ds_read_b128 v[206:209], v21
	v_mfma_f32_16x16x32_bf16 v[170:173], v[186:189], v[210:213], v[170:173]
	v_mfma_f32_16x16x32_bf16 v[174:177], v[190:193], v[210:213], v[174:177]
	v_mfma_f32_16x16x32_bf16 v[178:181], v[194:197], v[210:213], v[178:181]
	v_mfma_f32_16x16x32_bf16 v[166:169], v[202:205], v[210:213], v[166:169]
	ds_read_b128 v[210:213], v20
	v_mfma_f32_16x16x32_bf16 v[214:217], v[186:189], v[218:221], v[214:217]
	v_mfma_f32_16x16x32_bf16 v[56:59], v[190:193], v[218:221], v[56:59]
	v_mfma_f32_16x16x32_bf16 v[64:67], v[194:197], v[218:221], v[64:67]
	v_mfma_f32_16x16x32_bf16 v[72:75], v[202:205], v[218:221], v[72:75]
	ds_read_b128 v[218:221], v19
	s_waitcnt lgkmcnt(0)
	v_mfma_f32_16x16x32_bf16 v[116:119], v[186:189], v[198:201], v[116:119]
	v_mfma_f32_16x16x32_bf16 v[120:123], v[190:193], v[198:201], v[120:123]
	v_mfma_f32_16x16x32_bf16 v[124:127], v[194:197], v[198:201], v[124:127]
	v_mfma_f32_16x16x32_bf16 v[112:115], v[202:205], v[198:201], v[112:115]
	v_mfma_f32_16x16x32_bf16 v[92:95], v[186:189], v[206:209], v[92:95]
	v_mfma_f32_16x16x32_bf16 v[100:103], v[190:193], v[206:209], v[100:103]
	v_mfma_f32_16x16x32_bf16 v[104:107], v[194:197], v[206:209], v[104:107]
	v_mfma_f32_16x16x32_bf16 v[108:111], v[202:205], v[206:209], v[108:111]
	v_mfma_f32_16x16x32_bf16 v[76:79], v[186:189], v[210:213], v[76:79]
	v_mfma_f32_16x16x32_bf16 v[80:83], v[190:193], v[210:213], v[80:83]
	v_mfma_f32_16x16x32_bf16 v[84:87], v[194:197], v[210:213], v[84:87]
	v_mfma_f32_16x16x32_bf16 v[88:91], v[202:205], v[210:213], v[88:91]
	v_mfma_f32_16x16x32_bf16 v[52:55], v[186:189], v[218:221], v[52:55]
	v_mfma_f32_16x16x32_bf16 v[60:63], v[190:193], v[218:221], v[60:63]
	v_mfma_f32_16x16x32_bf16 v[68:71], v[194:197], v[218:221], v[68:71]
	v_mfma_f32_16x16x32_bf16 v[182:185], v[202:205], v[218:221], v[182:185]
	ds_read_b128 v[186:189], v18 offset:33792
	ds_read_b128 v[190:193], v18 offset:35840
	ds_read_b128 v[194:197], v18 offset:37888
	ds_read_b128 v[202:205], v18 offset:39936
	ds_read_b128 v[198:201], v32 offset:1024
	ds_read_b128 v[206:209], v33 offset:1024
	ds_read_b128 v[210:213], v34 offset:1024
	ds_read_b128 v[218:221], v35 offset:1024
	s_waitcnt lgkmcnt(0)
	v_mfma_f32_16x16x32_bf16 v[138:141], v[186:189], v[198:201], v[138:141]
	v_mfma_f32_16x16x32_bf16 v[142:145], v[190:193], v[198:201], v[142:145]
	v_mfma_f32_16x16x32_bf16 v[146:149], v[194:197], v[198:201], v[146:149]
	v_mfma_f32_16x16x32_bf16 v[134:137], v[202:205], v[198:201], v[134:137]
	ds_read_b128 v[198:201], v22 offset:1024
	v_mfma_f32_16x16x32_bf16 v[154:157], v[186:189], v[206:209], v[154:157]
	v_mfma_f32_16x16x32_bf16 v[158:161], v[190:193], v[206:209], v[158:161]
	v_mfma_f32_16x16x32_bf16 v[162:165], v[194:197], v[206:209], v[162:165]
	v_mfma_f32_16x16x32_bf16 v[150:153], v[202:205], v[206:209], v[150:153]
	ds_read_b128 v[206:209], v21 offset:1024
	v_mfma_f32_16x16x32_bf16 v[170:173], v[186:189], v[210:213], v[170:173]
	v_mfma_f32_16x16x32_bf16 v[174:177], v[190:193], v[210:213], v[174:177]
	v_mfma_f32_16x16x32_bf16 v[178:181], v[194:197], v[210:213], v[178:181]
	v_mfma_f32_16x16x32_bf16 v[166:169], v[202:205], v[210:213], v[166:169]
	ds_read_b128 v[210:213], v20 offset:1024
	v_mfma_f32_16x16x32_bf16 v[214:217], v[186:189], v[218:221], v[214:217]
	v_mfma_f32_16x16x32_bf16 v[56:59], v[190:193], v[218:221], v[56:59]
	v_mfma_f32_16x16x32_bf16 v[64:67], v[194:197], v[218:221], v[64:67]
	v_mfma_f32_16x16x32_bf16 v[72:75], v[202:205], v[218:221], v[72:75]
	ds_read_b128 v[218:221], v19 offset:1024
	s_waitcnt lgkmcnt(0)
	v_mfma_f32_16x16x32_bf16 v[116:119], v[186:189], v[198:201], v[116:119]
	v_mfma_f32_16x16x32_bf16 v[120:123], v[190:193], v[198:201], v[120:123]
	v_mfma_f32_16x16x32_bf16 v[124:127], v[194:197], v[198:201], v[124:127]
	v_mfma_f32_16x16x32_bf16 v[112:115], v[202:205], v[198:201], v[112:115]
	v_mfma_f32_16x16x32_bf16 v[92:95], v[186:189], v[206:209], v[92:95]
	v_mfma_f32_16x16x32_bf16 v[100:103], v[190:193], v[206:209], v[100:103]
	v_mfma_f32_16x16x32_bf16 v[104:107], v[194:197], v[206:209], v[104:107]
	v_mfma_f32_16x16x32_bf16 v[108:111], v[202:205], v[206:209], v[108:111]
	v_mfma_f32_16x16x32_bf16 v[76:79], v[186:189], v[210:213], v[76:79]
	v_mfma_f32_16x16x32_bf16 v[80:83], v[190:193], v[210:213], v[80:83]
	v_mfma_f32_16x16x32_bf16 v[84:87], v[194:197], v[210:213], v[84:87]
	v_mfma_f32_16x16x32_bf16 v[88:91], v[202:205], v[210:213], v[88:91]
	v_mfma_f32_16x16x32_bf16 v[52:55], v[186:189], v[218:221], v[52:55]
	v_mfma_f32_16x16x32_bf16 v[60:63], v[190:193], v[218:221], v[60:63]
	v_mfma_f32_16x16x32_bf16 v[68:71], v[194:197], v[218:221], v[68:71]
	v_mfma_f32_16x16x32_bf16 v[182:185], v[202:205], v[218:221], v[182:185]
	v_readfirstlane_b32 s56, v45
	v_lshl_add_u64 v[96:97], v[2:3], 0, s[18:19]
	s_mov_b32 m0, s56
	v_readfirstlane_b32 s0, v44
	s_waitcnt vmcnt(0)
	s_waitcnt vmcnt(0)
	s_barrier
	global_load_lds_dwordx4 v[96:97], off
	v_lshl_add_u64 v[96:97], v[4:5], 0, s[18:19]
	s_mov_b32 m0, s0
	v_readfirstlane_b32 s42, v46
	global_load_lds_dwordx4 v[96:97], off
	v_lshl_add_u64 v[44:45], v[6:7], 0, s[18:19]
	s_mov_b32 m0, s42
	v_readfirstlane_b32 s43, v47
	global_load_lds_dwordx4 v[44:45], off
	v_lshl_add_u64 v[44:45], v[8:9], 0, s[18:19]
	s_mov_b32 m0, s43
	v_readfirstlane_b32 s53, v48
	global_load_lds_dwordx4 v[44:45], off
	v_lshl_add_u64 v[44:45], v[10:11], 0, s[18:19]
	s_mov_b32 m0, s53
	v_readfirstlane_b32 s54, v49
	global_load_lds_dwordx4 v[44:45], off
	v_lshl_add_u64 v[44:45], v[12:13], 0, s[18:19]
	s_mov_b32 m0, s54
	v_readfirstlane_b32 s55, v50
	global_load_lds_dwordx4 v[44:45], off
	v_lshl_add_u64 v[44:45], v[14:15], 0, s[18:19]
	s_mov_b32 m0, s55
	v_readfirstlane_b32 s57, v51
	global_load_lds_dwordx4 v[44:45], off
	v_lshl_add_u64 v[44:45], v[16:17], 0, s[18:19]
	s_mov_b32 m0, s57
	s_nop 0
	global_load_lds_dwordx4 v[44:45], off
	ds_read_b128 v[44:47], v23
	ds_read_b128 v[48:51], v23 offset:2048
	ds_read_b128 v[186:189], v23 offset:4096
	ds_read_b128 v[194:197], v23 offset:6144
	ds_read_b128 v[190:193], v24
	ds_read_b128 v[198:201], v25
	ds_read_b128 v[202:205], v26
	ds_read_b128 v[206:209], v27
	s_waitcnt lgkmcnt(0)
	v_mfma_f32_16x16x32_bf16 v[138:141], v[44:47], v[190:193], v[138:141]
	v_mfma_f32_16x16x32_bf16 v[142:145], v[48:51], v[190:193], v[142:145]
	v_mfma_f32_16x16x32_bf16 v[146:149], v[186:189], v[190:193], v[146:149]
	v_mfma_f32_16x16x32_bf16 v[134:137], v[194:197], v[190:193], v[134:137]
	ds_read_b128 v[190:193], v28
	v_mfma_f32_16x16x32_bf16 v[154:157], v[44:47], v[198:201], v[154:157]
	v_mfma_f32_16x16x32_bf16 v[158:161], v[48:51], v[198:201], v[158:161]
	v_mfma_f32_16x16x32_bf16 v[162:165], v[186:189], v[198:201], v[162:165]
	v_mfma_f32_16x16x32_bf16 v[150:153], v[194:197], v[198:201], v[150:153]
	ds_read_b128 v[198:201], v29
	v_mfma_f32_16x16x32_bf16 v[170:173], v[44:47], v[202:205], v[170:173]
	v_mfma_f32_16x16x32_bf16 v[174:177], v[48:51], v[202:205], v[174:177]
	v_mfma_f32_16x16x32_bf16 v[178:181], v[186:189], v[202:205], v[178:181]
	v_mfma_f32_16x16x32_bf16 v[166:169], v[194:197], v[202:205], v[166:169]
	ds_read_b128 v[202:205], v30
	v_mfma_f32_16x16x32_bf16 v[210:213], v[44:47], v[206:209], v[214:217]
	v_mfma_f32_16x16x32_bf16 v[56:59], v[48:51], v[206:209], v[56:59]
	v_mfma_f32_16x16x32_bf16 v[64:67], v[186:189], v[206:209], v[64:67]
	v_mfma_f32_16x16x32_bf16 v[72:75], v[194:197], v[206:209], v[72:75]
	ds_read_b128 v[206:209], v31
	s_waitcnt lgkmcnt(0)
	v_mfma_f32_16x16x32_bf16 v[116:119], v[44:47], v[190:193], v[116:119]
	v_mfma_f32_16x16x32_bf16 v[120:123], v[48:51], v[190:193], v[120:123]
	v_mfma_f32_16x16x32_bf16 v[124:127], v[186:189], v[190:193], v[124:127]
	v_mfma_f32_16x16x32_bf16 v[112:115], v[194:197], v[190:193], v[112:115]
	v_mfma_f32_16x16x32_bf16 v[92:95], v[44:47], v[198:201], v[92:95]
	v_mfma_f32_16x16x32_bf16 v[100:103], v[48:51], v[198:201], v[100:103]
	v_mfma_f32_16x16x32_bf16 v[104:107], v[186:189], v[198:201], v[104:107]
	v_mfma_f32_16x16x32_bf16 v[108:111], v[194:197], v[198:201], v[108:111]
	v_mfma_f32_16x16x32_bf16 v[76:79], v[44:47], v[202:205], v[76:79]
	v_mfma_f32_16x16x32_bf16 v[80:83], v[48:51], v[202:205], v[80:83]
	v_mfma_f32_16x16x32_bf16 v[84:87], v[186:189], v[202:205], v[84:87]
	v_mfma_f32_16x16x32_bf16 v[88:91], v[194:197], v[202:205], v[88:91]
	v_mfma_f32_16x16x32_bf16 v[44:47], v[44:47], v[206:209], v[52:55]
	v_mfma_f32_16x16x32_bf16 v[48:51], v[48:51], v[206:209], v[60:63]
	v_mfma_f32_16x16x32_bf16 v[52:55], v[186:189], v[206:209], v[68:71]
	v_mfma_f32_16x16x32_bf16 v[60:63], v[194:197], v[206:209], v[182:185]
	s_nop 1
	ds_read_b128 v[68:71], v23 offset:1024
	ds_read_b128 v[182:185], v23 offset:3072
	ds_read_b128 v[186:189], v23 offset:5120
	ds_read_b128 v[194:197], v23 offset:7168
	ds_read_b128 v[190:193], v24 offset:1024
	ds_read_b128 v[198:201], v25 offset:1024
	ds_read_b128 v[202:205], v26 offset:1024
	ds_read_b128 v[206:209], v27 offset:1024
	s_waitcnt lgkmcnt(0)
	v_mfma_f32_16x16x32_bf16 v[138:141], v[68:71], v[190:193], v[138:141]
	v_mfma_f32_16x16x32_bf16 v[142:145], v[182:185], v[190:193], v[142:145]
	v_mfma_f32_16x16x32_bf16 v[146:149], v[186:189], v[190:193], v[146:149]
	v_mfma_f32_16x16x32_bf16 v[134:137], v[194:197], v[190:193], v[134:137]
	ds_read_b128 v[190:193], v28 offset:1024
	v_mfma_f32_16x16x32_bf16 v[154:157], v[68:71], v[198:201], v[154:157]
	v_mfma_f32_16x16x32_bf16 v[158:161], v[182:185], v[198:201], v[158:161]
	v_mfma_f32_16x16x32_bf16 v[162:165], v[186:189], v[198:201], v[162:165]
	v_mfma_f32_16x16x32_bf16 v[150:153], v[194:197], v[198:201], v[150:153]
	ds_read_b128 v[198:201], v29 offset:1024
	v_mfma_f32_16x16x32_bf16 v[170:173], v[68:71], v[202:205], v[170:173]
	v_mfma_f32_16x16x32_bf16 v[174:177], v[182:185], v[202:205], v[174:177]
	v_mfma_f32_16x16x32_bf16 v[178:181], v[186:189], v[202:205], v[178:181]
	v_mfma_f32_16x16x32_bf16 v[166:169], v[194:197], v[202:205], v[166:169]
	ds_read_b128 v[202:205], v30 offset:1024
	v_mfma_f32_16x16x32_bf16 v[210:213], v[68:71], v[206:209], v[210:213]
	v_mfma_f32_16x16x32_bf16 v[56:59], v[182:185], v[206:209], v[56:59]
	v_mfma_f32_16x16x32_bf16 v[64:67], v[186:189], v[206:209], v[64:67]
	v_mfma_f32_16x16x32_bf16 v[72:75], v[194:197], v[206:209], v[72:75]
	ds_read_b128 v[206:209], v31 offset:1024
	s_waitcnt lgkmcnt(0)
	v_mfma_f32_16x16x32_bf16 v[116:119], v[68:71], v[190:193], v[116:119]
	v_mfma_f32_16x16x32_bf16 v[120:123], v[182:185], v[190:193], v[120:123]
	v_mfma_f32_16x16x32_bf16 v[124:127], v[186:189], v[190:193], v[124:127]
	v_mfma_f32_16x16x32_bf16 v[112:115], v[194:197], v[190:193], v[112:115]
	v_mfma_f32_16x16x32_bf16 v[92:95], v[68:71], v[198:201], v[92:95]
	v_mfma_f32_16x16x32_bf16 v[100:103], v[182:185], v[198:201], v[100:103]
	v_mfma_f32_16x16x32_bf16 v[104:107], v[186:189], v[198:201], v[104:107]
	v_mfma_f32_16x16x32_bf16 v[108:111], v[194:197], v[198:201], v[108:111]
	v_mfma_f32_16x16x32_bf16 v[76:79], v[68:71], v[202:205], v[76:79]
	v_mfma_f32_16x16x32_bf16 v[80:83], v[182:185], v[202:205], v[80:83]
	v_mfma_f32_16x16x32_bf16 v[84:87], v[186:189], v[202:205], v[84:87]
	v_mfma_f32_16x16x32_bf16 v[88:91], v[194:197], v[202:205], v[88:91]
	v_mfma_f32_16x16x32_bf16 v[44:47], v[68:71], v[206:209], v[44:47]
	v_mfma_f32_16x16x32_bf16 v[48:51], v[182:185], v[206:209], v[48:51]
	v_mfma_f32_16x16x32_bf16 v[52:55], v[186:189], v[206:209], v[52:55]
	v_mfma_f32_16x16x32_bf16 v[60:63], v[194:197], v[206:209], v[60:63]
	v_readfirstlane_b32 s64, v37
	v_lshl_add_u64 v[68:69], v[2:3], 0, s[20:21]
	s_mov_b32 m0, s64
	v_readfirstlane_b32 s58, v36
	s_waitcnt vmcnt(0)
	s_waitcnt vmcnt(0)
	s_barrier
	global_load_lds_dwordx4 v[68:69], off
	v_lshl_add_u64 v[68:69], v[4:5], 0, s[20:21]
	s_mov_b32 m0, s58
	v_readfirstlane_b32 s59, v38
	global_load_lds_dwordx4 v[68:69], off
	v_lshl_add_u64 v[36:37], v[6:7], 0, s[20:21]
	s_mov_b32 m0, s59
	v_readfirstlane_b32 s60, v39
	global_load_lds_dwordx4 v[36:37], off
	v_lshl_add_u64 v[36:37], v[8:9], 0, s[20:21]
	s_mov_b32 m0, s60
	v_readfirstlane_b32 s61, v40
	global_load_lds_dwordx4 v[36:37], off
	v_lshl_add_u64 v[36:37], v[10:11], 0, s[20:21]
	s_mov_b32 m0, s61
	v_readfirstlane_b32 s62, v41
	global_load_lds_dwordx4 v[36:37], off
	v_lshl_add_u64 v[36:37], v[12:13], 0, s[20:21]
	s_mov_b32 m0, s62
	v_readfirstlane_b32 s63, v42
	global_load_lds_dwordx4 v[36:37], off
	v_lshl_add_u64 v[36:37], v[14:15], 0, s[20:21]
	s_mov_b32 m0, s63
	v_readfirstlane_b32 s65, v43
	global_load_lds_dwordx4 v[36:37], off
	v_lshl_add_u64 v[36:37], v[16:17], 0, s[20:21]
	s_mov_b32 m0, s65
	s_nop 0
	global_load_lds_dwordx4 v[36:37], off
	ds_read_b128 v[36:39], v18 offset:32768
	ds_read_b128 v[40:43], v18 offset:34816
	ds_read_b128 v[68:71], v18 offset:36864
	ds_read_b128 v[186:189], v18 offset:38912
	ds_read_b128 v[182:185], v32
	ds_read_b128 v[190:193], v33
	ds_read_b128 v[194:197], v34
	ds_read_b128 v[198:201], v35
	s_waitcnt lgkmcnt(0)
	v_mfma_f32_16x16x32_bf16 v[138:141], v[36:39], v[182:185], v[138:141]
	v_mfma_f32_16x16x32_bf16 v[142:145], v[40:43], v[182:185], v[142:145]
	v_mfma_f32_16x16x32_bf16 v[146:149], v[68:71], v[182:185], v[146:149]
	v_mfma_f32_16x16x32_bf16 v[134:137], v[186:189], v[182:185], v[134:137]
	ds_read_b128 v[182:185], v22
	v_mfma_f32_16x16x32_bf16 v[154:157], v[36:39], v[190:193], v[154:157]
	v_mfma_f32_16x16x32_bf16 v[158:161], v[40:43], v[190:193], v[158:161]
	v_mfma_f32_16x16x32_bf16 v[162:165], v[68:71], v[190:193], v[162:165]
	v_mfma_f32_16x16x32_bf16 v[150:153], v[186:189], v[190:193], v[150:153]
	ds_read_b128 v[190:193], v21
	v_mfma_f32_16x16x32_bf16 v[170:173], v[36:39], v[194:197], v[170:173]
	v_mfma_f32_16x16x32_bf16 v[174:177], v[40:43], v[194:197], v[174:177]
	v_mfma_f32_16x16x32_bf16 v[178:181], v[68:71], v[194:197], v[178:181]
	v_mfma_f32_16x16x32_bf16 v[166:169], v[186:189], v[194:197], v[166:169]
	ds_read_b128 v[194:197], v20
	v_mfma_f32_16x16x32_bf16 v[202:205], v[36:39], v[198:201], v[210:213]
	v_mfma_f32_16x16x32_bf16 v[56:59], v[40:43], v[198:201], v[56:59]
	v_mfma_f32_16x16x32_bf16 v[64:67], v[68:71], v[198:201], v[64:67]
	v_mfma_f32_16x16x32_bf16 v[72:75], v[186:189], v[198:201], v[72:75]
	ds_read_b128 v[198:201], v19
	s_waitcnt lgkmcnt(0)
	v_mfma_f32_16x16x32_bf16 v[116:119], v[36:39], v[182:185], v[116:119]
	v_mfma_f32_16x16x32_bf16 v[120:123], v[40:43], v[182:185], v[120:123]
	v_mfma_f32_16x16x32_bf16 v[124:127], v[68:71], v[182:185], v[124:127]
	v_mfma_f32_16x16x32_bf16 v[112:115], v[186:189], v[182:185], v[112:115]
	v_mfma_f32_16x16x32_bf16 v[92:95], v[36:39], v[190:193], v[92:95]
	v_mfma_f32_16x16x32_bf16 v[100:103], v[40:43], v[190:193], v[100:103]
	v_mfma_f32_16x16x32_bf16 v[104:107], v[68:71], v[190:193], v[104:107]
	v_mfma_f32_16x16x32_bf16 v[108:111], v[186:189], v[190:193], v[108:111]
	v_mfma_f32_16x16x32_bf16 v[76:79], v[36:39], v[194:197], v[76:79]
	v_mfma_f32_16x16x32_bf16 v[80:83], v[40:43], v[194:197], v[80:83]
	v_mfma_f32_16x16x32_bf16 v[84:87], v[68:71], v[194:197], v[84:87]
	v_mfma_f32_16x16x32_bf16 v[88:91], v[186:189], v[194:197], v[88:91]
	v_mfma_f32_16x16x32_bf16 v[36:39], v[36:39], v[198:201], v[44:47]
	v_mfma_f32_16x16x32_bf16 v[40:43], v[40:43], v[198:201], v[48:51]
	v_mfma_f32_16x16x32_bf16 v[44:47], v[68:71], v[198:201], v[52:55]
	v_mfma_f32_16x16x32_bf16 v[48:51], v[186:189], v[198:201], v[60:63]
	s_nop 1
	ds_read_b128 v[52:55], v18 offset:33792
	ds_read_b128 v[60:63], v18 offset:35840
	ds_read_b128 v[68:71], v18 offset:37888
	ds_read_b128 v[186:189], v18 offset:39936
	ds_read_b128 v[182:185], v32 offset:1024
	ds_read_b128 v[190:193], v33 offset:1024
	ds_read_b128 v[194:197], v34 offset:1024
	ds_read_b128 v[198:201], v35 offset:1024
	s_waitcnt lgkmcnt(0)
	v_mfma_f32_16x16x32_bf16 v[138:141], v[52:55], v[182:185], v[138:141]
	v_mfma_f32_16x16x32_bf16 v[142:145], v[60:63], v[182:185], v[142:145]
	v_mfma_f32_16x16x32_bf16 v[146:149], v[68:71], v[182:185], v[146:149]
	v_mfma_f32_16x16x32_bf16 v[134:137], v[186:189], v[182:185], v[134:137]
	ds_read_b128 v[182:185], v22 offset:1024
	v_mfma_f32_16x16x32_bf16 v[154:157], v[52:55], v[190:193], v[154:157]
	v_mfma_f32_16x16x32_bf16 v[158:161], v[60:63], v[190:193], v[158:161]
	v_mfma_f32_16x16x32_bf16 v[162:165], v[68:71], v[190:193], v[162:165]
	v_mfma_f32_16x16x32_bf16 v[150:153], v[186:189], v[190:193], v[150:153]
	ds_read_b128 v[190:193], v21 offset:1024
	v_mfma_f32_16x16x32_bf16 v[170:173], v[52:55], v[194:197], v[170:173]
	v_mfma_f32_16x16x32_bf16 v[174:177], v[60:63], v[194:197], v[174:177]
	v_mfma_f32_16x16x32_bf16 v[178:181], v[68:71], v[194:197], v[178:181]
	v_mfma_f32_16x16x32_bf16 v[166:169], v[186:189], v[194:197], v[166:169]
	ds_read_b128 v[194:197], v20 offset:1024
	v_mfma_f32_16x16x32_bf16 v[202:205], v[52:55], v[198:201], v[202:205]
	v_mfma_f32_16x16x32_bf16 v[56:59], v[60:63], v[198:201], v[56:59]
	v_mfma_f32_16x16x32_bf16 v[64:67], v[68:71], v[198:201], v[64:67]
	v_mfma_f32_16x16x32_bf16 v[72:75], v[186:189], v[198:201], v[72:75]
	ds_read_b128 v[198:201], v19 offset:1024
	s_waitcnt lgkmcnt(0)
	v_mfma_f32_16x16x32_bf16 v[116:119], v[52:55], v[182:185], v[116:119]
	v_mfma_f32_16x16x32_bf16 v[120:123], v[60:63], v[182:185], v[120:123]
	v_mfma_f32_16x16x32_bf16 v[124:127], v[68:71], v[182:185], v[124:127]
	v_mfma_f32_16x16x32_bf16 v[112:115], v[186:189], v[182:185], v[112:115]
	v_mfma_f32_16x16x32_bf16 v[92:95], v[52:55], v[190:193], v[92:95]
	v_mfma_f32_16x16x32_bf16 v[100:103], v[60:63], v[190:193], v[100:103]
	v_mfma_f32_16x16x32_bf16 v[104:107], v[68:71], v[190:193], v[104:107]
	v_mfma_f32_16x16x32_bf16 v[108:111], v[186:189], v[190:193], v[108:111]
	v_mfma_f32_16x16x32_bf16 v[76:79], v[52:55], v[194:197], v[76:79]
	v_mfma_f32_16x16x32_bf16 v[80:83], v[60:63], v[194:197], v[80:83]
	v_mfma_f32_16x16x32_bf16 v[84:87], v[68:71], v[194:197], v[84:87]
	v_mfma_f32_16x16x32_bf16 v[88:91], v[186:189], v[194:197], v[88:91]
	v_mfma_f32_16x16x32_bf16 v[36:39], v[52:55], v[198:201], v[36:39]
	v_mfma_f32_16x16x32_bf16 v[40:43], v[60:63], v[198:201], v[40:43]
	v_mfma_f32_16x16x32_bf16 v[44:47], v[68:71], v[198:201], v[44:47]
	v_mfma_f32_16x16x32_bf16 v[48:51], v[186:189], v[198:201], v[48:51]
	s_mov_b32 m0, s56
	v_lshl_add_u64 v[52:53], v[2:3], 0, s[22:23]
	s_waitcnt vmcnt(0)
	s_waitcnt vmcnt(0)
	s_barrier
	global_load_lds_dwordx4 v[52:53], off
	v_lshl_add_u64 v[52:53], v[4:5], 0, s[22:23]
	s_mov_b32 m0, s0
	s_nop 0
	global_load_lds_dwordx4 v[52:53], off
	v_lshl_add_u64 v[52:53], v[6:7], 0, s[22:23]
	s_mov_b32 m0, s42
	s_nop 0
	global_load_lds_dwordx4 v[52:53], off
	v_lshl_add_u64 v[52:53], v[8:9], 0, s[22:23]
	s_mov_b32 m0, s43
	s_nop 0
	global_load_lds_dwordx4 v[52:53], off
	v_lshl_add_u64 v[52:53], v[10:11], 0, s[22:23]
	s_mov_b32 m0, s53
	s_nop 0
	global_load_lds_dwordx4 v[52:53], off
	v_lshl_add_u64 v[52:53], v[12:13], 0, s[22:23]
	s_mov_b32 m0, s54
	s_nop 0
	global_load_lds_dwordx4 v[52:53], off
	v_lshl_add_u64 v[52:53], v[14:15], 0, s[22:23]
	s_mov_b32 m0, s55
	s_nop 0
	global_load_lds_dwordx4 v[52:53], off
	v_lshl_add_u64 v[52:53], v[16:17], 0, s[22:23]
	s_mov_b32 m0, s57
	s_nop 0
	global_load_lds_dwordx4 v[52:53], off
	ds_read_b128 v[52:55], v23
	ds_read_b128 v[60:63], v23 offset:2048
	ds_read_b128 v[68:71], v23 offset:4096
	ds_read_b128 v[186:189], v23 offset:6144
	ds_read_b128 v[182:185], v24
	ds_read_b128 v[190:193], v25
	ds_read_b128 v[194:197], v26
	ds_read_b128 v[198:201], v27
	s_waitcnt lgkmcnt(0)
	v_mfma_f32_16x16x32_bf16 v[138:141], v[52:55], v[182:185], v[138:141]
	v_mfma_f32_16x16x32_bf16 v[142:145], v[60:63], v[182:185], v[142:145]
	v_mfma_f32_16x16x32_bf16 v[146:149], v[68:71], v[182:185], v[146:149]
	v_mfma_f32_16x16x32_bf16 v[134:137], v[186:189], v[182:185], v[134:137]
	ds_read_b128 v[182:185], v28
	v_mfma_f32_16x16x32_bf16 v[154:157], v[52:55], v[190:193], v[154:157]
	v_mfma_f32_16x16x32_bf16 v[158:161], v[60:63], v[190:193], v[158:161]
	v_mfma_f32_16x16x32_bf16 v[162:165], v[68:71], v[190:193], v[162:165]
	v_mfma_f32_16x16x32_bf16 v[150:153], v[186:189], v[190:193], v[150:153]
	ds_read_b128 v[190:193], v29
	v_mfma_f32_16x16x32_bf16 v[170:173], v[52:55], v[194:197], v[170:173]
	v_mfma_f32_16x16x32_bf16 v[174:177], v[60:63], v[194:197], v[174:177]
	v_mfma_f32_16x16x32_bf16 v[178:181], v[68:71], v[194:197], v[178:181]
	v_mfma_f32_16x16x32_bf16 v[166:169], v[186:189], v[194:197], v[166:169]
	ds_read_b128 v[194:197], v30
	v_mfma_f32_16x16x32_bf16 v[202:205], v[52:55], v[198:201], v[202:205]
	v_mfma_f32_16x16x32_bf16 v[56:59], v[60:63], v[198:201], v[56:59]
	v_mfma_f32_16x16x32_bf16 v[64:67], v[68:71], v[198:201], v[64:67]
	v_mfma_f32_16x16x32_bf16 v[72:75], v[186:189], v[198:201], v[72:75]
	ds_read_b128 v[198:201], v31
	s_waitcnt lgkmcnt(0)
	v_mfma_f32_16x16x32_bf16 v[116:119], v[52:55], v[182:185], v[116:119]
	v_mfma_f32_16x16x32_bf16 v[120:123], v[60:63], v[182:185], v[120:123]
	v_mfma_f32_16x16x32_bf16 v[124:127], v[68:71], v[182:185], v[124:127]
	v_mfma_f32_16x16x32_bf16 v[112:115], v[186:189], v[182:185], v[112:115]
	v_mfma_f32_16x16x32_bf16 v[92:95], v[52:55], v[190:193], v[92:95]
	v_mfma_f32_16x16x32_bf16 v[100:103], v[60:63], v[190:193], v[100:103]
	v_mfma_f32_16x16x32_bf16 v[104:107], v[68:71], v[190:193], v[104:107]
	v_mfma_f32_16x16x32_bf16 v[108:111], v[186:189], v[190:193], v[108:111]
	v_mfma_f32_16x16x32_bf16 v[76:79], v[52:55], v[194:197], v[76:79]
	v_mfma_f32_16x16x32_bf16 v[80:83], v[60:63], v[194:197], v[80:83]
	v_mfma_f32_16x16x32_bf16 v[84:87], v[68:71], v[194:197], v[84:87]
	v_mfma_f32_16x16x32_bf16 v[88:91], v[186:189], v[194:197], v[88:91]
	v_mfma_f32_16x16x32_bf16 v[36:39], v[52:55], v[198:201], v[36:39]
	v_mfma_f32_16x16x32_bf16 v[40:43], v[60:63], v[198:201], v[40:43]
	v_mfma_f32_16x16x32_bf16 v[44:47], v[68:71], v[198:201], v[44:47]
	v_mfma_f32_16x16x32_bf16 v[48:51], v[186:189], v[198:201], v[48:51]
	ds_read_b128 v[52:55], v23 offset:1024
	ds_read_b128 v[60:63], v23 offset:3072
	ds_read_b128 v[68:71], v23 offset:5120
	ds_read_b128 v[186:189], v23 offset:7168
	ds_read_b128 v[182:185], v24 offset:1024
	ds_read_b128 v[190:193], v25 offset:1024
	ds_read_b128 v[194:197], v26 offset:1024
	ds_read_b128 v[198:201], v27 offset:1024
	s_waitcnt lgkmcnt(0)
	v_mfma_f32_16x16x32_bf16 v[138:141], v[52:55], v[182:185], v[138:141]
	v_mfma_f32_16x16x32_bf16 v[142:145], v[60:63], v[182:185], v[142:145]
	v_mfma_f32_16x16x32_bf16 v[146:149], v[68:71], v[182:185], v[146:149]
	v_mfma_f32_16x16x32_bf16 v[134:137], v[186:189], v[182:185], v[134:137]
	ds_read_b128 v[182:185], v28 offset:1024
	v_mfma_f32_16x16x32_bf16 v[154:157], v[52:55], v[190:193], v[154:157]
	v_mfma_f32_16x16x32_bf16 v[158:161], v[60:63], v[190:193], v[158:161]
	v_mfma_f32_16x16x32_bf16 v[162:165], v[68:71], v[190:193], v[162:165]
	v_mfma_f32_16x16x32_bf16 v[150:153], v[186:189], v[190:193], v[150:153]
	ds_read_b128 v[190:193], v29 offset:1024
	v_mfma_f32_16x16x32_bf16 v[170:173], v[52:55], v[194:197], v[170:173]
	v_mfma_f32_16x16x32_bf16 v[174:177], v[60:63], v[194:197], v[174:177]
	v_mfma_f32_16x16x32_bf16 v[178:181], v[68:71], v[194:197], v[178:181]
	v_mfma_f32_16x16x32_bf16 v[166:169], v[186:189], v[194:197], v[166:169]
	ds_read_b128 v[194:197], v30 offset:1024
	v_mfma_f32_16x16x32_bf16 v[202:205], v[52:55], v[198:201], v[202:205]
	v_mfma_f32_16x16x32_bf16 v[56:59], v[60:63], v[198:201], v[56:59]
	v_mfma_f32_16x16x32_bf16 v[64:67], v[68:71], v[198:201], v[64:67]
	v_mfma_f32_16x16x32_bf16 v[72:75], v[186:189], v[198:201], v[72:75]
	ds_read_b128 v[198:201], v31 offset:1024
	s_waitcnt lgkmcnt(0)
	v_mfma_f32_16x16x32_bf16 v[116:119], v[52:55], v[182:185], v[116:119]
	v_mfma_f32_16x16x32_bf16 v[120:123], v[60:63], v[182:185], v[120:123]
	v_mfma_f32_16x16x32_bf16 v[124:127], v[68:71], v[182:185], v[124:127]
	v_mfma_f32_16x16x32_bf16 v[112:115], v[186:189], v[182:185], v[112:115]
	v_mfma_f32_16x16x32_bf16 v[92:95], v[52:55], v[190:193], v[92:95]
	v_mfma_f32_16x16x32_bf16 v[100:103], v[60:63], v[190:193], v[100:103]
	v_mfma_f32_16x16x32_bf16 v[104:107], v[68:71], v[190:193], v[104:107]
	v_mfma_f32_16x16x32_bf16 v[108:111], v[186:189], v[190:193], v[108:111]
	v_mfma_f32_16x16x32_bf16 v[76:79], v[52:55], v[194:197], v[76:79]
	v_mfma_f32_16x16x32_bf16 v[80:83], v[60:63], v[194:197], v[80:83]
	v_mfma_f32_16x16x32_bf16 v[84:87], v[68:71], v[194:197], v[84:87]
	v_mfma_f32_16x16x32_bf16 v[88:91], v[186:189], v[194:197], v[88:91]
	v_mfma_f32_16x16x32_bf16 v[36:39], v[52:55], v[198:201], v[36:39]
	v_mfma_f32_16x16x32_bf16 v[40:43], v[60:63], v[198:201], v[40:43]
	v_mfma_f32_16x16x32_bf16 v[44:47], v[68:71], v[198:201], v[44:47]
	v_mfma_f32_16x16x32_bf16 v[48:51], v[186:189], v[198:201], v[48:51]
	s_mov_b32 m0, s64
	v_lshl_add_u64 v[2:3], v[2:3], 0, s[24:25]
	s_waitcnt vmcnt(0)
	s_waitcnt vmcnt(0)
	s_barrier
	global_load_lds_dwordx4 v[2:3], off
	v_lshl_add_u64 v[2:3], v[4:5], 0, s[24:25]
	s_mov_b32 m0, s58
	s_nop 0
	global_load_lds_dwordx4 v[2:3], off
	v_lshl_add_u64 v[2:3], v[6:7], 0, s[24:25]
	s_mov_b32 m0, s59
	s_nop 0
	global_load_lds_dwordx4 v[2:3], off
	v_lshl_add_u64 v[2:3], v[8:9], 0, s[24:25]
	s_mov_b32 m0, s60
	s_nop 0
	global_load_lds_dwordx4 v[2:3], off
	v_lshl_add_u64 v[2:3], v[10:11], 0, s[24:25]
	s_mov_b32 m0, s61
	s_nop 0
	global_load_lds_dwordx4 v[2:3], off
	v_lshl_add_u64 v[2:3], v[12:13], 0, s[24:25]
	s_mov_b32 m0, s62
	s_nop 0
	global_load_lds_dwordx4 v[2:3], off
	v_lshl_add_u64 v[2:3], v[14:15], 0, s[24:25]
	s_mov_b32 m0, s63
	s_nop 0
	global_load_lds_dwordx4 v[2:3], off
	v_lshl_add_u64 v[2:3], v[16:17], 0, s[24:25]
	s_mov_b32 m0, s65
	s_nop 0
	global_load_lds_dwordx4 v[2:3], off
	ds_read_b128 v[2:5], v18 offset:32768
	ds_read_b128 v[6:9], v18 offset:34816
	ds_read_b128 v[10:13], v18 offset:36864
	ds_read_b128 v[52:55], v18 offset:38912
	ds_read_b128 v[14:17], v32
	ds_read_b128 v[60:63], v33
	ds_read_b128 v[68:71], v34
	ds_read_b128 v[182:185], v35
	s_waitcnt lgkmcnt(0)
	v_mfma_f32_16x16x32_bf16 v[138:141], v[2:5], v[14:17], v[138:141]
	v_mfma_f32_16x16x32_bf16 v[142:145], v[6:9], v[14:17], v[142:145]
	v_mfma_f32_16x16x32_bf16 v[146:149], v[10:13], v[14:17], v[146:149]
	v_mfma_f32_16x16x32_bf16 v[14:17], v[52:55], v[14:17], v[134:137]
	s_nop 2
	ds_read_b128 v[134:137], v22
	v_mfma_f32_16x16x32_bf16 v[154:157], v[2:5], v[60:63], v[154:157]
	v_mfma_f32_16x16x32_bf16 v[158:161], v[6:9], v[60:63], v[158:161]
	v_mfma_f32_16x16x32_bf16 v[162:165], v[10:13], v[60:63], v[162:165]
	v_mfma_f32_16x16x32_bf16 v[60:63], v[52:55], v[60:63], v[150:153]
	s_nop 2
	ds_read_b128 v[150:153], v21
	v_mfma_f32_16x16x32_bf16 v[170:173], v[2:5], v[68:71], v[170:173]
	v_mfma_f32_16x16x32_bf16 v[174:177], v[6:9], v[68:71], v[174:177]
	v_mfma_f32_16x16x32_bf16 v[178:181], v[10:13], v[68:71], v[178:181]
	v_mfma_f32_16x16x32_bf16 v[68:71], v[52:55], v[68:71], v[166:169]
	s_nop 2
	ds_read_b128 v[166:169], v20
	v_mfma_f32_16x16x32_bf16 v[186:189], v[2:5], v[182:185], v[202:205]
	v_mfma_f32_16x16x32_bf16 v[56:59], v[6:9], v[182:185], v[56:59]
	v_mfma_f32_16x16x32_bf16 v[64:67], v[10:13], v[182:185], v[64:67]
	v_mfma_f32_16x16x32_bf16 v[72:75], v[52:55], v[182:185], v[72:75]
	ds_read_b128 v[182:185], v19
	s_waitcnt lgkmcnt(0)
	v_mfma_f32_16x16x32_bf16 v[116:119], v[2:5], v[134:137], v[116:119]
	v_mfma_f32_16x16x32_bf16 v[120:123], v[6:9], v[134:137], v[120:123]
	v_mfma_f32_16x16x32_bf16 v[124:127], v[10:13], v[134:137], v[124:127]
	v_mfma_f32_16x16x32_bf16 v[112:115], v[52:55], v[134:137], v[112:115]
	v_mfma_f32_16x16x32_bf16 v[92:95], v[2:5], v[150:153], v[92:95]
	v_mfma_f32_16x16x32_bf16 v[100:103], v[6:9], v[150:153], v[100:103]
	v_mfma_f32_16x16x32_bf16 v[104:107], v[10:13], v[150:153], v[104:107]
	v_mfma_f32_16x16x32_bf16 v[108:111], v[52:55], v[150:153], v[108:111]
	v_mfma_f32_16x16x32_bf16 v[76:79], v[2:5], v[166:169], v[76:79]
	v_mfma_f32_16x16x32_bf16 v[80:83], v[6:9], v[166:169], v[80:83]
	v_mfma_f32_16x16x32_bf16 v[84:87], v[10:13], v[166:169], v[84:87]
	v_mfma_f32_16x16x32_bf16 v[88:91], v[52:55], v[166:169], v[88:91]
	v_mfma_f32_16x16x32_bf16 v[2:5], v[2:5], v[182:185], v[36:39]
	v_mfma_f32_16x16x32_bf16 v[6:9], v[6:9], v[182:185], v[40:43]
	v_mfma_f32_16x16x32_bf16 v[10:13], v[10:13], v[182:185], v[44:47]
	v_mfma_f32_16x16x32_bf16 v[36:39], v[52:55], v[182:185], v[48:51]
	s_nop 0
	ds_read_b128 v[40:43], v18 offset:33792
	ds_read_b128 v[44:47], v18 offset:35840
	ds_read_b128 v[48:51], v18 offset:37888
	ds_read_b128 v[134:137], v18 offset:39936
	ds_read_b128 v[52:55], v32 offset:1024
	ds_read_b128 v[150:153], v33 offset:1024
	ds_read_b128 v[166:169], v34 offset:1024
	ds_read_b128 v[32:35], v35 offset:1024
	s_waitcnt lgkmcnt(0)
	v_mfma_f32_16x16x32_bf16 v[138:141], v[40:43], v[52:55], v[138:141]
	v_mfma_f32_16x16x32_bf16 v[142:145], v[44:47], v[52:55], v[142:145]
	v_mfma_f32_16x16x32_bf16 v[146:149], v[48:51], v[52:55], v[146:149]
	v_mfma_f32_16x16x32_bf16 v[14:17], v[134:137], v[52:55], v[14:17]
	ds_read_b128 v[52:55], v22 offset:1024
	v_mfma_f32_16x16x32_bf16 v[154:157], v[40:43], v[150:153], v[154:157]
	v_mfma_f32_16x16x32_bf16 v[158:161], v[44:47], v[150:153], v[158:161]
	v_mfma_f32_16x16x32_bf16 v[162:165], v[48:51], v[150:153], v[162:165]
	v_mfma_f32_16x16x32_bf16 v[60:63], v[134:137], v[150:153], v[60:63]
	ds_read_b128 v[150:153], v21 offset:1024
	v_mfma_f32_16x16x32_bf16 v[170:173], v[40:43], v[166:169], v[170:173]
	v_mfma_f32_16x16x32_bf16 v[174:177], v[44:47], v[166:169], v[174:177]
	v_mfma_f32_16x16x32_bf16 v[178:181], v[48:51], v[166:169], v[178:181]
	v_mfma_f32_16x16x32_bf16 v[68:71], v[134:137], v[166:169], v[68:71]
	ds_read_b128 v[166:169], v20 offset:1024
	v_mfma_f32_16x16x32_bf16 v[182:185], v[40:43], v[32:35], v[186:189]
	v_mfma_f32_16x16x32_bf16 v[56:59], v[44:47], v[32:35], v[56:59]
	v_mfma_f32_16x16x32_bf16 v[64:67], v[48:51], v[32:35], v[64:67]
	v_mfma_f32_16x16x32_bf16 v[32:35], v[134:137], v[32:35], v[72:75]
	ds_read_b128 v[18:21], v19 offset:1024
	s_waitcnt lgkmcnt(0)
	v_mfma_f32_16x16x32_bf16 v[72:75], v[40:43], v[52:55], v[116:119]
	v_mfma_f32_16x16x32_bf16 v[116:119], v[44:47], v[52:55], v[120:123]
	v_mfma_f32_16x16x32_bf16 v[120:123], v[48:51], v[52:55], v[124:127]
	v_mfma_f32_16x16x32_bf16 v[52:55], v[134:137], v[52:55], v[112:115]
	v_mfma_f32_16x16x32_bf16 v[92:95], v[40:43], v[150:153], v[92:95]
	v_mfma_f32_16x16x32_bf16 v[100:103], v[44:47], v[150:153], v[100:103]
	v_mfma_f32_16x16x32_bf16 v[104:107], v[48:51], v[150:153], v[104:107]
	v_mfma_f32_16x16x32_bf16 v[108:111], v[134:137], v[150:153], v[108:111]
	v_mfma_f32_16x16x32_bf16 v[76:79], v[40:43], v[166:169], v[76:79]
	v_mfma_f32_16x16x32_bf16 v[80:83], v[44:47], v[166:169], v[80:83]
	v_mfma_f32_16x16x32_bf16 v[84:87], v[48:51], v[166:169], v[84:87]
	v_mfma_f32_16x16x32_bf16 v[88:91], v[134:137], v[166:169], v[88:91]
	v_mfma_f32_16x16x32_bf16 v[2:5], v[40:43], v[18:21], v[2:5]
	v_mfma_f32_16x16x32_bf16 v[6:9], v[44:47], v[18:21], v[6:9]
	v_mfma_f32_16x16x32_bf16 v[10:13], v[48:51], v[18:21], v[10:13]
	v_mfma_f32_16x16x32_bf16 v[18:21], v[134:137], v[18:21], v[36:39]
	s_waitcnt vmcnt(0)
	s_waitcnt vmcnt(0)
	s_barrier
	s_nop 0
	ds_read_b128 v[36:39], v31
	ds_read_b128 v[40:43], v30
	ds_read_b128 v[44:47], v29
	ds_read_b128 v[48:51], v28
	ds_read_b128 v[112:115], v27
	ds_read_b128 v[124:127], v26
	ds_read_b128 v[134:137], v25
	ds_read_b128 v[150:153], v24
	ds_read_b128 v[166:169], v23
	s_waitcnt lgkmcnt(0)
	v_mfma_f32_16x16x32_bf16 v[186:189], v[166:169], v[36:39], v[2:5]
	s_nop 2
	ds_read_b128 v[2:5], v23 offset:2048
	s_waitcnt lgkmcnt(0)
	v_mfma_f32_16x16x32_bf16 v[190:193], v[2:5], v[36:39], v[6:9]
	s_nop 2
	ds_read_b128 v[6:9], v23 offset:4096
	s_waitcnt lgkmcnt(0)
	v_mfma_f32_16x16x32_bf16 v[194:197], v[6:9], v[36:39], v[10:13]
	s_nop 2
	ds_read_b128 v[10:13], v23 offset:6144
	s_waitcnt lgkmcnt(0)
	v_mfma_f32_16x16x32_bf16 v[198:201], v[10:13], v[36:39], v[18:21]
	v_mfma_f32_16x16x32_bf16 v[18:21], v[10:13], v[134:137], v[60:63]
	v_mfma_f32_16x16x32_bf16 v[36:39], v[10:13], v[124:127], v[68:71]
	v_mfma_f32_16x16x32_bf16 v[68:71], v[6:9], v[134:137], v[162:165]
	v_mfma_f32_16x16x32_bf16 v[162:165], v[6:9], v[112:115], v[64:67]
	v_mfma_f32_16x16x32_bf16 v[64:67], v[2:5], v[150:153], v[142:145]
	v_mfma_f32_16x16x32_bf16 v[142:145], v[2:5], v[134:137], v[158:161]
	v_mfma_f32_16x16x32_bf16 v[134:137], v[166:169], v[134:137], v[154:157]
	v_mfma_f32_16x16x32_bf16 v[154:157], v[166:169], v[40:43], v[76:79]
	v_mfma_f32_16x16x32_bf16 v[60:63], v[6:9], v[150:153], v[146:149]
	v_mfma_f32_16x16x32_bf16 v[146:149], v[6:9], v[124:127], v[178:181]
	v_mfma_f32_16x16x32_bf16 v[158:161], v[2:5], v[124:127], v[174:177]
	v_mfma_f32_16x16x32_bf16 v[124:127], v[166:169], v[124:127], v[170:173]
	v_mfma_f32_16x16x32_bf16 v[170:173], v[6:9], v[40:43], v[84:87]
	v_mfma_f32_16x16x32_bf16 v[138:141], v[166:169], v[150:153], v[138:141]
	v_mfma_f32_16x16x32_bf16 v[56:59], v[2:5], v[112:115], v[56:59]
	v_mfma_f32_16x16x32_bf16 v[116:119], v[2:5], v[48:51], v[116:119]
	v_mfma_f32_16x16x32_bf16 v[120:123], v[6:9], v[48:51], v[120:123]
	v_mfma_f32_16x16x32_bf16 v[14:17], v[10:13], v[150:153], v[14:17]
	v_mfma_f32_16x16x32_bf16 v[150:153], v[166:169], v[48:51], v[72:75]
	v_mfma_f32_16x16x32_bf16 v[48:51], v[10:13], v[48:51], v[52:55]
	v_mfma_f32_16x16x32_bf16 v[52:55], v[166:169], v[44:47], v[92:95]
	v_mfma_f32_16x16x32_bf16 v[32:35], v[10:13], v[112:115], v[32:35]
	v_mfma_f32_16x16x32_bf16 v[112:115], v[166:169], v[112:115], v[182:185]
	v_mfma_f32_16x16x32_bf16 v[166:169], v[2:5], v[40:43], v[80:83]
	v_mfma_f32_16x16x32_bf16 v[104:107], v[6:9], v[44:47], v[104:107]
	v_mfma_f32_16x16x32_bf16 v[108:111], v[10:13], v[44:47], v[108:111]
	v_mfma_f32_16x16x32_bf16 v[100:103], v[2:5], v[44:47], v[100:103]
	v_mfma_f32_16x16x32_bf16 v[174:177], v[10:13], v[40:43], v[88:91]
	ds_read_b128 v[178:181], v23 offset:1024
	ds_read_b128 v[182:185], v23 offset:3072
	ds_read_b128 v[202:205], v23 offset:5120
	ds_read_b128 v[206:209], v23 offset:7168
	ds_read_b128 v[2:5], v24 offset:1024
	ds_read_b128 v[6:9], v25 offset:1024
	ds_read_b128 v[10:13], v26 offset:1024
	ds_read_b128 v[22:25], v27 offset:1024
	s_waitcnt lgkmcnt(3)
	v_mfma_f32_16x16x32_bf16 v[138:141], v[178:181], v[2:5], v[138:141]
	v_mfma_f32_16x16x32_bf16 v[210:213], v[182:185], v[2:5], v[64:67]
	v_mfma_f32_16x16x32_bf16 v[214:217], v[202:205], v[2:5], v[60:63]
	v_mfma_f32_16x16x32_bf16 v[218:221], v[206:209], v[2:5], v[14:17]
	ds_read_b128 v[2:5], v28 offset:1024
	s_waitcnt lgkmcnt(3)
	v_mfma_f32_16x16x32_bf16 v[134:137], v[178:181], v[6:9], v[134:137]
	v_mfma_f32_16x16x32_bf16 v[142:145], v[182:185], v[6:9], v[142:145]
	v_mfma_f32_16x16x32_bf16 v[222:225], v[202:205], v[6:9], v[68:71]
	v_mfma_f32_16x16x32_bf16 v[226:229], v[206:209], v[6:9], v[18:21]
	ds_read_b128 v[6:9], v29 offset:1024
	s_waitcnt lgkmcnt(3)
	v_mfma_f32_16x16x32_bf16 v[66:69], v[178:181], v[10:13], v[124:127]
	v_mfma_f32_16x16x32_bf16 v[70:73], v[182:185], v[10:13], v[158:161]
	v_mfma_f32_16x16x32_bf16 v[74:77], v[202:205], v[10:13], v[146:149]
	v_mfma_f32_16x16x32_bf16 v[78:81], v[206:209], v[10:13], v[36:39]
	ds_read_b128 v[14:17], v30 offset:1024
	s_waitcnt lgkmcnt(3)
	v_mfma_f32_16x16x32_bf16 v[82:85], v[178:181], v[22:25], v[112:115]
	v_mfma_f32_16x16x32_bf16 v[86:89], v[182:185], v[22:25], v[56:59]
	v_mfma_f32_16x16x32_bf16 v[90:93], v[202:205], v[22:25], v[162:165]
	v_mfma_f32_16x16x32_bf16 v[94:97], v[206:209], v[22:25], v[32:35]
	s_nop 2
	ds_read_b128 v[30:33], v31 offset:1024
	s_waitcnt lgkmcnt(3)
	v_mfma_f32_16x16x32_bf16 v[34:37], v[178:181], v[2:5], v[150:153]
	v_mfma_f32_16x16x32_bf16 v[38:41], v[182:185], v[2:5], v[116:119]
	v_mfma_f32_16x16x32_bf16 v[42:45], v[202:205], v[2:5], v[120:123]
	v_mfma_f32_16x16x32_bf16 v[46:49], v[206:209], v[2:5], v[48:51]
	s_waitcnt lgkmcnt(2)
	v_mfma_f32_16x16x32_bf16 v[50:53], v[178:181], v[6:9], v[52:55]
	v_mfma_f32_16x16x32_bf16 v[54:57], v[182:185], v[6:9], v[100:103]
	v_mfma_f32_16x16x32_bf16 v[58:61], v[202:205], v[6:9], v[104:107]
	v_mfma_f32_16x16x32_bf16 v[62:65], v[206:209], v[6:9], v[108:111]
	s_waitcnt lgkmcnt(1)
	v_mfma_f32_16x16x32_bf16 v[2:5], v[178:181], v[14:17], v[154:157]
	v_mfma_f32_16x16x32_bf16 v[6:9], v[182:185], v[14:17], v[166:169]
	v_mfma_f32_16x16x32_bf16 v[10:13], v[202:205], v[14:17], v[170:173]
	v_mfma_f32_16x16x32_bf16 v[14:17], v[206:209], v[14:17], v[174:177]
	s_waitcnt lgkmcnt(0)
	v_mfma_f32_16x16x32_bf16 v[18:21], v[178:181], v[30:33], v[186:189]
	v_mfma_f32_16x16x32_bf16 v[22:25], v[182:185], v[30:33], v[190:193]
	v_mfma_f32_16x16x32_bf16 v[26:29], v[202:205], v[30:33], v[194:197]
	v_mfma_f32_16x16x32_bf16 v[30:33], v[206:209], v[30:33], v[198:201]
	v_lshlrev_b32_e32 v101, 2, v98
	v_and_b32_e32 v112, 60, v101
	v_ashrrev_i32_e32 v101, 1, v98
	v_lshrrev_b32_e32 v99, 6, v98
	v_and_b32_e32 v101, 0xffffff80, v101
	v_and_b32_e32 v100, 15, v98
	v_mul_lo_u32 v99, v99, s48
	v_add_u32_e32 v107, s28, v101
	v_bfe_u32 v108, v98, 4, 2
	v_add_u32_e32 v109, s46, v99
	v_and_b32_e32 v99, 48, v98
	v_and_or_b32 v102, v98, s49, v112
	v_mul_u32_u24_e32 v98, 0x110, v100
	v_or_b32_e32 v100, v107, v108
	v_lshl_add_u64 v[0:1], v[0:1], 0, s[38:39]
	v_lshlrev_b32_e32 v130, 1, v102
	v_ashrrev_i32_e32 v101, 31, v100
	v_lshl_add_u64 v[0:1], v[0:1], 0, v[130:131]
	v_add3_u32 v99, v109, v99, v98
	v_lshlrev_b64 v[100:101], 11, v[100:101]
	s_waitcnt vmcnt(0)
	s_barrier
	ds_write_b128 v99, v[138:141]
	ds_write_b128 v99, v[210:213] offset:64
	ds_write_b128 v99, v[214:217] offset:128
	ds_write_b128 v99, v[218:221] offset:192
	ds_write_b128 v99, v[134:137] offset:4352
	ds_write_b128 v99, v[142:145] offset:4416
	ds_write_b128 v99, v[222:225] offset:4480
	ds_write_b128 v99, v[226:229] offset:4544
	v_lshl_add_u64 v[114:115], v[0:1], 0, v[100:101]
	flat_load_dwordx2 v[116:117], v[114:115]
	v_or_b32_e32 v100, 4, v108
	v_or_b32_e32 v102, v107, v100
	v_ashrrev_i32_e32 v103, 31, v102
	v_lshlrev_b64 v[102:103], 11, v[102:103]
	v_lshl_add_u64 v[118:119], v[0:1], 0, v[102:103]
	flat_load_dwordx2 v[120:121], v[118:119]
	v_or_b32_e32 v101, 8, v108
	v_or_b32_e32 v102, v107, v101
	v_ashrrev_i32_e32 v103, 31, v102
	v_lshlrev_b64 v[102:103], 11, v[102:103]
	v_lshl_add_u64 v[122:123], v[0:1], 0, v[102:103]
	flat_load_dwordx2 v[124:125], v[122:123]
	v_or_b32_e32 v102, 12, v108
	v_or_b32_e32 v104, v107, v102
	v_ashrrev_i32_e32 v105, 31, v104
	v_lshlrev_b64 v[104:105], 11, v[104:105]
	v_lshl_add_u64 v[126:127], v[0:1], 0, v[104:105]
	flat_load_dwordx2 v[128:129], v[126:127]
	v_or_b32_e32 v103, 16, v108
	v_or_b32_e32 v104, v107, v103
	v_ashrrev_i32_e32 v105, 31, v104
	v_lshlrev_b64 v[104:105], 11, v[104:105]
	v_lshl_add_u64 v[134:135], v[0:1], 0, v[104:105]
	flat_load_dwordx2 v[136:137], v[134:135]
	v_or_b32_e32 v104, 20, v108
	v_or_b32_e32 v110, v107, v104
	v_ashrrev_i32_e32 v111, 31, v110
	v_lshlrev_b64 v[110:111], 11, v[110:111]
	v_lshl_add_u64 v[138:139], v[0:1], 0, v[110:111]
	flat_load_dwordx2 v[140:141], v[138:139]
	v_or_b32_e32 v105, 24, v108
	v_or_b32_e32 v110, v107, v105
	v_ashrrev_i32_e32 v111, 31, v110
	v_lshlrev_b64 v[110:111], 11, v[110:111]
	v_lshl_add_u64 v[142:143], v[0:1], 0, v[110:111]
	flat_load_dwordx2 v[144:145], v[142:143]
	v_or_b32_e32 v106, 28, v108
	v_or_b32_e32 v146, v107, v106
	v_ashrrev_i32_e32 v147, 31, v146
	v_lshlrev_b64 v[146:147], 11, v[146:147]
	v_lshl_add_u64 v[146:147], v[0:1], 0, v[146:147]
	flat_load_dwordx2 v[148:149], v[146:147]
	v_mul_u32_u24_e32 v98, 0x110, v108
	v_lshlrev_b32_e32 v110, 2, v112
	v_add3_u32 v98, v109, v110, v98
	ds_read_b128 v[110:113], v98
	s_add_i32 s0, s30, 0x1600
	s_lshl_b64 s[42:43], s[0:1], 11
	s_waitcnt vmcnt(0) lgkmcnt(0)
	v_and_b32_e32 v151, 0xffff0000, v116
	v_lshlrev_b32_e32 v150, 16, v116
	v_and_b32_e32 v153, 0xffff0000, v117
	v_lshlrev_b32_e32 v152, 16, v117
	v_pk_mul_f32 v[110:111], v[110:111], v[150:151]
	v_pk_mul_f32 v[112:113], v[112:113], v[152:153]
	v_cvt_pk_bf16_f32 v110, v110, v111
	v_cvt_pk_bf16_f32 v111, v112, v113
	flat_store_dwordx2 v[114:115], v[110:111]
	ds_read_b128 v[110:113], v98 offset:1088
	v_and_b32_e32 v115, 0xffff0000, v120
	v_lshlrev_b32_e32 v114, 16, v120
	v_and_b32_e32 v117, 0xffff0000, v121
	v_lshlrev_b32_e32 v116, 16, v121
	s_waitcnt lgkmcnt(0)
	v_pk_mul_f32 v[110:111], v[110:111], v[114:115]
	v_pk_mul_f32 v[112:113], v[112:113], v[116:117]
	v_cvt_pk_bf16_f32 v110, v110, v111
	v_cvt_pk_bf16_f32 v111, v112, v113
	flat_store_dwordx2 v[118:119], v[110:111]
	ds_read_b128 v[110:113], v98 offset:2176
	v_and_b32_e32 v115, 0xffff0000, v124
	v_lshlrev_b32_e32 v114, 16, v124
	v_and_b32_e32 v117, 0xffff0000, v125
	v_lshlrev_b32_e32 v116, 16, v125
	s_waitcnt lgkmcnt(0)
	v_pk_mul_f32 v[110:111], v[110:111], v[114:115]
	v_pk_mul_f32 v[112:113], v[112:113], v[116:117]
	v_cvt_pk_bf16_f32 v110, v110, v111
	v_cvt_pk_bf16_f32 v111, v112, v113
	flat_store_dwordx2 v[122:123], v[110:111]
	ds_read_b128 v[110:113], v98 offset:3264
	v_and_b32_e32 v115, 0xffff0000, v128
	v_lshlrev_b32_e32 v114, 16, v128
	v_mov_b32_e32 v150, v132
	s_waitcnt lgkmcnt(0)
	v_pk_mul_f32 v[110:111], v[110:111], v[114:115]
	v_and_b32_e32 v115, 0xffff0000, v129
	v_lshlrev_b32_e32 v114, 16, v129
	v_pk_mul_f32 v[112:113], v[112:113], v[114:115]
	v_cvt_pk_bf16_f32 v110, v110, v111
	v_cvt_pk_bf16_f32 v111, v112, v113
	flat_store_dwordx2 v[126:127], v[110:111]
	ds_read_b128 v[110:113], v98 offset:4352
	v_and_b32_e32 v115, 0xffff0000, v136
	v_lshlrev_b32_e32 v114, 16, v136
	s_waitcnt lgkmcnt(0)
	v_pk_mul_f32 v[110:111], v[110:111], v[114:115]
	v_and_b32_e32 v115, 0xffff0000, v137
	v_lshlrev_b32_e32 v114, 16, v137
	v_pk_mul_f32 v[112:113], v[112:113], v[114:115]
	v_cvt_pk_bf16_f32 v110, v110, v111
	v_cvt_pk_bf16_f32 v111, v112, v113
	flat_store_dwordx2 v[134:135], v[110:111]
	ds_read_b128 v[110:113], v98 offset:5440
	v_and_b32_e32 v115, 0xffff0000, v140
	v_lshlrev_b32_e32 v114, 16, v140
	s_waitcnt lgkmcnt(0)
	v_pk_mul_f32 v[110:111], v[110:111], v[114:115]
	v_and_b32_e32 v115, 0xffff0000, v141
	v_lshlrev_b32_e32 v114, 16, v141
	v_pk_mul_f32 v[112:113], v[112:113], v[114:115]
	v_cvt_pk_bf16_f32 v110, v110, v111
	v_cvt_pk_bf16_f32 v111, v112, v113
	flat_store_dwordx2 v[138:139], v[110:111]
	ds_read_b128 v[110:113], v98 offset:6528
	v_and_b32_e32 v115, 0xffff0000, v144
	v_lshlrev_b32_e32 v114, 16, v144
	s_waitcnt lgkmcnt(0)
	v_pk_mul_f32 v[110:111], v[110:111], v[114:115]
	v_and_b32_e32 v115, 0xffff0000, v145
	v_lshlrev_b32_e32 v114, 16, v145
	v_pk_mul_f32 v[112:113], v[112:113], v[114:115]
	v_cvt_pk_bf16_f32 v110, v110, v111
	v_cvt_pk_bf16_f32 v111, v112, v113
	flat_store_dwordx2 v[142:143], v[110:111]
	ds_read_b128 v[110:113], v98 offset:7616
	v_and_b32_e32 v115, 0xffff0000, v148
	v_lshlrev_b32_e32 v114, 16, v148
	s_waitcnt lgkmcnt(0)
	v_pk_mul_f32 v[110:111], v[110:111], v[114:115]
	v_and_b32_e32 v115, 0xffff0000, v149
	v_lshlrev_b32_e32 v114, 16, v149
	v_pk_mul_f32 v[112:113], v[112:113], v[114:115]
	v_cvt_pk_bf16_f32 v110, v110, v111
	v_cvt_pk_bf16_f32 v111, v112, v113
	flat_store_dwordx2 v[146:147], v[110:111]
	ds_write_b128 v99, v[66:69]
	v_or_b32_e32 v68, 32, v107
	v_or_b32_e32 v66, v68, v108
	v_ashrrev_i32_e32 v67, 31, v66
	v_lshlrev_b64 v[66:67], 11, v[66:67]
	ds_write_b128 v99, v[70:73] offset:64
	ds_write_b128 v99, v[74:77] offset:128
	ds_write_b128 v99, v[78:81] offset:192
	ds_write_b128 v99, v[82:85] offset:4352
	ds_write_b128 v99, v[86:89] offset:4416
	ds_write_b128 v99, v[90:93] offset:4480
	ds_write_b128 v99, v[94:97] offset:4544
	v_lshl_add_u64 v[70:71], v[0:1], 0, v[66:67]
	flat_load_dwordx2 v[72:73], v[70:71]
	v_or_b32_e32 v66, v68, v100
	v_ashrrev_i32_e32 v67, 31, v66
	v_lshlrev_b64 v[66:67], 11, v[66:67]
	v_lshl_add_u64 v[74:75], v[0:1], 0, v[66:67]
	flat_load_dwordx2 v[76:77], v[74:75]
	v_or_b32_e32 v66, v68, v101
	v_ashrrev_i32_e32 v67, 31, v66
	v_lshlrev_b64 v[66:67], 11, v[66:67]
	v_lshl_add_u64 v[78:79], v[0:1], 0, v[66:67]
	flat_load_dwordx2 v[80:81], v[78:79]
	v_or_b32_e32 v66, v68, v102
	v_ashrrev_i32_e32 v67, 31, v66
	v_lshlrev_b64 v[66:67], 11, v[66:67]
	v_lshl_add_u64 v[82:83], v[0:1], 0, v[66:67]
	flat_load_dwordx2 v[84:85], v[82:83]
	v_or_b32_e32 v66, v68, v103
	v_ashrrev_i32_e32 v67, 31, v66
	v_lshlrev_b64 v[66:67], 11, v[66:67]
	v_lshl_add_u64 v[86:87], v[0:1], 0, v[66:67]
	flat_load_dwordx2 v[88:89], v[86:87]
	v_or_b32_e32 v66, v68, v104
	v_ashrrev_i32_e32 v67, 31, v66
	v_lshlrev_b64 v[66:67], 11, v[66:67]
	v_lshl_add_u64 v[90:91], v[0:1], 0, v[66:67]
	flat_load_dwordx2 v[92:93], v[90:91]
	v_or_b32_e32 v66, v68, v105
	v_ashrrev_i32_e32 v67, 31, v66
	v_lshlrev_b64 v[66:67], 11, v[66:67]
	v_lshl_add_u64 v[94:95], v[0:1], 0, v[66:67]
	flat_load_dwordx2 v[96:97], v[94:95]
	v_or_b32_e32 v66, v68, v106
	v_ashrrev_i32_e32 v67, 31, v66
	v_lshlrev_b64 v[66:67], 11, v[66:67]
	v_lshl_add_u64 v[110:111], v[0:1], 0, v[66:67]
	flat_load_dwordx2 v[112:113], v[110:111]
	ds_read_b128 v[66:69], v98
	s_waitcnt vmcnt(0) lgkmcnt(0)
	v_and_b32_e32 v115, 0xffff0000, v72
	v_lshlrev_b32_e32 v114, 16, v72
	v_and_b32_e32 v117, 0xffff0000, v73
	v_lshlrev_b32_e32 v116, 16, v73
	v_pk_mul_f32 v[66:67], v[66:67], v[114:115]
	v_pk_mul_f32 v[68:69], v[68:69], v[116:117]
	v_cvt_pk_bf16_f32 v66, v66, v67
	v_cvt_pk_bf16_f32 v67, v68, v69
	flat_store_dwordx2 v[70:71], v[66:67]
	ds_read_b128 v[66:69], v98 offset:1088
	v_and_b32_e32 v71, 0xffff0000, v76
	v_lshlrev_b32_e32 v70, 16, v76
	v_and_b32_e32 v73, 0xffff0000, v77
	v_lshlrev_b32_e32 v72, 16, v77
	s_waitcnt lgkmcnt(0)
	v_pk_mul_f32 v[66:67], v[66:67], v[70:71]
	v_pk_mul_f32 v[68:69], v[68:69], v[72:73]
	v_cvt_pk_bf16_f32 v66, v66, v67
	v_cvt_pk_bf16_f32 v67, v68, v69
	flat_store_dwordx2 v[74:75], v[66:67]
	ds_read_b128 v[66:69], v98 offset:2176
	v_and_b32_e32 v71, 0xffff0000, v80
	v_lshlrev_b32_e32 v70, 16, v80
	v_and_b32_e32 v73, 0xffff0000, v81
	v_lshlrev_b32_e32 v72, 16, v81
	s_waitcnt lgkmcnt(0)
	v_pk_mul_f32 v[66:67], v[66:67], v[70:71]
	v_pk_mul_f32 v[68:69], v[68:69], v[72:73]
	v_cvt_pk_bf16_f32 v66, v66, v67
	v_cvt_pk_bf16_f32 v67, v68, v69
	flat_store_dwordx2 v[78:79], v[66:67]
	ds_read_b128 v[66:69], v98 offset:3264
	v_and_b32_e32 v71, 0xffff0000, v84
	v_lshlrev_b32_e32 v70, 16, v84
	v_and_b32_e32 v73, 0xffff0000, v85
	v_lshlrev_b32_e32 v72, 16, v85
	s_waitcnt lgkmcnt(0)
	v_pk_mul_f32 v[66:67], v[66:67], v[70:71]
	v_pk_mul_f32 v[68:69], v[68:69], v[72:73]
	v_cvt_pk_bf16_f32 v66, v66, v67
	v_cvt_pk_bf16_f32 v67, v68, v69
	flat_store_dwordx2 v[82:83], v[66:67]
	ds_read_b128 v[66:69], v98 offset:4352
	v_and_b32_e32 v71, 0xffff0000, v88
	v_lshlrev_b32_e32 v70, 16, v88
	v_and_b32_e32 v73, 0xffff0000, v89
	v_lshlrev_b32_e32 v72, 16, v89
	s_waitcnt lgkmcnt(0)
	v_pk_mul_f32 v[66:67], v[66:67], v[70:71]
	v_pk_mul_f32 v[68:69], v[68:69], v[72:73]
	v_cvt_pk_bf16_f32 v66, v66, v67
	v_cvt_pk_bf16_f32 v67, v68, v69
	flat_store_dwordx2 v[86:87], v[66:67]
	ds_read_b128 v[66:69], v98 offset:5440
	v_and_b32_e32 v71, 0xffff0000, v92
	v_lshlrev_b32_e32 v70, 16, v92
	v_and_b32_e32 v73, 0xffff0000, v93
	v_lshlrev_b32_e32 v72, 16, v93
	s_waitcnt lgkmcnt(0)
	v_pk_mul_f32 v[66:67], v[66:67], v[70:71]
	v_pk_mul_f32 v[68:69], v[68:69], v[72:73]
	v_cvt_pk_bf16_f32 v66, v66, v67
	v_cvt_pk_bf16_f32 v67, v68, v69
	flat_store_dwordx2 v[90:91], v[66:67]
	ds_read_b128 v[66:69], v98 offset:6528
	v_and_b32_e32 v71, 0xffff0000, v96
	v_lshlrev_b32_e32 v70, 16, v96
	v_and_b32_e32 v73, 0xffff0000, v97
	v_lshlrev_b32_e32 v72, 16, v97
	s_waitcnt lgkmcnt(0)
	v_pk_mul_f32 v[66:67], v[66:67], v[70:71]
	v_pk_mul_f32 v[68:69], v[68:69], v[72:73]
	v_cvt_pk_bf16_f32 v66, v66, v67
	v_cvt_pk_bf16_f32 v67, v68, v69
	flat_store_dwordx2 v[94:95], v[66:67]
	ds_read_b128 v[66:69], v98 offset:7616
	v_and_b32_e32 v71, 0xffff0000, v112
	v_lshlrev_b32_e32 v70, 16, v112
	v_and_b32_e32 v73, 0xffff0000, v113
	v_lshlrev_b32_e32 v72, 16, v113
	s_waitcnt lgkmcnt(0)
	v_pk_mul_f32 v[66:67], v[66:67], v[70:71]
	v_pk_mul_f32 v[68:69], v[68:69], v[72:73]
	v_cvt_pk_bf16_f32 v66, v66, v67
	v_cvt_pk_bf16_f32 v67, v68, v69
	flat_store_dwordx2 v[110:111], v[66:67]
	ds_write_b128 v99, v[34:37]
	v_or_b32_e32 v36, 64, v107
	v_or_b32_e32 v34, v36, v108
	v_ashrrev_i32_e32 v35, 31, v34
	v_lshlrev_b64 v[34:35], 11, v[34:35]
	ds_write_b128 v99, v[38:41] offset:64
	ds_write_b128 v99, v[42:45] offset:128
	ds_write_b128 v99, v[46:49] offset:192
	ds_write_b128 v99, v[50:53] offset:4352
	ds_write_b128 v99, v[54:57] offset:4416
	ds_write_b128 v99, v[58:61] offset:4480
	ds_write_b128 v99, v[62:65] offset:4544
	v_lshl_add_u64 v[38:39], v[0:1], 0, v[34:35]
	flat_load_dwordx2 v[40:41], v[38:39]
	v_or_b32_e32 v34, v36, v100
	v_ashrrev_i32_e32 v35, 31, v34
	v_lshlrev_b64 v[34:35], 11, v[34:35]
	v_lshl_add_u64 v[42:43], v[0:1], 0, v[34:35]
	flat_load_dwordx2 v[44:45], v[42:43]
	v_or_b32_e32 v34, v36, v101
	v_ashrrev_i32_e32 v35, 31, v34
	v_lshlrev_b64 v[34:35], 11, v[34:35]
	v_lshl_add_u64 v[46:47], v[0:1], 0, v[34:35]
	flat_load_dwordx2 v[48:49], v[46:47]
	v_or_b32_e32 v34, v36, v102
	v_ashrrev_i32_e32 v35, 31, v34
	v_lshlrev_b64 v[34:35], 11, v[34:35]
	v_lshl_add_u64 v[50:51], v[0:1], 0, v[34:35]
	flat_load_dwordx2 v[52:53], v[50:51]
	v_or_b32_e32 v34, v36, v103
	v_ashrrev_i32_e32 v35, 31, v34
	v_lshlrev_b64 v[34:35], 11, v[34:35]
	v_lshl_add_u64 v[54:55], v[0:1], 0, v[34:35]
	flat_load_dwordx2 v[56:57], v[54:55]
	v_or_b32_e32 v34, v36, v104
	v_ashrrev_i32_e32 v35, 31, v34
	v_lshlrev_b64 v[34:35], 11, v[34:35]
	v_lshl_add_u64 v[58:59], v[0:1], 0, v[34:35]
	flat_load_dwordx2 v[60:61], v[58:59]
	v_or_b32_e32 v34, v36, v105
	v_ashrrev_i32_e32 v35, 31, v34
	v_lshlrev_b64 v[34:35], 11, v[34:35]
	v_lshl_add_u64 v[62:63], v[0:1], 0, v[34:35]
	flat_load_dwordx2 v[64:65], v[62:63]
	v_or_b32_e32 v34, v36, v106
	v_ashrrev_i32_e32 v35, 31, v34
	v_lshlrev_b64 v[34:35], 11, v[34:35]
	v_lshl_add_u64 v[66:67], v[0:1], 0, v[34:35]
	flat_load_dwordx2 v[68:69], v[66:67]
	ds_read_b128 v[34:37], v98
	v_or_b32_e32 v76, 0x60, v107
	v_or_b32_e32 v70, v76, v108
	v_ashrrev_i32_e32 v71, 31, v70
	s_waitcnt vmcnt(0) lgkmcnt(0)
	v_and_b32_e32 v73, 0xffff0000, v40
	v_lshlrev_b32_e32 v72, 16, v40
	v_and_b32_e32 v75, 0xffff0000, v41
	v_lshlrev_b32_e32 v74, 16, v41
	v_pk_mul_f32 v[34:35], v[34:35], v[72:73]
	v_pk_mul_f32 v[36:37], v[36:37], v[74:75]
	v_cvt_pk_bf16_f32 v34, v34, v35
	v_cvt_pk_bf16_f32 v35, v36, v37
	flat_store_dwordx2 v[38:39], v[34:35]
	ds_read_b128 v[34:37], v98 offset:1088
	v_and_b32_e32 v39, 0xffff0000, v44
	v_lshlrev_b32_e32 v38, 16, v44
	v_and_b32_e32 v41, 0xffff0000, v45
	v_lshlrev_b32_e32 v40, 16, v45
	s_waitcnt lgkmcnt(0)
	v_pk_mul_f32 v[34:35], v[34:35], v[38:39]
	v_pk_mul_f32 v[36:37], v[36:37], v[40:41]
	v_cvt_pk_bf16_f32 v34, v34, v35
	v_cvt_pk_bf16_f32 v35, v36, v37
	flat_store_dwordx2 v[42:43], v[34:35]
	ds_read_b128 v[34:37], v98 offset:2176
	v_and_b32_e32 v39, 0xffff0000, v48
	v_lshlrev_b32_e32 v38, 16, v48
	v_and_b32_e32 v41, 0xffff0000, v49
	v_lshlrev_b32_e32 v40, 16, v49
	s_waitcnt lgkmcnt(0)
	v_pk_mul_f32 v[34:35], v[34:35], v[38:39]
	v_pk_mul_f32 v[36:37], v[36:37], v[40:41]
	v_cvt_pk_bf16_f32 v34, v34, v35
	v_cvt_pk_bf16_f32 v35, v36, v37
	flat_store_dwordx2 v[46:47], v[34:35]
	ds_read_b128 v[34:37], v98 offset:3264
	v_and_b32_e32 v39, 0xffff0000, v52
	v_lshlrev_b32_e32 v38, 16, v52
	v_and_b32_e32 v41, 0xffff0000, v53
	v_lshlrev_b32_e32 v40, 16, v53
	s_waitcnt lgkmcnt(0)
	v_pk_mul_f32 v[34:35], v[34:35], v[38:39]
	v_pk_mul_f32 v[36:37], v[36:37], v[40:41]
	v_cvt_pk_bf16_f32 v34, v34, v35
	v_cvt_pk_bf16_f32 v35, v36, v37
	flat_store_dwordx2 v[50:51], v[34:35]
	ds_read_b128 v[34:37], v98 offset:4352
	v_and_b32_e32 v39, 0xffff0000, v56
	v_lshlrev_b32_e32 v38, 16, v56
	v_and_b32_e32 v41, 0xffff0000, v57
	v_lshlrev_b32_e32 v40, 16, v57
	s_waitcnt lgkmcnt(0)
	v_pk_mul_f32 v[34:35], v[34:35], v[38:39]
	v_pk_mul_f32 v[36:37], v[36:37], v[40:41]
	v_cvt_pk_bf16_f32 v34, v34, v35
	v_cvt_pk_bf16_f32 v35, v36, v37
	flat_store_dwordx2 v[54:55], v[34:35]
	ds_read_b128 v[34:37], v98 offset:5440
	v_and_b32_e32 v39, 0xffff0000, v60
	v_lshlrev_b32_e32 v38, 16, v60
	v_and_b32_e32 v41, 0xffff0000, v61
	v_lshlrev_b32_e32 v40, 16, v61
	s_waitcnt lgkmcnt(0)
	v_pk_mul_f32 v[34:35], v[34:35], v[38:39]
	v_pk_mul_f32 v[36:37], v[36:37], v[40:41]
	v_cvt_pk_bf16_f32 v34, v34, v35
	v_cvt_pk_bf16_f32 v35, v36, v37
	flat_store_dwordx2 v[58:59], v[34:35]
	ds_read_b128 v[34:37], v98 offset:6528
	v_and_b32_e32 v39, 0xffff0000, v64
	v_lshlrev_b32_e32 v38, 16, v64
	v_and_b32_e32 v41, 0xffff0000, v65
	v_lshlrev_b32_e32 v40, 16, v65
	s_waitcnt lgkmcnt(0)
	v_pk_mul_f32 v[34:35], v[34:35], v[38:39]
	v_pk_mul_f32 v[36:37], v[36:37], v[40:41]
	v_cvt_pk_bf16_f32 v34, v34, v35
	v_cvt_pk_bf16_f32 v35, v36, v37
	flat_store_dwordx2 v[62:63], v[34:35]
	ds_read_b128 v[34:37], v98 offset:7616
	v_and_b32_e32 v39, 0xffff0000, v68
	v_lshlrev_b32_e32 v38, 16, v68
	v_and_b32_e32 v41, 0xffff0000, v69
	v_lshlrev_b32_e32 v40, 16, v69
	s_waitcnt lgkmcnt(0)
	v_pk_mul_f32 v[34:35], v[34:35], v[38:39]
	v_pk_mul_f32 v[36:37], v[36:37], v[40:41]
	v_cvt_pk_bf16_f32 v34, v34, v35
	v_cvt_pk_bf16_f32 v35, v36, v37
	flat_store_dwordx2 v[66:67], v[34:35]
	ds_write_b128 v99, v[2:5]
	v_lshlrev_b64 v[2:3], 11, v[70:71]
	ds_write_b128 v99, v[6:9] offset:64
	ds_write_b128 v99, v[10:13] offset:128
	ds_write_b128 v99, v[14:17] offset:192
	ds_write_b128 v99, v[18:21] offset:4352
	ds_write_b128 v99, v[22:25] offset:4416
	ds_write_b128 v99, v[26:29] offset:4480
	ds_write_b128 v99, v[30:33] offset:4544
	v_lshl_add_u64 v[4:5], v[0:1], 0, v[2:3]
	flat_load_dwordx2 v[6:7], v[4:5]
	v_or_b32_e32 v2, v76, v100
	v_ashrrev_i32_e32 v3, 31, v2
	v_lshlrev_b64 v[2:3], 11, v[2:3]
	v_lshl_add_u64 v[8:9], v[0:1], 0, v[2:3]
	flat_load_dwordx2 v[10:11], v[8:9]
	v_or_b32_e32 v2, v76, v101
	v_ashrrev_i32_e32 v3, 31, v2
	v_lshlrev_b64 v[2:3], 11, v[2:3]
	v_lshl_add_u64 v[12:13], v[0:1], 0, v[2:3]
	flat_load_dwordx2 v[14:15], v[12:13]
	v_or_b32_e32 v2, v76, v102
	v_ashrrev_i32_e32 v3, 31, v2
	v_lshlrev_b64 v[2:3], 11, v[2:3]
	v_lshl_add_u64 v[16:17], v[0:1], 0, v[2:3]
	flat_load_dwordx2 v[18:19], v[16:17]
	v_or_b32_e32 v2, v76, v103
	v_ashrrev_i32_e32 v3, 31, v2
	v_lshlrev_b64 v[2:3], 11, v[2:3]
	v_lshl_add_u64 v[20:21], v[0:1], 0, v[2:3]
	flat_load_dwordx2 v[22:23], v[20:21]
	v_or_b32_e32 v2, v76, v104
	v_ashrrev_i32_e32 v3, 31, v2
	v_lshlrev_b64 v[2:3], 11, v[2:3]
	v_lshl_add_u64 v[24:25], v[0:1], 0, v[2:3]
	flat_load_dwordx2 v[26:27], v[24:25]
	v_or_b32_e32 v2, v76, v105
	v_ashrrev_i32_e32 v3, 31, v2
	v_lshlrev_b64 v[2:3], 11, v[2:3]
	v_lshl_add_u64 v[28:29], v[0:1], 0, v[2:3]
	flat_load_dwordx2 v[30:31], v[28:29]
	v_or_b32_e32 v2, v76, v106
	v_ashrrev_i32_e32 v3, 31, v2
	v_lshlrev_b64 v[2:3], 11, v[2:3]
	v_lshl_add_u64 v[32:33], v[0:1], 0, v[2:3]
	flat_load_dwordx2 v[34:35], v[32:33]
	ds_read_b128 v[0:3], v98
	v_mov_b32_e32 v40, s51
	v_mov_b32_e32 v41, v132
	s_waitcnt vmcnt(0) lgkmcnt(0)
	v_and_b32_e32 v37, 0xffff0000, v6
	v_lshlrev_b32_e32 v36, 16, v6
	v_and_b32_e32 v39, 0xffff0000, v7
	v_lshlrev_b32_e32 v38, 16, v7
	v_pk_mul_f32 v[0:1], v[0:1], v[36:37]
	v_pk_mul_f32 v[2:3], v[2:3], v[38:39]
	v_cvt_pk_bf16_f32 v0, v0, v1
	v_cvt_pk_bf16_f32 v1, v2, v3
	flat_store_dwordx2 v[4:5], v[0:1]
	ds_read_b128 v[0:3], v98 offset:1088
	v_and_b32_e32 v5, 0xffff0000, v10
	v_lshlrev_b32_e32 v4, 16, v10
	v_and_b32_e32 v7, 0xffff0000, v11
	v_lshlrev_b32_e32 v6, 16, v11
	s_waitcnt lgkmcnt(0)
	v_pk_mul_f32 v[0:1], v[0:1], v[4:5]
	v_pk_mul_f32 v[2:3], v[2:3], v[6:7]
	v_cvt_pk_bf16_f32 v0, v0, v1
	v_cvt_pk_bf16_f32 v1, v2, v3
	flat_store_dwordx2 v[8:9], v[0:1]
	ds_read_b128 v[0:3], v98 offset:2176
	v_and_b32_e32 v5, 0xffff0000, v14
	v_lshlrev_b32_e32 v4, 16, v14
	v_and_b32_e32 v7, 0xffff0000, v15
	v_lshlrev_b32_e32 v6, 16, v15
	s_waitcnt lgkmcnt(0)
	v_pk_mul_f32 v[0:1], v[0:1], v[4:5]
	v_pk_mul_f32 v[2:3], v[2:3], v[6:7]
	v_cvt_pk_bf16_f32 v0, v0, v1
	v_cvt_pk_bf16_f32 v1, v2, v3
	flat_store_dwordx2 v[12:13], v[0:1]
	ds_read_b128 v[0:3], v98 offset:3264
	v_and_b32_e32 v5, 0xffff0000, v18
	v_lshlrev_b32_e32 v4, 16, v18
	v_and_b32_e32 v7, 0xffff0000, v19
	v_lshlrev_b32_e32 v6, 16, v19
	s_waitcnt lgkmcnt(0)
	v_pk_mul_f32 v[0:1], v[0:1], v[4:5]
	v_pk_mul_f32 v[2:3], v[2:3], v[6:7]
	v_cvt_pk_bf16_f32 v0, v0, v1
	v_cvt_pk_bf16_f32 v1, v2, v3
	flat_store_dwordx2 v[16:17], v[0:1]
	ds_read_b128 v[0:3], v98 offset:4352
	v_and_b32_e32 v5, 0xffff0000, v22
	v_lshlrev_b32_e32 v4, 16, v22
	v_and_b32_e32 v7, 0xffff0000, v23
	v_lshlrev_b32_e32 v6, 16, v23
	s_waitcnt lgkmcnt(0)
	v_pk_mul_f32 v[0:1], v[0:1], v[4:5]
	v_pk_mul_f32 v[2:3], v[2:3], v[6:7]
	v_cvt_pk_bf16_f32 v0, v0, v1
	v_cvt_pk_bf16_f32 v1, v2, v3
	flat_store_dwordx2 v[20:21], v[0:1]
	ds_read_b128 v[0:3], v98 offset:5440
	v_and_b32_e32 v5, 0xffff0000, v26
	v_lshlrev_b32_e32 v4, 16, v26
	v_and_b32_e32 v7, 0xffff0000, v27
	v_lshlrev_b32_e32 v6, 16, v27
	s_waitcnt lgkmcnt(0)
	v_pk_mul_f32 v[0:1], v[0:1], v[4:5]
	v_pk_mul_f32 v[2:3], v[2:3], v[6:7]
	v_cvt_pk_bf16_f32 v0, v0, v1
	v_cvt_pk_bf16_f32 v1, v2, v3
	flat_store_dwordx2 v[24:25], v[0:1]
	ds_read_b128 v[0:3], v98 offset:6528
	v_and_b32_e32 v5, 0xffff0000, v30
	v_lshlrev_b32_e32 v4, 16, v30
	v_and_b32_e32 v7, 0xffff0000, v31
	v_lshlrev_b32_e32 v6, 16, v31
	s_waitcnt lgkmcnt(0)
	v_pk_mul_f32 v[0:1], v[0:1], v[4:5]
	v_pk_mul_f32 v[2:3], v[2:3], v[6:7]
	v_cvt_pk_bf16_f32 v0, v0, v1
	v_cvt_pk_bf16_f32 v1, v2, v3
	flat_store_dwordx2 v[28:29], v[0:1]
	ds_read_b128 v[0:3], v98 offset:7616
	v_and_b32_e32 v5, 0xffff0000, v34
	v_lshlrev_b32_e32 v4, 16, v34
	v_and_b32_e32 v7, 0xffff0000, v35
	v_lshlrev_b32_e32 v6, 16, v35
	s_waitcnt lgkmcnt(0)
	v_pk_mul_f32 v[0:1], v[0:1], v[4:5]
	v_pk_mul_f32 v[2:3], v[2:3], v[6:7]
	v_cvt_pk_bf16_f32 v0, v0, v1
	v_cvt_pk_bf16_f32 v1, v2, v3
	flat_store_dwordx2 v[32:33], v[0:1]
	ds_read_b64 v[128:129], v40
	s_waitcnt lgkmcnt(0)
	v_lshl_add_u64 v[2:3], v[128:129], 0, s[42:43]
	v_lshlrev_b32_e32 v5, 4, v41
	v_and_b32_e32 v0, 32, v41
	v_lshrrev_b32_e32 v1, 1, v41
	v_bitop3_b32 v0, v5, v0, 48 bitop3:0x6c
	v_bfe_u32 v16, v41, 2, 4
	v_ashrrev_i32_e32 v17, 3, v41
	v_and_b32_e32 v9, 0xfffffc00, v5
	v_and_b32_e32 v18, 32, v1
	v_add_u32_e32 v1, 0x2000, v5
	v_lshrrev_b32_e32 v19, 1, v0
	v_add_u32_e32 v8, 0x4000, v5
	v_add_u32_e32 v5, 0x6000, v5
	v_and_or_b32 v4, v17, s44, v16
	v_ashrrev_i32_e32 v20, 7, v1
	v_or_b32_e32 v10, v19, v18
	v_ashrrev_i32_e32 v21, 7, v8
	v_ashrrev_i32_e32 v22, 7, v5
	v_and_or_b32 v6, v20, s44, v16
	v_lshl_add_u64 v[0:1], v[128:129], 0, s[36:37]
	v_lshl_or_b32 v130, v4, 10, v10
	v_and_or_b32 v8, v21, s44, v16
	v_and_or_b32 v5, v22, s44, v16
	v_add_u32_e32 v151, 0, v9
	v_lshl_or_b32 v4, v6, 10, v10
	v_lshl_add_u64 v[6:7], v[0:1], 0, s[4:5]
	v_lshl_or_b32 v8, v8, 10, v10
	v_lshl_or_b32 v10, v5, 10, v10
	v_add_u32_e32 v5, 0x8000, v151
	v_lshlrev_b64 v[12:13], 1, v[130:131]
	v_readfirstlane_b32 s0, v151
	v_lshl_add_u64 v[14:15], v[6:7], 0, v[12:13]
	s_mov_b32 m0, s0
	v_readfirstlane_b32 s0, v5
	v_mov_b32_e32 v5, v131
	v_add_u32_e32 v9, 0x2000, v151
	global_load_lds_dwordx4 v[14:15], off
	v_lshl_add_u64 v[12:13], v[2:3], 0, v[12:13]
	s_mov_b32 m0, s0
	v_lshlrev_b64 v[4:5], 1, v[4:5]
	v_readfirstlane_b32 s0, v9
	v_add_u32_e32 v9, 0xa000, v151
	global_load_lds_dwordx4 v[12:13], off
	v_lshl_add_u64 v[12:13], v[6:7], 0, v[4:5]
	s_mov_b32 m0, s0
	v_readfirstlane_b32 s0, v9
	global_load_lds_dwordx4 v[12:13], off
	v_lshl_add_u64 v[4:5], v[2:3], 0, v[4:5]
	s_mov_b32 m0, s0
	v_mov_b32_e32 v9, v131
	v_add_u32_e32 v11, 0x4000, v151
	global_load_lds_dwordx4 v[4:5], off
	v_lshlrev_b64 v[4:5], 1, v[8:9]
	v_readfirstlane_b32 s0, v11
	v_lshl_add_u64 v[8:9], v[6:7], 0, v[4:5]
	s_mov_b32 m0, s0
	v_lshl_add_u64 v[4:5], v[2:3], 0, v[4:5]
	global_load_lds_dwordx4 v[8:9], off
	v_add_u32_e32 v8, 0xc000, v151
	v_mov_b32_e32 v11, v131
	v_readfirstlane_b32 s0, v8
	s_mov_b32 m0, s0
	v_add_u32_e32 v8, 0x6000, v151
	global_load_lds_dwordx4 v[4:5], off
	v_lshlrev_b64 v[4:5], 1, v[10:11]
	v_readfirstlane_b32 s0, v8
	v_lshl_add_u64 v[6:7], v[6:7], 0, v[4:5]
	s_mov_b32 m0, s0
	v_lshl_add_u64 v[4:5], v[2:3], 0, v[4:5]
	global_load_lds_dwordx4 v[6:7], off
	v_add_u32_e32 v6, 0xe000, v151
	v_and_b32_e32 v23, 15, v41
	v_readfirstlane_b32 s0, v6
	s_mov_b32 m0, s0
	v_lshlrev_b32_e32 v6, 2, v41
	global_load_lds_dwordx4 v[4:5], off
	v_and_b32_e32 v4, 48, v41
	v_lshlrev_b32_e32 v5, 6, v23
	v_and_b32_e32 v6, 32, v6
	v_bitop3_b32 v152, v5, v6, v4 bitop3:0x36
	v_lshlrev_b32_e32 v5, 7, v41
	v_and_b32_e32 v153, 0x6000, v5
	v_lshlrev_b32_e32 v5, 6, v41
	v_and_b32_e32 v154, 0xffffc000, v5
	v_and_b32_e32 v5, 0x3c0, v5
	v_bitop3_b32 v156, v5, v6, v4 bitop3:0x36
	v_lshlrev_b32_e32 v4, 10, v22
	v_and_or_b32 v4, v4, s45, v19
	v_lshlrev_b32_e32 v10, 10, v16
	v_lshlrev_b32_e32 v6, 10, v21
	v_or3_b32 v130, v4, v10, v18
	v_and_or_b32 v6, v6, s45, v19
	v_lshlrev_b32_e32 v8, 10, v20
	v_lshlrev_b64 v[4:5], 1, v[130:131]
	v_or3_b32 v130, v6, v10, v18
	v_and_or_b32 v8, v8, s45, v19
	v_lshlrev_b32_e32 v11, 10, v17
	v_lshlrev_b64 v[6:7], 1, v[130:131]
	v_or3_b32 v130, v8, v10, v18
	v_and_or_b32 v11, v11, s45, v19
	s_nop 0
	v_lshl_add_u64 v[2:3], v[2:3], 0, s[6:7]
	v_lshlrev_b64 v[8:9], 1, v[130:131]
	v_or3_b32 v130, v11, v10, v18
	v_lshl_add_u64 v[0:1], v[0:1], 0, s[8:9]
	v_lshl_add_u64 v[138:139], v[2:3], 0, v[8:9]
	v_lshlrev_b64 v[10:11], 1, v[130:131]
	v_lshl_add_u64 v[146:147], v[0:1], 0, v[8:9]
	v_mov_b32_e32 v8, 0
	v_or_b32_e32 v155, 0x800, v154
	v_or_b32_e32 v157, 0x1000, v154
	v_or_b32_e32 v158, 0x1800, v154
	v_or_b32_e32 v159, 0x2000, v154
	v_or_b32_e32 v160, 0x2800, v154
	v_or_b32_e32 v161, 0x3000, v154
	v_or_b32_e32 v162, 0x3800, v154
	v_lshl_add_u64 v[134:135], v[2:3], 0, v[4:5]
	v_lshl_add_u64 v[136:137], v[2:3], 0, v[6:7]
	v_lshl_add_u64 v[140:141], v[2:3], 0, v[10:11]
	v_lshl_add_u64 v[142:143], v[0:1], 0, v[4:5]
	v_lshl_add_u64 v[144:145], v[0:1], 0, v[6:7]
	v_lshl_add_u64 v[148:149], v[0:1], 0, v[10:11]
	s_mov_b64 s[42:43], 0
	v_mov_b32_e32 v9, v8
	v_mov_b32_e32 v10, v8
	v_mov_b32_e32 v11, v8
	v_mov_b32_e32 v20, v8
	v_mov_b32_e32 v21, v8
	v_mov_b32_e32 v22, v8
	v_mov_b32_e32 v23, v8
	v_mov_b32_e32 v28, v8
	v_mov_b32_e32 v29, v8
	v_mov_b32_e32 v30, v8
	v_mov_b32_e32 v31, v8
	v_mov_b32_e32 v36, v8
	v_mov_b32_e32 v37, v8
	v_mov_b32_e32 v38, v8
	v_mov_b32_e32 v39, v8
	v_mov_b32_e32 v0, v8
	v_mov_b32_e32 v1, v8
	v_mov_b32_e32 v2, v8
	v_mov_b32_e32 v3, v8
	v_mov_b32_e32 v4, v8
	v_mov_b32_e32 v5, v8
	v_mov_b32_e32 v6, v8
	v_mov_b32_e32 v7, v8
	v_mov_b32_e32 v12, v8
	v_mov_b32_e32 v13, v8
	v_mov_b32_e32 v14, v8
	v_mov_b32_e32 v15, v8
	v_mov_b32_e32 v16, v8
	v_mov_b32_e32 v17, v8
	v_mov_b32_e32 v18, v8
	v_mov_b32_e32 v19, v8
	v_mov_b32_e32 v24, v8
	v_mov_b32_e32 v25, v8
	v_mov_b32_e32 v26, v8
	v_mov_b32_e32 v27, v8
	v_mov_b32_e32 v32, v8
	v_mov_b32_e32 v33, v8
	v_mov_b32_e32 v34, v8
	v_mov_b32_e32 v35, v8
	v_mov_b32_e32 v40, v8
	v_mov_b32_e32 v41, v8
	v_mov_b32_e32 v42, v8
	v_mov_b32_e32 v43, v8
	v_mov_b32_e32 v44, v8
	v_mov_b32_e32 v45, v8
	v_mov_b32_e32 v46, v8
	v_mov_b32_e32 v47, v8
	v_mov_b32_e32 v48, v8
	v_mov_b32_e32 v49, v8
	v_mov_b32_e32 v50, v8
	v_mov_b32_e32 v51, v8
	v_mov_b32_e32 v52, v8
	v_mov_b32_e32 v53, v8
	v_mov_b32_e32 v54, v8
	v_mov_b32_e32 v55, v8
	v_mov_b32_e32 v56, v8
	v_mov_b32_e32 v57, v8
	v_mov_b32_e32 v58, v8
	v_mov_b32_e32 v59, v8
	v_mov_b32_e32 v60, v8
	v_mov_b32_e32 v61, v8
	v_mov_b32_e32 v62, v8
	v_mov_b32_e32 v63, v8
	v_mov_b32_e32 v64, v8
	v_mov_b32_e32 v65, v8
	v_mov_b32_e32 v66, v8
	v_mov_b32_e32 v67, v8
	v_mov_b32_e32 v68, v8
	v_mov_b32_e32 v69, v8
	v_mov_b32_e32 v70, v8
	v_mov_b32_e32 v71, v8
	v_mov_b32_e32 v72, v8
	v_mov_b32_e32 v73, v8
	v_mov_b32_e32 v74, v8
	v_mov_b32_e32 v75, v8
	v_mov_b32_e32 v76, v8
	v_mov_b32_e32 v77, v8
	v_mov_b32_e32 v78, v8
	v_mov_b32_e32 v79, v8
	v_mov_b32_e32 v80, v8
	v_mov_b32_e32 v81, v8
	v_mov_b32_e32 v82, v8
	v_mov_b32_e32 v83, v8
	v_mov_b32_e32 v84, v8
	v_mov_b32_e32 v85, v8
	v_mov_b32_e32 v86, v8
	v_mov_b32_e32 v87, v8
	v_mov_b32_e32 v88, v8
	v_mov_b32_e32 v89, v8
	v_mov_b32_e32 v90, v8
	v_mov_b32_e32 v91, v8
	v_mov_b32_e32 v92, v8
	v_mov_b32_e32 v93, v8
	v_mov_b32_e32 v94, v8
	v_mov_b32_e32 v95, v8
	v_mov_b32_e32 v96, v8
	v_mov_b32_e32 v97, v8
	v_mov_b32_e32 v98, v8
	v_mov_b32_e32 v99, v8
	v_mov_b32_e32 v100, v8
	v_mov_b32_e32 v101, v8
	v_mov_b32_e32 v102, v8
	v_mov_b32_e32 v103, v8
	v_mov_b32_e32 v104, v8
	v_mov_b32_e32 v105, v8
	v_mov_b32_e32 v106, v8
	v_mov_b32_e32 v107, v8
	v_mov_b32_e32 v108, v8
	v_mov_b32_e32 v109, v8
	v_mov_b32_e32 v110, v8
	v_mov_b32_e32 v111, v8
	v_mov_b32_e32 v112, v8
	v_mov_b32_e32 v113, v8
	v_mov_b32_e32 v114, v8
	v_mov_b32_e32 v115, v8
	v_mov_b32_e32 v116, v8
	v_mov_b32_e32 v117, v8
	v_mov_b32_e32 v118, v8
	v_mov_b32_e32 v119, v8
	v_mov_b32_e32 v120, v8
	v_mov_b32_e32 v121, v8
	v_mov_b32_e32 v122, v8
	v_mov_b32_e32 v123, v8
	v_mov_b32_e32 v124, v8
	v_mov_b32_e32 v125, v8
	v_mov_b32_e32 v126, v8
	v_mov_b32_e32 v127, v8
	s_waitcnt vmcnt(0) lgkmcnt(0)
	s_barrier
	v_readfirstlane_b32 s100, v151
	s_and_b32 s0, s29, 0x10000
	s_xor_b32 s53, s0, 0x10000
	s_add_i32 s0, s0, 0
	v_add3_u32 v130, s0, v152, v153
	v_add3_u32 v163, s0, v152, v154
	v_add3_u32 v196, s0, v156, v155
	v_add3_u32 v197, s0, v156, v157
	v_add3_u32 v198, s0, v156, v158
	v_add3_u32 v199, s0, v156, v159
	v_add3_u32 v200, s0, v156, v160
	v_add3_u32 v201, s0, v156, v161
	v_add3_u32 v202, s0, v156, v162
	ds_read_b128 v[180:183], v130 offset:32768
	ds_read_b128 v[164:167], v163
	ds_read_b128 v[168:171], v196
	ds_read_b128 v[172:175], v197
	ds_read_b128 v[176:179], v198
	ds_read_b128 v[184:187], v130 offset:34816
	ds_read_b128 v[188:191], v130 offset:36864
	ds_read_b128 v[192:195], v130 offset:38912
	s_add_i32 s101, s100, s53
	v_readfirstlane_b32 s98, v148
	v_readfirstlane_b32 s99, v149
	v_readfirstlane_b32 vcc_lo, v140
	v_readfirstlane_b32 vcc_hi, v141
	s_sub_u32 s98, s98, 0x1000000
	s_subb_u32 s99, s99, 0
	s_sub_u32 vcc_lo, vcc_lo, 0x1000000
	s_subb_u32 vcc_hi, vcc_hi, 0
	v_subrev_u32_e32 v148, s98, v148
	v_subrev_u32_e32 v140, vcc_lo, v140
	v_subrev_u32_e32 v146, s98, v146
	v_subrev_u32_e32 v138, vcc_lo, v138
	v_subrev_u32_e32 v144, s98, v144
	v_subrev_u32_e32 v136, vcc_lo, v136
	v_subrev_u32_e32 v142, s98, v142
	v_subrev_u32_e32 v134, vcc_lo, v134
	s_mov_b32 m0, s101
	s_nop 0
	global_load_lds_dwordx4 v148, s[98:99]
	s_add_i32 m0, s101, 0x8000
	s_nop 0
	global_load_lds_dwordx4 v140, vcc
	s_add_i32 m0, s101, 0x2000
	s_nop 0
	global_load_lds_dwordx4 v146, s[98:99]
	s_add_i32 m0, s101, 0xa000
	s_nop 0
	global_load_lds_dwordx4 v138, vcc
	s_add_i32 m0, s101, 0x4000
	s_nop 0
	global_load_lds_dwordx4 v144, s[98:99]
	s_add_i32 m0, s101, 0xc000
	s_nop 0
	global_load_lds_dwordx4 v136, vcc
	s_add_i32 m0, s101, 0x6000
	s_nop 0
	global_load_lds_dwordx4 v142, s[98:99]
	s_add_i32 m0, s101, 0xe000
	s_nop 0
	global_load_lds_dwordx4 v134, vcc

.Lex_795:
	s_waitcnt lgkmcnt(0)
	v_add3_u32 v130, s46, v156, v162
	v_add3_u32 v151, s46, v156, v161
	v_add3_u32 v206, s46, v156, v160
	v_add3_u32 v198, s46, v156, v159
	v_add3_u32 v186, s46, v156, v158
	v_add3_u32 v187, s46, v156, v157
	v_add3_u32 v188, s46, v156, v155
	v_add3_u32 v189, s46, v152, v154
	v_add3_u32 v190, s47, v152, v153
	ds_read_b128 v[134:137], v130
	ds_read_b128 v[138:141], v151
	ds_read_b128 v[142:145], v206
	ds_read_b128 v[146:149], v198
	ds_read_b128 v[158:161], v186
	ds_read_b128 v[162:165], v187
	ds_read_b128 v[166:169], v188
	ds_read_b128 v[154:157], v189
	ds_read_b128 v[170:173], v190
	s_waitcnt lgkmcnt(0)
	v_mfma_f32_16x16x32_bf16 v[16:19], v[170:173], v[138:141], v[16:19]
	v_mfma_f32_16x16x32_bf16 v[174:177], v[170:173], v[134:137], v[36:39]
	s_nop 2
	ds_read_b128 v[36:39], v190 offset:2048
	s_waitcnt lgkmcnt(0)
	v_mfma_f32_16x16x32_bf16 v[12:15], v[36:39], v[138:141], v[12:15]
	v_mfma_f32_16x16x32_bf16 v[60:63], v[170:173], v[146:149], v[60:63]
	v_mfma_f32_16x16x32_bf16 v[28:31], v[36:39], v[134:137], v[28:31]
	v_mfma_f32_16x16x32_bf16 v[56:59], v[36:39], v[146:149], v[56:59]
	ds_read_b128 v[178:181], v190 offset:4096
	s_waitcnt lgkmcnt(0)
	v_mfma_f32_16x16x32_bf16 v[182:185], v[178:181], v[134:137], v[20:23]
	v_mfma_f32_16x16x32_bf16 v[52:55], v[178:181], v[146:149], v[52:55]
	s_nop 1
	ds_read_b128 v[20:23], v190 offset:6144
	s_waitcnt lgkmcnt(0)
	v_mfma_f32_16x16x32_bf16 v[134:137], v[20:23], v[134:137], v[8:11]
	v_mfma_f32_16x16x32_bf16 v[8:11], v[20:23], v[154:157], v[112:115]
	v_mfma_f32_16x16x32_bf16 v[112:115], v[20:23], v[158:161], v[64:67]
	v_mfma_f32_16x16x32_bf16 v[64:67], v[178:181], v[154:157], v[116:119]
	v_mfma_f32_16x16x32_bf16 v[116:119], v[178:181], v[158:161], v[68:71]
	v_mfma_f32_16x16x32_bf16 v[68:71], v[36:39], v[154:157], v[120:123]
	v_mfma_f32_16x16x32_bf16 v[120:123], v[36:39], v[158:161], v[72:75]
	v_mfma_f32_16x16x32_bf16 v[72:75], v[170:173], v[154:157], v[124:127]
	v_mfma_f32_16x16x32_bf16 v[124:127], v[170:173], v[158:161], v[76:79]
	v_mfma_f32_16x16x32_bf16 v[48:51], v[20:23], v[146:149], v[48:51]
	v_mfma_f32_16x16x32_bf16 v[146:149], v[170:173], v[142:145], v[44:47]
	v_mfma_f32_16x16x32_bf16 v[152:155], v[36:39], v[142:145], v[40:43]
	v_mfma_f32_16x16x32_bf16 v[156:159], v[178:181], v[142:145], v[32:35]
	v_mfma_f32_16x16x32_bf16 v[24:27], v[20:23], v[142:145], v[24:27]
	v_mfma_f32_16x16x32_bf16 v[142:145], v[178:181], v[138:141], v[4:7]
	v_mfma_f32_16x16x32_bf16 v[108:111], v[170:173], v[166:169], v[108:111]
	v_mfma_f32_16x16x32_bf16 v[92:95], v[170:173], v[162:165], v[92:95]
	v_mfma_f32_16x16x32_bf16 v[104:107], v[36:39], v[166:169], v[104:107]
	v_mfma_f32_16x16x32_bf16 v[88:91], v[36:39], v[162:165], v[88:91]
	v_mfma_f32_16x16x32_bf16 v[100:103], v[178:181], v[166:169], v[100:103]
	v_mfma_f32_16x16x32_bf16 v[84:87], v[178:181], v[162:165], v[84:87]
	v_mfma_f32_16x16x32_bf16 v[96:99], v[20:23], v[166:169], v[96:99]
	v_mfma_f32_16x16x32_bf16 v[80:83], v[20:23], v[162:165], v[80:83]
	v_mfma_f32_16x16x32_bf16 v[20:23], v[20:23], v[138:141], v[0:3]
	ds_read_b128 v[138:141], v190 offset:1024
	ds_read_b128 v[160:163], v190 offset:3072
	ds_read_b128 v[164:167], v190 offset:5120
	ds_read_b128 v[168:171], v190 offset:7168
	ds_read_b128 v[0:3], v189 offset:1024
	ds_read_b128 v[4:7], v188 offset:1024
	ds_read_b128 v[32:35], v187 offset:1024
	ds_read_b128 v[36:39], v186 offset:1024
	s_waitcnt lgkmcnt(3)
	v_mfma_f32_16x16x32_bf16 v[178:181], v[138:141], v[0:3], v[72:75]
	v_mfma_f32_16x16x32_bf16 v[186:189], v[160:163], v[0:3], v[68:71]
	v_mfma_f32_16x16x32_bf16 v[190:193], v[164:167], v[0:3], v[64:67]
	v_mfma_f32_16x16x32_bf16 v[194:197], v[168:171], v[0:3], v[8:11]
	ds_read_b128 v[0:3], v198 offset:1024
	s_waitcnt lgkmcnt(3)
	v_mfma_f32_16x16x32_bf16 v[108:111], v[138:141], v[4:7], v[108:111]
	v_mfma_f32_16x16x32_bf16 v[104:107], v[160:163], v[4:7], v[104:107]
	v_mfma_f32_16x16x32_bf16 v[198:201], v[164:167], v[4:7], v[100:103]
	v_mfma_f32_16x16x32_bf16 v[202:205], v[168:171], v[4:7], v[96:99]
	ds_read_b128 v[4:7], v206 offset:1024
	s_waitcnt lgkmcnt(3)
	v_mfma_f32_16x16x32_bf16 v[64:67], v[138:141], v[32:35], v[92:95]
	v_mfma_f32_16x16x32_bf16 v[68:71], v[160:163], v[32:35], v[88:91]
	v_mfma_f32_16x16x32_bf16 v[72:75], v[164:167], v[32:35], v[84:87]
	v_mfma_f32_16x16x32_bf16 v[76:79], v[168:171], v[32:35], v[80:83]
	ds_read_b128 v[96:99], v151 offset:1024
	s_waitcnt lgkmcnt(3)
	v_mfma_f32_16x16x32_bf16 v[80:83], v[138:141], v[36:39], v[124:127]
	v_mfma_f32_16x16x32_bf16 v[84:87], v[160:163], v[36:39], v[120:123]
	v_mfma_f32_16x16x32_bf16 v[88:91], v[164:167], v[36:39], v[116:119]
	v_mfma_f32_16x16x32_bf16 v[92:95], v[168:171], v[36:39], v[112:115]
	ds_read_b128 v[100:103], v130 offset:1024
	s_waitcnt lgkmcnt(3)
	v_mfma_f32_16x16x32_bf16 v[32:35], v[138:141], v[0:3], v[60:63]
	v_mfma_f32_16x16x32_bf16 v[36:39], v[160:163], v[0:3], v[56:59]
	v_mfma_f32_16x16x32_bf16 v[40:43], v[164:167], v[0:3], v[52:55]
	v_mfma_f32_16x16x32_bf16 v[44:47], v[168:171], v[0:3], v[48:51]
	s_waitcnt lgkmcnt(2)
	v_mfma_f32_16x16x32_bf16 v[48:51], v[138:141], v[4:7], v[146:149]
	v_mfma_f32_16x16x32_bf16 v[52:55], v[160:163], v[4:7], v[152:155]
	v_mfma_f32_16x16x32_bf16 v[56:59], v[164:167], v[4:7], v[156:159]
	v_mfma_f32_16x16x32_bf16 v[60:63], v[168:171], v[4:7], v[24:27]
	s_waitcnt lgkmcnt(1)
	v_mfma_f32_16x16x32_bf16 v[0:3], v[138:141], v[96:99], v[16:19]
	v_mfma_f32_16x16x32_bf16 v[4:7], v[160:163], v[96:99], v[12:15]
	v_mfma_f32_16x16x32_bf16 v[8:11], v[164:167], v[96:99], v[142:145]
	v_mfma_f32_16x16x32_bf16 v[12:15], v[168:171], v[96:99], v[20:23]
	s_waitcnt lgkmcnt(0)
	v_mfma_f32_16x16x32_bf16 v[16:19], v[138:141], v[100:103], v[174:177]
	v_mfma_f32_16x16x32_bf16 v[20:23], v[160:163], v[100:103], v[28:31]
	v_mfma_f32_16x16x32_bf16 v[24:27], v[164:167], v[100:103], v[182:185]
	v_mfma_f32_16x16x32_bf16 v[28:31], v[168:171], v[100:103], v[134:137]
	v_lshrrev_b32_e32 v96, 6, v150
	v_lshlrev_b32_e32 v98, 2, v150
	v_and_b32_e32 v97, 15, v150
	v_mul_lo_u32 v96, v96, s48
	v_and_b32_e32 v112, 60, v98
	v_bfe_u32 v99, v150, 4, 2
	v_add_u32_e32 v96, s46, v96
	v_and_b32_e32 v100, 48, v150
	v_lshlrev_b32_e32 v98, 2, v112
	v_mul_u32_u24_e32 v101, 0x110, v99
	v_mul_u32_u24_e32 v97, 0x110, v97
	v_add3_u32 v98, v96, v98, v101
	v_add3_u32 v101, v96, v100, v97
	s_waitcnt vmcnt(0)
	s_barrier
	ds_write_b128 v101, v[178:181]
	ds_write_b128 v101, v[186:189] offset:64
	ds_write_b128 v101, v[190:193] offset:128
	ds_write_b128 v101, v[194:197] offset:192
	ds_write_b128 v101, v[108:111] offset:4352
	ds_write_b128 v101, v[104:107] offset:4416
	ds_write_b128 v101, v[198:201] offset:4480
	ds_write_b128 v101, v[202:205] offset:4544
	ds_read_b128 v[102:105], v98
	v_ashrrev_i32_e32 v113, 1, v150
	v_and_b32_e32 v96, 0xffffff80, v113
	v_and_or_b32 v106, v150, s49, v112
	v_add_u32_e32 v100, s28, v96
	s_waitcnt lgkmcnt(0)
	v_mul_f32_e32 v102, 0xbfb8aa3b, v102
	v_mul_f32_e32 v103, 0xbfb8aa3b, v103
	v_mul_f32_e32 v104, 0xbfb8aa3b, v104
	v_mul_f32_e32 v105, 0xbfb8aa3b, v105
	v_exp_f32_e32 v102, v102
	v_exp_f32_e32 v103, v103
	v_exp_f32_e32 v104, v104
	v_exp_f32_e32 v105, v105
	v_add_f32_e32 v102, 1.0, v102
	v_add_f32_e32 v103, 1.0, v103
	v_add_f32_e32 v104, 1.0, v104
	v_add_f32_e32 v105, 1.0, v105
	v_rcp_f32_e32 v102, v102
	v_rcp_f32_e32 v103, v103
	v_rcp_f32_e32 v104, v104
	v_rcp_f32_e32 v105, v105
	v_lshl_add_u64 v[96:97], v[128:129], 0, s[38:39]
	v_lshlrev_b32_e32 v130, 1, v106
	v_cvt_pk_bf16_f32 v102, v102, v103
	v_cvt_pk_bf16_f32 v103, v104, v105
	v_or_b32_e32 v104, v100, v99
	v_lshl_add_u64 v[96:97], v[96:97], 0, v[130:131]
	v_ashrrev_i32_e32 v105, 31, v104
	v_lshl_add_u64 v[96:97], v[96:97], 0, s[26:27]
	v_lshlrev_b64 v[104:105], 11, v[104:105]
	v_lshl_add_u64 v[104:105], v[96:97], 0, v[104:105]
	flat_store_dwordx2 v[104:105], v[102:103]
	ds_read_b128 v[102:105], v98 offset:1088
	v_mov_b32_e32 v150, v132
	s_waitcnt lgkmcnt(0)
	v_mul_f32_e32 v102, 0xbfb8aa3b, v102
	v_exp_f32_e32 v102, v102
	v_mul_f32_e32 v103, 0xbfb8aa3b, v103
	v_exp_f32_e32 v103, v103
	v_add_f32_e32 v102, 1.0, v102
	v_rcp_f32_e32 v106, v102
	v_add_f32_e32 v102, 1.0, v103
	v_mul_f32_e32 v103, 0xbfb8aa3b, v104
	v_exp_f32_e32 v103, v103
	v_mul_f32_e32 v104, 0xbfb8aa3b, v105
	v_exp_f32_e32 v104, v104
	v_rcp_f32_e32 v105, v102
	v_add_f32_e32 v102, 1.0, v103
	v_rcp_f32_e32 v103, v102
	v_add_f32_e32 v102, 1.0, v104
	v_rcp_f32_e32 v107, v102
	v_or_b32_e32 v102, 4, v99
	v_cvt_pk_bf16_f32 v104, v106, v105
	v_or_b32_e32 v106, v100, v102
	v_cvt_pk_bf16_f32 v105, v103, v107
	v_ashrrev_i32_e32 v107, 31, v106
	v_lshlrev_b64 v[106:107], 11, v[106:107]
	v_lshl_add_u64 v[106:107], v[96:97], 0, v[106:107]
	flat_store_dwordx2 v[106:107], v[104:105]
	ds_read_b128 v[104:107], v98 offset:2176
	s_waitcnt lgkmcnt(0)
	v_mul_f32_e32 v103, 0xbfb8aa3b, v104
	v_exp_f32_e32 v103, v103
	v_mul_f32_e32 v104, 0xbfb8aa3b, v105
	v_exp_f32_e32 v104, v104
	v_add_f32_e32 v103, 1.0, v103
	v_rcp_f32_e32 v105, v103
	v_add_f32_e32 v103, 1.0, v104
	v_mul_f32_e32 v104, 0xbfb8aa3b, v106
	v_exp_f32_e32 v104, v104
	v_mul_f32_e32 v106, 0xbfb8aa3b, v107
	v_exp_f32_e32 v106, v106
	v_rcp_f32_e32 v107, v103
	v_add_f32_e32 v103, 1.0, v104
	v_rcp_f32_e32 v108, v103
	v_add_f32_e32 v103, 1.0, v106
	v_rcp_f32_e32 v106, v103
	v_or_b32_e32 v103, 8, v99
	v_cvt_pk_bf16_f32 v104, v105, v107
	v_cvt_pk_bf16_f32 v105, v108, v106
	v_or_b32_e32 v106, v100, v103
	v_ashrrev_i32_e32 v107, 31, v106
	v_lshlrev_b64 v[106:107], 11, v[106:107]
	v_lshl_add_u64 v[106:107], v[96:97], 0, v[106:107]
	flat_store_dwordx2 v[106:107], v[104:105]
	ds_read_b128 v[104:107], v98 offset:3264
	s_waitcnt lgkmcnt(0)
	v_mul_f32_e32 v104, 0xbfb8aa3b, v104
	v_exp_f32_e32 v104, v104
	v_mul_f32_e32 v105, 0xbfb8aa3b, v105
	v_exp_f32_e32 v105, v105
	v_add_f32_e32 v104, 1.0, v104
	v_rcp_f32_e32 v108, v104
	v_add_f32_e32 v104, 1.0, v105
	v_mul_f32_e32 v105, 0xbfb8aa3b, v106
	v_exp_f32_e32 v105, v105
	v_mul_f32_e32 v106, 0xbfb8aa3b, v107
	v_exp_f32_e32 v106, v106
	v_rcp_f32_e32 v107, v104
	v_add_f32_e32 v104, 1.0, v105
	v_rcp_f32_e32 v105, v104
	v_add_f32_e32 v104, 1.0, v106
	v_rcp_f32_e32 v109, v104
	v_or_b32_e32 v104, 12, v99
	v_cvt_pk_bf16_f32 v106, v108, v107
	v_or_b32_e32 v108, v100, v104
	v_cvt_pk_bf16_f32 v107, v105, v109
	v_ashrrev_i32_e32 v109, 31, v108
	v_lshlrev_b64 v[108:109], 11, v[108:109]
	v_lshl_add_u64 v[108:109], v[96:97], 0, v[108:109]
	flat_store_dwordx2 v[108:109], v[106:107]
	ds_read_b128 v[106:109], v98 offset:4352
	s_waitcnt lgkmcnt(0)
	v_mul_f32_e32 v105, 0xbfb8aa3b, v106
	v_exp_f32_e32 v105, v105
	v_mul_f32_e32 v106, 0xbfb8aa3b, v107
	v_exp_f32_e32 v106, v106
	v_add_f32_e32 v105, 1.0, v105
	v_rcp_f32_e32 v107, v105
	v_add_f32_e32 v105, 1.0, v106
	v_mul_f32_e32 v106, 0xbfb8aa3b, v108
	v_exp_f32_e32 v106, v106
	v_mul_f32_e32 v108, 0xbfb8aa3b, v109
	v_exp_f32_e32 v108, v108
	v_rcp_f32_e32 v109, v105
	v_add_f32_e32 v105, 1.0, v106
	v_rcp_f32_e32 v110, v105
	v_add_f32_e32 v105, 1.0, v108
	v_rcp_f32_e32 v108, v105
	v_or_b32_e32 v105, 16, v99
	v_cvt_pk_bf16_f32 v106, v107, v109
	v_cvt_pk_bf16_f32 v107, v110, v108
	v_or_b32_e32 v108, v100, v105
	v_ashrrev_i32_e32 v109, 31, v108
	v_lshlrev_b64 v[108:109], 11, v[108:109]
	v_lshl_add_u64 v[108:109], v[96:97], 0, v[108:109]
	flat_store_dwordx2 v[108:109], v[106:107]
	ds_read_b128 v[106:109], v98 offset:5440
	s_waitcnt lgkmcnt(0)
	v_mul_f32_e32 v106, 0xbfb8aa3b, v106
	v_exp_f32_e32 v106, v106
	v_mul_f32_e32 v107, 0xbfb8aa3b, v107
	v_exp_f32_e32 v107, v107
	v_add_f32_e32 v106, 1.0, v106
	v_rcp_f32_e32 v110, v106
	v_add_f32_e32 v106, 1.0, v107
	v_mul_f32_e32 v107, 0xbfb8aa3b, v108
	v_exp_f32_e32 v107, v107
	v_mul_f32_e32 v108, 0xbfb8aa3b, v109
	v_exp_f32_e32 v108, v108
	v_rcp_f32_e32 v109, v106
	v_add_f32_e32 v106, 1.0, v107
	v_rcp_f32_e32 v107, v106
	v_add_f32_e32 v106, 1.0, v108
	v_rcp_f32_e32 v111, v106
	v_or_b32_e32 v106, 20, v99
	v_cvt_pk_bf16_f32 v108, v110, v109
	v_or_b32_e32 v110, v100, v106
	v_cvt_pk_bf16_f32 v109, v107, v111
	v_ashrrev_i32_e32 v111, 31, v110
	v_lshlrev_b64 v[110:111], 11, v[110:111]
	v_lshl_add_u64 v[110:111], v[96:97], 0, v[110:111]
	flat_store_dwordx2 v[110:111], v[108:109]
	ds_read_b128 v[108:111], v98 offset:6528
	s_waitcnt lgkmcnt(0)
	v_mul_f32_e32 v107, 0xbfb8aa3b, v108
	v_exp_f32_e32 v107, v107
	v_mul_f32_e32 v108, 0xbfb8aa3b, v109
	v_exp_f32_e32 v108, v108
	v_add_f32_e32 v107, 1.0, v107
	v_rcp_f32_e32 v109, v107
	v_add_f32_e32 v107, 1.0, v108
	v_mul_f32_e32 v108, 0xbfb8aa3b, v110
	v_exp_f32_e32 v108, v108
	v_mul_f32_e32 v110, 0xbfb8aa3b, v111
	v_exp_f32_e32 v110, v110
	v_rcp_f32_e32 v111, v107
	v_add_f32_e32 v107, 1.0, v108
	v_rcp_f32_e32 v112, v107
	v_add_f32_e32 v107, 1.0, v110
	v_rcp_f32_e32 v110, v107
	v_or_b32_e32 v107, 24, v99
	v_cvt_pk_bf16_f32 v108, v109, v111
	v_cvt_pk_bf16_f32 v109, v112, v110
	v_or_b32_e32 v110, v100, v107
	v_ashrrev_i32_e32 v111, 31, v110
	v_lshlrev_b64 v[110:111], 11, v[110:111]
	v_lshl_add_u64 v[110:111], v[96:97], 0, v[110:111]
	flat_store_dwordx2 v[110:111], v[108:109]
	ds_read_b128 v[108:111], v98 offset:7616
	s_waitcnt lgkmcnt(0)
	v_mul_f32_e32 v108, 0xbfb8aa3b, v108
	v_exp_f32_e32 v108, v108
	v_mul_f32_e32 v109, 0xbfb8aa3b, v109
	v_exp_f32_e32 v109, v109
	v_add_f32_e32 v108, 1.0, v108
	v_rcp_f32_e32 v112, v108
	v_add_f32_e32 v108, 1.0, v109
	v_mul_f32_e32 v109, 0xbfb8aa3b, v110
	v_exp_f32_e32 v109, v109
	v_mul_f32_e32 v110, 0xbfb8aa3b, v111
	v_exp_f32_e32 v110, v110
	v_rcp_f32_e32 v111, v108
	v_add_f32_e32 v108, 1.0, v109
	v_rcp_f32_e32 v109, v108
	v_add_f32_e32 v108, 1.0, v110
	v_rcp_f32_e32 v113, v108
	v_or_b32_e32 v108, 28, v99
	v_cvt_pk_bf16_f32 v110, v112, v111
	v_or_b32_e32 v112, v100, v108
	v_cvt_pk_bf16_f32 v111, v109, v113
	v_ashrrev_i32_e32 v113, 31, v112
	v_lshlrev_b64 v[112:113], 11, v[112:113]
	v_lshl_add_u64 v[112:113], v[96:97], 0, v[112:113]
	flat_store_dwordx2 v[112:113], v[110:111]
	ds_write_b128 v101, v[64:67]
	ds_write_b128 v101, v[68:71] offset:64
	ds_write_b128 v101, v[72:75] offset:128
	ds_write_b128 v101, v[76:79] offset:192
	ds_write_b128 v101, v[80:83] offset:4352
	ds_write_b128 v101, v[84:87] offset:4416
	ds_write_b128 v101, v[88:91] offset:4480
	ds_write_b128 v101, v[92:95] offset:4544
	ds_read_b128 v[64:67], v98
	v_or_b32_e32 v68, 32, v100
	s_waitcnt lgkmcnt(0)
	v_mul_f32_e32 v64, 0xbfb8aa3b, v64
	v_mul_f32_e32 v65, 0xbfb8aa3b, v65
	v_mul_f32_e32 v66, 0xbfb8aa3b, v66
	v_mul_f32_e32 v67, 0xbfb8aa3b, v67
	v_exp_f32_e32 v64, v64
	v_exp_f32_e32 v65, v65
	v_exp_f32_e32 v66, v66
	v_exp_f32_e32 v67, v67
	v_add_f32_e32 v64, 1.0, v64
	v_add_f32_e32 v65, 1.0, v65
	v_add_f32_e32 v66, 1.0, v66
	v_add_f32_e32 v67, 1.0, v67
	v_rcp_f32_e32 v64, v64
	v_rcp_f32_e32 v65, v65
	v_rcp_f32_e32 v66, v66
	v_rcp_f32_e32 v67, v67
	v_cvt_pk_bf16_f32 v64, v64, v65
	v_cvt_pk_bf16_f32 v65, v66, v67
	v_or_b32_e32 v66, v68, v99
	v_ashrrev_i32_e32 v67, 31, v66
	v_lshlrev_b64 v[66:67], 11, v[66:67]
	v_lshl_add_u64 v[66:67], v[96:97], 0, v[66:67]
	flat_store_dwordx2 v[66:67], v[64:65]
	ds_read_b128 v[64:67], v98 offset:1088
	s_waitcnt lgkmcnt(0)
	v_mul_f32_e32 v64, 0xbfb8aa3b, v64
	v_mul_f32_e32 v65, 0xbfb8aa3b, v65
	v_mul_f32_e32 v66, 0xbfb8aa3b, v66
	v_mul_f32_e32 v67, 0xbfb8aa3b, v67
	v_exp_f32_e32 v64, v64
	v_exp_f32_e32 v65, v65
	v_exp_f32_e32 v66, v66
	v_exp_f32_e32 v67, v67
	v_add_f32_e32 v64, 1.0, v64
	v_add_f32_e32 v65, 1.0, v65
	v_add_f32_e32 v66, 1.0, v66
	v_add_f32_e32 v67, 1.0, v67
	v_rcp_f32_e32 v64, v64
	v_rcp_f32_e32 v65, v65
	v_rcp_f32_e32 v66, v66
	v_rcp_f32_e32 v67, v67
	v_cvt_pk_bf16_f32 v64, v64, v65
	v_cvt_pk_bf16_f32 v65, v66, v67
	v_or_b32_e32 v66, v68, v102
	v_ashrrev_i32_e32 v67, 31, v66
	v_lshlrev_b64 v[66:67], 11, v[66:67]
	v_lshl_add_u64 v[66:67], v[96:97], 0, v[66:67]
	flat_store_dwordx2 v[66:67], v[64:65]
	ds_read_b128 v[64:67], v98 offset:2176
	s_waitcnt lgkmcnt(0)
	v_mul_f32_e32 v64, 0xbfb8aa3b, v64
	v_mul_f32_e32 v65, 0xbfb8aa3b, v65
	v_mul_f32_e32 v66, 0xbfb8aa3b, v66
	v_mul_f32_e32 v67, 0xbfb8aa3b, v67
	v_exp_f32_e32 v64, v64
	v_exp_f32_e32 v65, v65
	v_exp_f32_e32 v66, v66
	v_exp_f32_e32 v67, v67
	v_add_f32_e32 v64, 1.0, v64
	v_add_f32_e32 v65, 1.0, v65
	v_add_f32_e32 v66, 1.0, v66
	v_add_f32_e32 v67, 1.0, v67
	v_rcp_f32_e32 v64, v64
	v_rcp_f32_e32 v65, v65
	v_rcp_f32_e32 v66, v66
	v_rcp_f32_e32 v67, v67
	v_cvt_pk_bf16_f32 v64, v64, v65
	v_cvt_pk_bf16_f32 v65, v66, v67
	v_or_b32_e32 v66, v68, v103
	v_ashrrev_i32_e32 v67, 31, v66
	v_lshlrev_b64 v[66:67], 11, v[66:67]
	v_lshl_add_u64 v[66:67], v[96:97], 0, v[66:67]
	flat_store_dwordx2 v[66:67], v[64:65]
	ds_read_b128 v[64:67], v98 offset:3264
	s_waitcnt lgkmcnt(0)
	v_mul_f32_e32 v64, 0xbfb8aa3b, v64
	v_mul_f32_e32 v65, 0xbfb8aa3b, v65
	v_mul_f32_e32 v66, 0xbfb8aa3b, v66
	v_mul_f32_e32 v67, 0xbfb8aa3b, v67
	v_exp_f32_e32 v64, v64
	v_exp_f32_e32 v65, v65
	v_exp_f32_e32 v66, v66
	v_exp_f32_e32 v67, v67
	v_add_f32_e32 v64, 1.0, v64
	v_add_f32_e32 v65, 1.0, v65
	v_add_f32_e32 v66, 1.0, v66
	v_add_f32_e32 v67, 1.0, v67
	v_rcp_f32_e32 v64, v64
	v_rcp_f32_e32 v65, v65
	v_rcp_f32_e32 v66, v66
	v_rcp_f32_e32 v67, v67
	v_cvt_pk_bf16_f32 v64, v64, v65
	v_cvt_pk_bf16_f32 v65, v66, v67
	v_or_b32_e32 v66, v68, v104
	v_ashrrev_i32_e32 v67, 31, v66
	v_lshlrev_b64 v[66:67], 11, v[66:67]
	v_lshl_add_u64 v[66:67], v[96:97], 0, v[66:67]
	flat_store_dwordx2 v[66:67], v[64:65]
	ds_read_b128 v[64:67], v98 offset:4352
	s_waitcnt lgkmcnt(0)
	v_mul_f32_e32 v64, 0xbfb8aa3b, v64
	v_mul_f32_e32 v65, 0xbfb8aa3b, v65
	v_mul_f32_e32 v66, 0xbfb8aa3b, v66
	v_mul_f32_e32 v67, 0xbfb8aa3b, v67
	v_exp_f32_e32 v64, v64
	v_exp_f32_e32 v65, v65
	v_exp_f32_e32 v66, v66
	v_exp_f32_e32 v67, v67
	v_add_f32_e32 v64, 1.0, v64
	v_add_f32_e32 v65, 1.0, v65
	v_add_f32_e32 v66, 1.0, v66
	v_add_f32_e32 v67, 1.0, v67
	v_rcp_f32_e32 v64, v64
	v_rcp_f32_e32 v65, v65
	v_rcp_f32_e32 v66, v66
	v_rcp_f32_e32 v67, v67
	v_cvt_pk_bf16_f32 v64, v64, v65
	v_cvt_pk_bf16_f32 v65, v66, v67
	v_or_b32_e32 v66, v68, v105
	v_ashrrev_i32_e32 v67, 31, v66
	v_lshlrev_b64 v[66:67], 11, v[66:67]
	v_lshl_add_u64 v[66:67], v[96:97], 0, v[66:67]
	flat_store_dwordx2 v[66:67], v[64:65]
	ds_read_b128 v[64:67], v98 offset:5440
	s_waitcnt lgkmcnt(0)
	v_mul_f32_e32 v64, 0xbfb8aa3b, v64
	v_mul_f32_e32 v65, 0xbfb8aa3b, v65
	v_mul_f32_e32 v66, 0xbfb8aa3b, v66
	v_mul_f32_e32 v67, 0xbfb8aa3b, v67
	v_exp_f32_e32 v64, v64
	v_exp_f32_e32 v65, v65
	v_exp_f32_e32 v66, v66
	v_exp_f32_e32 v67, v67
	v_add_f32_e32 v64, 1.0, v64
	v_add_f32_e32 v65, 1.0, v65
	v_add_f32_e32 v66, 1.0, v66
	v_add_f32_e32 v67, 1.0, v67
	v_rcp_f32_e32 v64, v64
	v_rcp_f32_e32 v65, v65
	v_rcp_f32_e32 v66, v66
	v_rcp_f32_e32 v67, v67
	v_cvt_pk_bf16_f32 v64, v64, v65
	v_cvt_pk_bf16_f32 v65, v66, v67
	v_or_b32_e32 v66, v68, v106
	v_ashrrev_i32_e32 v67, 31, v66
	v_lshlrev_b64 v[66:67], 11, v[66:67]
	v_lshl_add_u64 v[66:67], v[96:97], 0, v[66:67]
	flat_store_dwordx2 v[66:67], v[64:65]
	ds_read_b128 v[64:67], v98 offset:6528
	s_waitcnt lgkmcnt(0)
	v_mul_f32_e32 v64, 0xbfb8aa3b, v64
	v_mul_f32_e32 v65, 0xbfb8aa3b, v65
	v_mul_f32_e32 v66, 0xbfb8aa3b, v66
	v_mul_f32_e32 v67, 0xbfb8aa3b, v67
	v_exp_f32_e32 v64, v64
	v_exp_f32_e32 v65, v65
	v_exp_f32_e32 v66, v66
	v_exp_f32_e32 v67, v67
	v_add_f32_e32 v64, 1.0, v64
	v_add_f32_e32 v65, 1.0, v65
	v_add_f32_e32 v66, 1.0, v66
	v_add_f32_e32 v67, 1.0, v67
	v_rcp_f32_e32 v64, v64
	v_rcp_f32_e32 v65, v65
	v_rcp_f32_e32 v66, v66
	v_rcp_f32_e32 v67, v67
	v_cvt_pk_bf16_f32 v64, v64, v65
	v_cvt_pk_bf16_f32 v65, v66, v67
	v_or_b32_e32 v66, v68, v107
	v_ashrrev_i32_e32 v67, 31, v66
	v_lshlrev_b64 v[66:67], 11, v[66:67]
	v_lshl_add_u64 v[66:67], v[96:97], 0, v[66:67]
	flat_store_dwordx2 v[66:67], v[64:65]
	ds_read_b128 v[64:67], v98 offset:7616
	s_waitcnt lgkmcnt(0)
	v_mul_f32_e32 v64, 0xbfb8aa3b, v64
	v_mul_f32_e32 v65, 0xbfb8aa3b, v65
	v_mul_f32_e32 v66, 0xbfb8aa3b, v66
	v_mul_f32_e32 v67, 0xbfb8aa3b, v67
	v_exp_f32_e32 v64, v64
	v_exp_f32_e32 v65, v65
	v_exp_f32_e32 v66, v66
	v_exp_f32_e32 v67, v67
	v_add_f32_e32 v64, 1.0, v64
	v_add_f32_e32 v65, 1.0, v65
	v_add_f32_e32 v66, 1.0, v66
	v_add_f32_e32 v67, 1.0, v67
	v_rcp_f32_e32 v64, v64
	v_rcp_f32_e32 v65, v65
	v_rcp_f32_e32 v66, v66
	v_rcp_f32_e32 v67, v67
	v_cvt_pk_bf16_f32 v64, v64, v65
	v_cvt_pk_bf16_f32 v65, v66, v67
	v_or_b32_e32 v66, v68, v108
	v_ashrrev_i32_e32 v67, 31, v66
	v_lshlrev_b64 v[66:67], 11, v[66:67]
	v_lshl_add_u64 v[66:67], v[96:97], 0, v[66:67]
	flat_store_dwordx2 v[66:67], v[64:65]
	ds_write_b128 v101, v[32:35]
	ds_write_b128 v101, v[36:39] offset:64
	ds_write_b128 v101, v[40:43] offset:128
	ds_write_b128 v101, v[44:47] offset:192
	ds_write_b128 v101, v[48:51] offset:4352
	ds_write_b128 v101, v[52:55] offset:4416
	ds_write_b128 v101, v[56:59] offset:4480
	ds_write_b128 v101, v[60:63] offset:4544
	ds_read_b128 v[32:35], v98
	v_or_b32_e32 v36, 64, v100
	s_waitcnt lgkmcnt(0)
	v_mul_f32_e32 v32, 0xbfb8aa3b, v32
	v_mul_f32_e32 v33, 0xbfb8aa3b, v33
	v_mul_f32_e32 v34, 0xbfb8aa3b, v34
	v_mul_f32_e32 v35, 0xbfb8aa3b, v35
	v_exp_f32_e32 v32, v32
	v_exp_f32_e32 v33, v33
	v_exp_f32_e32 v34, v34
	v_exp_f32_e32 v35, v35
	v_add_f32_e32 v32, 1.0, v32
	v_add_f32_e32 v33, 1.0, v33
	v_add_f32_e32 v34, 1.0, v34
	v_add_f32_e32 v35, 1.0, v35
	v_rcp_f32_e32 v32, v32
	v_rcp_f32_e32 v33, v33
	v_rcp_f32_e32 v34, v34
	v_rcp_f32_e32 v35, v35
	v_cvt_pk_bf16_f32 v32, v32, v33
	v_cvt_pk_bf16_f32 v33, v34, v35
	v_or_b32_e32 v34, v36, v99
	v_ashrrev_i32_e32 v35, 31, v34
	v_lshlrev_b64 v[34:35], 11, v[34:35]
	v_lshl_add_u64 v[34:35], v[96:97], 0, v[34:35]
	flat_store_dwordx2 v[34:35], v[32:33]
	ds_read_b128 v[32:35], v98 offset:1088
	s_waitcnt lgkmcnt(0)
	v_mul_f32_e32 v32, 0xbfb8aa3b, v32
	v_mul_f32_e32 v33, 0xbfb8aa3b, v33
	v_mul_f32_e32 v34, 0xbfb8aa3b, v34
	v_mul_f32_e32 v35, 0xbfb8aa3b, v35
	v_exp_f32_e32 v32, v32
	v_exp_f32_e32 v33, v33
	v_exp_f32_e32 v34, v34
	v_exp_f32_e32 v35, v35
	v_add_f32_e32 v32, 1.0, v32
	v_add_f32_e32 v33, 1.0, v33
	v_add_f32_e32 v34, 1.0, v34
	v_add_f32_e32 v35, 1.0, v35
	v_rcp_f32_e32 v32, v32
	v_rcp_f32_e32 v33, v33
	v_rcp_f32_e32 v34, v34
	v_rcp_f32_e32 v35, v35
	v_cvt_pk_bf16_f32 v32, v32, v33
	v_cvt_pk_bf16_f32 v33, v34, v35
	v_or_b32_e32 v34, v36, v102
	v_ashrrev_i32_e32 v35, 31, v34
	v_lshlrev_b64 v[34:35], 11, v[34:35]
	v_lshl_add_u64 v[34:35], v[96:97], 0, v[34:35]
	flat_store_dwordx2 v[34:35], v[32:33]
	ds_read_b128 v[32:35], v98 offset:2176
	s_waitcnt lgkmcnt(0)
	v_mul_f32_e32 v32, 0xbfb8aa3b, v32
	v_mul_f32_e32 v33, 0xbfb8aa3b, v33
	v_mul_f32_e32 v34, 0xbfb8aa3b, v34
	v_mul_f32_e32 v35, 0xbfb8aa3b, v35
	v_exp_f32_e32 v32, v32
	v_exp_f32_e32 v33, v33
	v_exp_f32_e32 v34, v34
	v_exp_f32_e32 v35, v35
	v_add_f32_e32 v32, 1.0, v32
	v_add_f32_e32 v33, 1.0, v33
	v_add_f32_e32 v34, 1.0, v34
	v_add_f32_e32 v35, 1.0, v35
	v_rcp_f32_e32 v32, v32
	v_rcp_f32_e32 v33, v33
	v_rcp_f32_e32 v34, v34
	v_rcp_f32_e32 v35, v35
	v_cvt_pk_bf16_f32 v32, v32, v33
	v_cvt_pk_bf16_f32 v33, v34, v35
	v_or_b32_e32 v34, v36, v103
	v_ashrrev_i32_e32 v35, 31, v34
	v_lshlrev_b64 v[34:35], 11, v[34:35]
	v_lshl_add_u64 v[34:35], v[96:97], 0, v[34:35]
	flat_store_dwordx2 v[34:35], v[32:33]
	ds_read_b128 v[32:35], v98 offset:3264
	s_waitcnt lgkmcnt(0)
	v_mul_f32_e32 v32, 0xbfb8aa3b, v32
	v_mul_f32_e32 v33, 0xbfb8aa3b, v33
	v_mul_f32_e32 v34, 0xbfb8aa3b, v34
	v_mul_f32_e32 v35, 0xbfb8aa3b, v35
	v_exp_f32_e32 v32, v32
	v_exp_f32_e32 v33, v33
	v_exp_f32_e32 v34, v34
	v_exp_f32_e32 v35, v35
	v_add_f32_e32 v32, 1.0, v32
	v_add_f32_e32 v33, 1.0, v33
	v_add_f32_e32 v34, 1.0, v34
	v_add_f32_e32 v35, 1.0, v35
	v_rcp_f32_e32 v32, v32
	v_rcp_f32_e32 v33, v33
	v_rcp_f32_e32 v34, v34
	v_rcp_f32_e32 v35, v35
	v_cvt_pk_bf16_f32 v32, v32, v33
	v_cvt_pk_bf16_f32 v33, v34, v35
	v_or_b32_e32 v34, v36, v104
	v_ashrrev_i32_e32 v35, 31, v34
	v_lshlrev_b64 v[34:35], 11, v[34:35]
	v_lshl_add_u64 v[34:35], v[96:97], 0, v[34:35]
	flat_store_dwordx2 v[34:35], v[32:33]
	ds_read_b128 v[32:35], v98 offset:4352
	s_waitcnt lgkmcnt(0)
	v_mul_f32_e32 v32, 0xbfb8aa3b, v32
	v_mul_f32_e32 v33, 0xbfb8aa3b, v33
	v_mul_f32_e32 v34, 0xbfb8aa3b, v34
	v_mul_f32_e32 v35, 0xbfb8aa3b, v35
	v_exp_f32_e32 v32, v32
	v_exp_f32_e32 v33, v33
	v_exp_f32_e32 v34, v34
	v_exp_f32_e32 v35, v35
	v_add_f32_e32 v32, 1.0, v32
	v_add_f32_e32 v33, 1.0, v33
	v_add_f32_e32 v34, 1.0, v34
	v_add_f32_e32 v35, 1.0, v35
	v_rcp_f32_e32 v32, v32
	v_rcp_f32_e32 v33, v33
	v_rcp_f32_e32 v34, v34
	v_rcp_f32_e32 v35, v35
	v_cvt_pk_bf16_f32 v32, v32, v33
	v_cvt_pk_bf16_f32 v33, v34, v35
	v_or_b32_e32 v34, v36, v105
	v_ashrrev_i32_e32 v35, 31, v34
	v_lshlrev_b64 v[34:35], 11, v[34:35]
	v_lshl_add_u64 v[34:35], v[96:97], 0, v[34:35]
	flat_store_dwordx2 v[34:35], v[32:33]
	ds_read_b128 v[32:35], v98 offset:5440
	s_waitcnt lgkmcnt(0)
	v_mul_f32_e32 v32, 0xbfb8aa3b, v32
	v_mul_f32_e32 v33, 0xbfb8aa3b, v33
	v_mul_f32_e32 v34, 0xbfb8aa3b, v34
	v_mul_f32_e32 v35, 0xbfb8aa3b, v35
	v_exp_f32_e32 v32, v32
	v_exp_f32_e32 v33, v33
	v_exp_f32_e32 v34, v34
	v_exp_f32_e32 v35, v35
	v_add_f32_e32 v32, 1.0, v32
	v_add_f32_e32 v33, 1.0, v33
	v_add_f32_e32 v34, 1.0, v34
	v_add_f32_e32 v35, 1.0, v35
	v_rcp_f32_e32 v32, v32
	v_rcp_f32_e32 v33, v33
	v_rcp_f32_e32 v34, v34
	v_rcp_f32_e32 v35, v35
	v_cvt_pk_bf16_f32 v32, v32, v33
	v_cvt_pk_bf16_f32 v33, v34, v35
	v_or_b32_e32 v34, v36, v106
	v_ashrrev_i32_e32 v35, 31, v34
	v_lshlrev_b64 v[34:35], 11, v[34:35]
	v_lshl_add_u64 v[34:35], v[96:97], 0, v[34:35]
	flat_store_dwordx2 v[34:35], v[32:33]
	ds_read_b128 v[32:35], v98 offset:6528
	s_waitcnt lgkmcnt(0)
	v_mul_f32_e32 v32, 0xbfb8aa3b, v32
	v_mul_f32_e32 v33, 0xbfb8aa3b, v33
	v_mul_f32_e32 v34, 0xbfb8aa3b, v34
	v_mul_f32_e32 v35, 0xbfb8aa3b, v35
	v_exp_f32_e32 v32, v32
	v_exp_f32_e32 v33, v33
	v_exp_f32_e32 v34, v34
	v_exp_f32_e32 v35, v35
	v_add_f32_e32 v32, 1.0, v32
	v_add_f32_e32 v33, 1.0, v33
	v_add_f32_e32 v34, 1.0, v34
	v_add_f32_e32 v35, 1.0, v35
	v_rcp_f32_e32 v32, v32
	v_rcp_f32_e32 v33, v33
	v_rcp_f32_e32 v34, v34
	v_rcp_f32_e32 v35, v35
	v_cvt_pk_bf16_f32 v32, v32, v33
	v_cvt_pk_bf16_f32 v33, v34, v35
	v_or_b32_e32 v34, v36, v107
	v_ashrrev_i32_e32 v35, 31, v34
	v_lshlrev_b64 v[34:35], 11, v[34:35]
	v_lshl_add_u64 v[34:35], v[96:97], 0, v[34:35]
	flat_store_dwordx2 v[34:35], v[32:33]
	ds_read_b128 v[32:35], v98 offset:7616
	s_waitcnt lgkmcnt(0)
	v_mul_f32_e32 v32, 0xbfb8aa3b, v32
	v_mul_f32_e32 v33, 0xbfb8aa3b, v33
	v_mul_f32_e32 v34, 0xbfb8aa3b, v34
	v_mul_f32_e32 v35, 0xbfb8aa3b, v35
	v_exp_f32_e32 v32, v32
	v_exp_f32_e32 v33, v33
	v_exp_f32_e32 v34, v34
	v_exp_f32_e32 v35, v35
	v_add_f32_e32 v32, 1.0, v32
	v_add_f32_e32 v33, 1.0, v33
	v_add_f32_e32 v34, 1.0, v34
	v_add_f32_e32 v35, 1.0, v35
	v_rcp_f32_e32 v32, v32
	v_rcp_f32_e32 v33, v33
	v_rcp_f32_e32 v34, v34
	v_rcp_f32_e32 v35, v35
	v_cvt_pk_bf16_f32 v32, v32, v33
	v_cvt_pk_bf16_f32 v33, v34, v35
	v_or_b32_e32 v34, v36, v108
	v_ashrrev_i32_e32 v35, 31, v34
	v_lshlrev_b64 v[34:35], 11, v[34:35]
	v_lshl_add_u64 v[34:35], v[96:97], 0, v[34:35]
	flat_store_dwordx2 v[34:35], v[32:33]
	ds_write_b128 v101, v[0:3]
	ds_write_b128 v101, v[4:7] offset:64
	ds_write_b128 v101, v[8:11] offset:128
	ds_write_b128 v101, v[12:15] offset:192
	ds_write_b128 v101, v[16:19] offset:4352
	ds_write_b128 v101, v[20:23] offset:4416
	ds_write_b128 v101, v[24:27] offset:4480
	ds_write_b128 v101, v[28:31] offset:4544
	ds_read_b128 v[0:3], v98
	v_or_b32_e32 v4, 0x60, v100
	v_mov_b32_e32 v12, v132
	s_waitcnt lgkmcnt(0)
	v_mul_f32_e32 v0, 0xbfb8aa3b, v0
	v_mul_f32_e32 v1, 0xbfb8aa3b, v1
	v_mul_f32_e32 v2, 0xbfb8aa3b, v2
	v_mul_f32_e32 v3, 0xbfb8aa3b, v3
	v_exp_f32_e32 v0, v0
	v_exp_f32_e32 v1, v1
	v_exp_f32_e32 v2, v2
	v_exp_f32_e32 v3, v3
	v_add_f32_e32 v0, 1.0, v0
	v_add_f32_e32 v1, 1.0, v1
	v_add_f32_e32 v2, 1.0, v2
	v_add_f32_e32 v3, 1.0, v3
	v_rcp_f32_e32 v0, v0
	v_rcp_f32_e32 v1, v1
	v_rcp_f32_e32 v2, v2
	v_rcp_f32_e32 v3, v3
	v_cvt_pk_bf16_f32 v0, v0, v1
	v_cvt_pk_bf16_f32 v1, v2, v3
	v_or_b32_e32 v2, v4, v99
	v_ashrrev_i32_e32 v3, 31, v2
	v_lshlrev_b64 v[2:3], 11, v[2:3]
	v_lshl_add_u64 v[2:3], v[96:97], 0, v[2:3]
	flat_store_dwordx2 v[2:3], v[0:1]
	ds_read_b128 v[0:3], v98 offset:1088
	s_waitcnt lgkmcnt(0)
	v_mul_f32_e32 v0, 0xbfb8aa3b, v0
	v_mul_f32_e32 v1, 0xbfb8aa3b, v1
	v_mul_f32_e32 v2, 0xbfb8aa3b, v2
	v_mul_f32_e32 v3, 0xbfb8aa3b, v3
	v_exp_f32_e32 v0, v0
	v_exp_f32_e32 v1, v1
	v_exp_f32_e32 v2, v2
	v_exp_f32_e32 v3, v3
	v_add_f32_e32 v0, 1.0, v0
	v_add_f32_e32 v1, 1.0, v1
	v_add_f32_e32 v2, 1.0, v2
	v_add_f32_e32 v3, 1.0, v3
	v_rcp_f32_e32 v0, v0
	v_rcp_f32_e32 v1, v1
	v_rcp_f32_e32 v2, v2
	v_rcp_f32_e32 v3, v3
	v_cvt_pk_bf16_f32 v0, v0, v1
	v_cvt_pk_bf16_f32 v1, v2, v3
	v_or_b32_e32 v2, v4, v102
	v_ashrrev_i32_e32 v3, 31, v2
	v_lshlrev_b64 v[2:3], 11, v[2:3]
	v_lshl_add_u64 v[2:3], v[96:97], 0, v[2:3]
	flat_store_dwordx2 v[2:3], v[0:1]
	ds_read_b128 v[0:3], v98 offset:2176
	s_waitcnt lgkmcnt(0)
	v_mul_f32_e32 v0, 0xbfb8aa3b, v0
	v_mul_f32_e32 v1, 0xbfb8aa3b, v1
	v_mul_f32_e32 v2, 0xbfb8aa3b, v2
	v_mul_f32_e32 v3, 0xbfb8aa3b, v3
	v_exp_f32_e32 v0, v0
	v_exp_f32_e32 v1, v1
	v_exp_f32_e32 v2, v2
	v_exp_f32_e32 v3, v3
	v_add_f32_e32 v0, 1.0, v0
	v_add_f32_e32 v1, 1.0, v1
	v_add_f32_e32 v2, 1.0, v2
	v_add_f32_e32 v3, 1.0, v3
	v_rcp_f32_e32 v0, v0
	v_rcp_f32_e32 v1, v1
	v_rcp_f32_e32 v2, v2
	v_rcp_f32_e32 v3, v3
	v_cvt_pk_bf16_f32 v0, v0, v1
	v_cvt_pk_bf16_f32 v1, v2, v3
	v_or_b32_e32 v2, v4, v103
	v_ashrrev_i32_e32 v3, 31, v2
	v_lshlrev_b64 v[2:3], 11, v[2:3]
	v_lshl_add_u64 v[2:3], v[96:97], 0, v[2:3]
	flat_store_dwordx2 v[2:3], v[0:1]
	ds_read_b128 v[0:3], v98 offset:3264
	s_waitcnt lgkmcnt(0)
	v_mul_f32_e32 v0, 0xbfb8aa3b, v0
	v_mul_f32_e32 v1, 0xbfb8aa3b, v1
	v_mul_f32_e32 v2, 0xbfb8aa3b, v2
	v_mul_f32_e32 v3, 0xbfb8aa3b, v3
	v_exp_f32_e32 v0, v0
	v_exp_f32_e32 v1, v1
	v_exp_f32_e32 v2, v2
	v_exp_f32_e32 v3, v3
	v_add_f32_e32 v0, 1.0, v0
	v_add_f32_e32 v1, 1.0, v1
	v_add_f32_e32 v2, 1.0, v2
	v_add_f32_e32 v3, 1.0, v3
	v_rcp_f32_e32 v0, v0
	v_rcp_f32_e32 v1, v1
	v_rcp_f32_e32 v2, v2
	v_rcp_f32_e32 v3, v3
	v_cvt_pk_bf16_f32 v0, v0, v1
	v_cvt_pk_bf16_f32 v1, v2, v3
	v_or_b32_e32 v2, v4, v104
	v_ashrrev_i32_e32 v3, 31, v2
	v_lshlrev_b64 v[2:3], 11, v[2:3]
	v_lshl_add_u64 v[2:3], v[96:97], 0, v[2:3]
	flat_store_dwordx2 v[2:3], v[0:1]
	ds_read_b128 v[0:3], v98 offset:4352
	s_waitcnt lgkmcnt(0)
	v_mul_f32_e32 v0, 0xbfb8aa3b, v0
	v_mul_f32_e32 v1, 0xbfb8aa3b, v1
	v_mul_f32_e32 v2, 0xbfb8aa3b, v2
	v_mul_f32_e32 v3, 0xbfb8aa3b, v3
	v_exp_f32_e32 v0, v0
	v_exp_f32_e32 v1, v1
	v_exp_f32_e32 v2, v2
	v_exp_f32_e32 v3, v3
	v_add_f32_e32 v0, 1.0, v0
	v_add_f32_e32 v1, 1.0, v1
	v_add_f32_e32 v2, 1.0, v2
	v_add_f32_e32 v3, 1.0, v3
	v_rcp_f32_e32 v0, v0
	v_rcp_f32_e32 v1, v1
	v_rcp_f32_e32 v2, v2
	v_rcp_f32_e32 v3, v3
	v_cvt_pk_bf16_f32 v0, v0, v1
	v_cvt_pk_bf16_f32 v1, v2, v3
	v_or_b32_e32 v2, v4, v105
	v_ashrrev_i32_e32 v3, 31, v2
	v_lshlrev_b64 v[2:3], 11, v[2:3]
	v_lshl_add_u64 v[2:3], v[96:97], 0, v[2:3]
	flat_store_dwordx2 v[2:3], v[0:1]
	ds_read_b128 v[0:3], v98 offset:5440
	s_waitcnt lgkmcnt(0)
	v_mul_f32_e32 v0, 0xbfb8aa3b, v0
	v_mul_f32_e32 v1, 0xbfb8aa3b, v1
	v_mul_f32_e32 v2, 0xbfb8aa3b, v2
	v_mul_f32_e32 v3, 0xbfb8aa3b, v3
	v_exp_f32_e32 v0, v0
	v_exp_f32_e32 v1, v1
	v_exp_f32_e32 v2, v2
	v_exp_f32_e32 v3, v3
	v_add_f32_e32 v0, 1.0, v0
	v_add_f32_e32 v1, 1.0, v1
	v_add_f32_e32 v2, 1.0, v2
	v_add_f32_e32 v3, 1.0, v3
	v_rcp_f32_e32 v0, v0
	v_rcp_f32_e32 v1, v1
	v_rcp_f32_e32 v2, v2
	v_rcp_f32_e32 v3, v3
	v_cvt_pk_bf16_f32 v0, v0, v1
	v_cvt_pk_bf16_f32 v1, v2, v3
	v_or_b32_e32 v2, v4, v106
	v_ashrrev_i32_e32 v3, 31, v2
	v_lshlrev_b64 v[2:3], 11, v[2:3]
	v_lshl_add_u64 v[2:3], v[96:97], 0, v[2:3]
	flat_store_dwordx2 v[2:3], v[0:1]
	ds_read_b128 v[0:3], v98 offset:6528
	s_waitcnt lgkmcnt(0)
	v_mul_f32_e32 v0, 0xbfb8aa3b, v0
	v_mul_f32_e32 v1, 0xbfb8aa3b, v1
	v_mul_f32_e32 v2, 0xbfb8aa3b, v2
	v_mul_f32_e32 v3, 0xbfb8aa3b, v3
	v_exp_f32_e32 v0, v0
	v_exp_f32_e32 v1, v1
	v_exp_f32_e32 v2, v2
	v_exp_f32_e32 v3, v3
	v_add_f32_e32 v0, 1.0, v0
	v_add_f32_e32 v1, 1.0, v1
	v_add_f32_e32 v2, 1.0, v2
	v_add_f32_e32 v3, 1.0, v3
	v_rcp_f32_e32 v0, v0
	v_rcp_f32_e32 v1, v1
	v_rcp_f32_e32 v2, v2
	v_rcp_f32_e32 v3, v3
	v_cvt_pk_bf16_f32 v0, v0, v1
	v_cvt_pk_bf16_f32 v1, v2, v3
	v_or_b32_e32 v2, v4, v107
	v_ashrrev_i32_e32 v3, 31, v2
	v_lshlrev_b64 v[2:3], 11, v[2:3]
	v_lshl_add_u64 v[2:3], v[96:97], 0, v[2:3]
	flat_store_dwordx2 v[2:3], v[0:1]
	ds_read_b128 v[0:3], v98 offset:7616
	s_waitcnt lgkmcnt(0)
	v_mul_f32_e32 v0, 0xbfb8aa3b, v0
	v_mul_f32_e32 v1, 0xbfb8aa3b, v1
	v_mul_f32_e32 v2, 0xbfb8aa3b, v2
	v_mul_f32_e32 v3, 0xbfb8aa3b, v3
	v_exp_f32_e32 v0, v0
	v_exp_f32_e32 v1, v1
	v_exp_f32_e32 v2, v2
	v_exp_f32_e32 v3, v3
	v_add_f32_e32 v0, 1.0, v0
	v_add_f32_e32 v1, 1.0, v1
	v_add_f32_e32 v2, 1.0, v2
	v_add_f32_e32 v3, 1.0, v3
	v_rcp_f32_e32 v0, v0
	v_rcp_f32_e32 v1, v1
	v_rcp_f32_e32 v2, v2
	v_rcp_f32_e32 v3, v3
	v_cvt_pk_bf16_f32 v0, v0, v1
	v_cvt_pk_bf16_f32 v1, v2, v3
	v_or_b32_e32 v2, v4, v108
	v_ashrrev_i32_e32 v3, 31, v2
	v_lshlrev_b64 v[2:3], 11, v[2:3]
	v_lshl_add_u64 v[2:3], v[96:97], 0, v[2:3]
	flat_store_dwordx2 v[2:3], v[0:1]
	v_mov_b32_e32 v0, s3
	ds_read_b128 v[0:3], v0
	s_waitcnt lgkmcnt(0)
	v_readfirstlane_b32 s0, v3
	v_readfirstlane_b32 s29, v2
	v_lshlrev_b32_e32 v3, 4, v12
	v_and_b32_e32 v2, 32, v12
	s_add_u32 s42, s29, s36
	v_lshrrev_b32_e32 v4, 1, v12
	v_bitop3_b32 v2, v3, v2, 48 bitop3:0x6c
	s_addc_u32 s43, s0, s37
	v_bfe_u32 v13, v12, 2, 4
	v_and_b32_e32 v14, 32, v4
	v_lshrrev_b32_e32 v15, 1, v2
	v_ashrrev_i32_e32 v16, 3, v12
	s_add_u32 s36, s42, 0x18800000
	v_or_b32_e32 v6, v15, v14
	v_and_or_b32 v2, v16, s44, v13
	s_addc_u32 s37, s43, 0
	s_lshl_b64 s[38:39], s[30:31], 11
	v_and_b32_e32 v5, 0xfffffc00, v3
	v_lshl_or_b32 v130, v2, 10, v6
	v_add_u32_e32 v2, 0x2000, v3
	v_add_u32_e32 v4, 0x4000, v3
	v_add_u32_e32 v3, 0x6000, v3
	s_add_u32 s53, s29, s38
	v_ashrrev_i32_e32 v17, 7, v2
	v_ashrrev_i32_e32 v18, 7, v4
	v_ashrrev_i32_e32 v19, 7, v3
	s_addc_u32 s54, s0, s39
	v_and_or_b32 v2, v17, s44, v13
	v_and_or_b32 v4, v18, s44, v13
	v_and_or_b32 v3, v19, s44, v13
	v_add_u32_e32 v151, 0, v5
	s_add_u32 s38, s53, 0xe00000
	v_lshl_or_b32 v2, v2, 10, v6
	v_lshl_or_b32 v4, v4, 10, v6
	v_lshl_or_b32 v6, v3, 10, v6
	v_add_u32_e32 v3, 0x8000, v151
	v_lshlrev_b64 v[8:9], 1, v[130:131]
	v_readfirstlane_b32 s55, v151
	s_addc_u32 s39, s54, 0
	v_lshl_add_u64 v[10:11], s[36:37], 0, v[8:9]
	s_mov_b32 m0, s55
	v_readfirstlane_b32 s55, v3
	v_mov_b32_e32 v3, v131
	v_add_u32_e32 v5, 0x2000, v151
	global_load_lds_dwordx4 v[10:11], off
	v_lshl_add_u64 v[8:9], s[38:39], 0, v[8:9]
	s_mov_b32 m0, s55
	v_lshlrev_b64 v[2:3], 1, v[2:3]
	v_readfirstlane_b32 s55, v5
	v_add_u32_e32 v5, 0xa000, v151
	global_load_lds_dwordx4 v[8:9], off
	v_lshl_add_u64 v[8:9], s[36:37], 0, v[2:3]
	s_mov_b32 m0, s55
	v_readfirstlane_b32 s55, v5
	global_load_lds_dwordx4 v[8:9], off
	v_lshl_add_u64 v[2:3], s[38:39], 0, v[2:3]
	s_mov_b32 m0, s55
	v_mov_b32_e32 v5, v131
	v_add_u32_e32 v7, 0x4000, v151
	global_load_lds_dwordx4 v[2:3], off
	v_lshlrev_b64 v[2:3], 1, v[4:5]
	v_readfirstlane_b32 s55, v7
	v_lshl_add_u64 v[4:5], s[36:37], 0, v[2:3]
	s_mov_b32 m0, s55
	v_lshl_add_u64 v[2:3], s[38:39], 0, v[2:3]
	global_load_lds_dwordx4 v[4:5], off
	v_add_u32_e32 v4, 0xc000, v151
	v_mov_b32_e32 v7, v131
	v_readfirstlane_b32 s55, v4
	s_mov_b32 m0, s55
	v_and_b32_e32 v20, 15, v12
	global_load_lds_dwordx4 v[2:3], off
	v_lshlrev_b64 v[2:3], 1, v[6:7]
	v_add_u32_e32 v6, 0x6000, v151
	v_lshl_add_u64 v[4:5], s[36:37], 0, v[2:3]
	v_readfirstlane_b32 s36, v6
	s_mov_b32 m0, s36
	v_lshl_add_u64 v[2:3], s[38:39], 0, v[2:3]
	global_load_lds_dwordx4 v[4:5], off
	v_add_u32_e32 v4, 0xe000, v151
	v_lshlrev_b32_e32 v8, 10, v13
	v_readfirstlane_b32 s36, v4
	s_mov_b32 m0, s36
	v_lshlrev_b32_e32 v4, 2, v12
	global_load_lds_dwordx4 v[2:3], off
	v_and_b32_e32 v2, 48, v12
	v_lshlrev_b32_e32 v3, 6, v20
	v_and_b32_e32 v4, 32, v4
	v_bitop3_b32 v152, v3, v4, v2 bitop3:0x36
	v_lshlrev_b32_e32 v3, 7, v12
	v_and_b32_e32 v153, 0x6000, v3
	v_lshlrev_b32_e32 v3, 6, v12
	v_and_b32_e32 v154, 0xffffc000, v3
	v_and_b32_e32 v3, 0x3c0, v3
	v_bitop3_b32 v156, v3, v4, v2 bitop3:0x36
	v_lshlrev_b32_e32 v2, 10, v19
	v_and_or_b32 v2, v2, s45, v15
	v_lshlrev_b32_e32 v4, 10, v18
	v_or3_b32 v130, v2, v8, v14
	v_and_or_b32 v4, v4, s45, v15
	v_lshlrev_b32_e32 v6, 10, v17
	v_lshlrev_b64 v[2:3], 1, v[130:131]
	v_or3_b32 v130, v4, v8, v14
	v_and_or_b32 v6, v6, s45, v15
	v_lshlrev_b32_e32 v9, 10, v16
	v_lshlrev_b64 v[4:5], 1, v[130:131]
	v_or3_b32 v130, v6, v8, v14
	v_and_or_b32 v9, v9, s45, v15
	s_add_u32 s36, s53, 0xe00080
	v_lshlrev_b64 v[6:7], 1, v[130:131]
	v_or3_b32 v130, v9, v8, v14
	s_addc_u32 s37, s54, 0
	v_lshlrev_b64 v[8:9], 1, v[130:131]
	s_nop 0
	v_lshl_add_u64 v[134:135], s[36:37], 0, v[2:3]
	v_lshl_add_u64 v[136:137], s[36:37], 0, v[4:5]
	v_lshl_add_u64 v[138:139], s[36:37], 0, v[6:7]
	v_lshl_add_u64 v[140:141], s[36:37], 0, v[8:9]
	s_add_u32 s36, s42, 0x18800080
	s_addc_u32 s37, s43, 0
	v_mov_b32_e32 v10, 0
	v_or_b32_e32 v155, 0x800, v154
	v_or_b32_e32 v157, 0x1000, v154
	v_or_b32_e32 v158, 0x1800, v154
	v_or_b32_e32 v159, 0x2000, v154
	v_or_b32_e32 v160, 0x2800, v154
	v_or_b32_e32 v161, 0x3000, v154
	v_or_b32_e32 v162, 0x3800, v154
	v_lshl_add_u64 v[142:143], s[36:37], 0, v[2:3]
	v_lshl_add_u64 v[144:145], s[36:37], 0, v[4:5]
	v_lshl_add_u64 v[146:147], s[36:37], 0, v[6:7]
	v_lshl_add_u64 v[148:149], s[36:37], 0, v[8:9]
	s_mov_b32 s38, 0
	s_mov_b64 s[36:37], 0
	v_mov_b32_e32 v11, v10
	v_mov_b32_e32 v12, v10
	v_mov_b32_e32 v13, v10
	v_mov_b32_e32 v22, v10
	v_mov_b32_e32 v23, v10
	v_mov_b32_e32 v24, v10
	v_mov_b32_e32 v25, v10
	v_mov_b32_e32 v30, v10
	v_mov_b32_e32 v31, v10
	v_mov_b32_e32 v32, v10
	v_mov_b32_e32 v33, v10
	v_mov_b32_e32 v38, v10
	v_mov_b32_e32 v39, v10
	v_mov_b32_e32 v40, v10
	v_mov_b32_e32 v41, v10
	v_mov_b32_e32 v2, v10
	v_mov_b32_e32 v3, v10
	v_mov_b32_e32 v4, v10
	v_mov_b32_e32 v5, v10
	v_mov_b32_e32 v6, v10
	v_mov_b32_e32 v7, v10
	v_mov_b32_e32 v8, v10
	v_mov_b32_e32 v9, v10
	v_mov_b32_e32 v14, v10
	v_mov_b32_e32 v15, v10
	v_mov_b32_e32 v16, v10
	v_mov_b32_e32 v17, v10
	v_mov_b32_e32 v18, v10
	v_mov_b32_e32 v19, v10
	v_mov_b32_e32 v20, v10
	v_mov_b32_e32 v21, v10
	v_mov_b32_e32 v26, v10
	v_mov_b32_e32 v27, v10
	v_mov_b32_e32 v28, v10
	v_mov_b32_e32 v29, v10
	v_mov_b32_e32 v34, v10
	v_mov_b32_e32 v35, v10
	v_mov_b32_e32 v36, v10
	v_mov_b32_e32 v37, v10
	v_mov_b32_e32 v42, v10
	v_mov_b32_e32 v43, v10
	v_mov_b32_e32 v44, v10
	v_mov_b32_e32 v45, v10
	v_mov_b32_e32 v46, v10
	v_mov_b32_e32 v47, v10
	v_mov_b32_e32 v48, v10
	v_mov_b32_e32 v49, v10
	v_mov_b32_e32 v50, v10
	v_mov_b32_e32 v51, v10
	v_mov_b32_e32 v52, v10
	v_mov_b32_e32 v53, v10
	v_mov_b32_e32 v54, v10
	v_mov_b32_e32 v55, v10
	v_mov_b32_e32 v56, v10
	v_mov_b32_e32 v57, v10
	v_mov_b32_e32 v58, v10
	v_mov_b32_e32 v59, v10
	v_mov_b32_e32 v60, v10
	v_mov_b32_e32 v61, v10
	v_mov_b32_e32 v62, v10
	v_mov_b32_e32 v63, v10
	v_mov_b32_e32 v64, v10
	v_mov_b32_e32 v65, v10
	v_mov_b32_e32 v66, v10
	v_mov_b32_e32 v67, v10
	v_mov_b32_e32 v68, v10
	v_mov_b32_e32 v69, v10
	v_mov_b32_e32 v70, v10
	v_mov_b32_e32 v71, v10
	v_mov_b32_e32 v72, v10
	v_mov_b32_e32 v73, v10
	v_mov_b32_e32 v74, v10
	v_mov_b32_e32 v75, v10
	v_mov_b32_e32 v76, v10
	v_mov_b32_e32 v77, v10
	v_mov_b32_e32 v78, v10
	v_mov_b32_e32 v79, v10
	v_mov_b32_e32 v80, v10
	v_mov_b32_e32 v81, v10
	v_mov_b32_e32 v82, v10
	v_mov_b32_e32 v83, v10
	v_mov_b32_e32 v84, v10
	v_mov_b32_e32 v85, v10
	v_mov_b32_e32 v86, v10
	v_mov_b32_e32 v87, v10
	v_mov_b32_e32 v88, v10
	v_mov_b32_e32 v89, v10
	v_mov_b32_e32 v90, v10
	v_mov_b32_e32 v91, v10
	v_mov_b32_e32 v92, v10
	v_mov_b32_e32 v93, v10
	v_mov_b32_e32 v94, v10
	v_mov_b32_e32 v95, v10
	v_mov_b32_e32 v96, v10
	v_mov_b32_e32 v97, v10
	v_mov_b32_e32 v98, v10
	v_mov_b32_e32 v99, v10
	v_mov_b32_e32 v100, v10
	v_mov_b32_e32 v101, v10
	v_mov_b32_e32 v102, v10
	v_mov_b32_e32 v103, v10
	v_mov_b32_e32 v104, v10
	v_mov_b32_e32 v105, v10
	v_mov_b32_e32 v106, v10
	v_mov_b32_e32 v107, v10
	v_mov_b32_e32 v108, v10
	v_mov_b32_e32 v109, v10
	v_mov_b32_e32 v110, v10
	v_mov_b32_e32 v111, v10
	v_mov_b32_e32 v112, v10
	v_mov_b32_e32 v113, v10
	v_mov_b32_e32 v114, v10
	v_mov_b32_e32 v115, v10
	v_mov_b32_e32 v116, v10
	v_mov_b32_e32 v117, v10
	v_mov_b32_e32 v118, v10
	v_mov_b32_e32 v119, v10
	v_mov_b32_e32 v120, v10
	v_mov_b32_e32 v121, v10
	v_mov_b32_e32 v122, v10
	v_mov_b32_e32 v123, v10
	v_mov_b32_e32 v124, v10
	v_mov_b32_e32 v125, v10
	v_mov_b32_e32 v126, v10
	v_mov_b32_e32 v127, v10
	v_mov_b32_e32 v128, v10
	v_mov_b32_e32 v129, v10
	s_waitcnt vmcnt(0) lgkmcnt(0)
	s_barrier
	v_readfirstlane_b32 s100, v151
	s_and_b32 s39, s38, 0x10000
	s_xor_b32 s42, s39, 0x10000
	s_add_i32 s39, s39, 0
	v_add3_u32 v130, s39, v152, v153
	v_add3_u32 v163, s39, v152, v154
	v_add3_u32 v196, s39, v156, v155
	v_add3_u32 v197, s39, v156, v157
	v_add3_u32 v198, s39, v156, v158
	v_add3_u32 v199, s39, v156, v159
	v_add3_u32 v200, s39, v156, v160
	v_add3_u32 v201, s39, v156, v161
	v_add3_u32 v202, s39, v156, v162
	ds_read_b128 v[180:183], v130 offset:32768
	ds_read_b128 v[164:167], v163
	ds_read_b128 v[168:171], v196
	ds_read_b128 v[172:175], v197
	ds_read_b128 v[176:179], v198
	ds_read_b128 v[184:187], v130 offset:34816
	ds_read_b128 v[188:191], v130 offset:36864
	ds_read_b128 v[192:195], v130 offset:38912
	s_add_i32 s101, s100, s42
	v_readfirstlane_b32 s98, v148
	v_readfirstlane_b32 s99, v149
	v_readfirstlane_b32 vcc_lo, v140
	v_readfirstlane_b32 vcc_hi, v141
	s_sub_u32 s98, s98, 0x1000000
	s_subb_u32 s99, s99, 0
	s_sub_u32 vcc_lo, vcc_lo, 0x1000000
	s_subb_u32 vcc_hi, vcc_hi, 0
	v_subrev_u32_e32 v148, s98, v148
	v_subrev_u32_e32 v140, vcc_lo, v140
	v_subrev_u32_e32 v146, s98, v146
	v_subrev_u32_e32 v138, vcc_lo, v138
	v_subrev_u32_e32 v144, s98, v144
	v_subrev_u32_e32 v136, vcc_lo, v136
	v_subrev_u32_e32 v142, s98, v142
	v_subrev_u32_e32 v134, vcc_lo, v134
	s_mov_b32 m0, s101
	s_nop 0
	global_load_lds_dwordx4 v148, s[98:99]
	s_add_i32 m0, s101, 0x8000
	s_nop 0
	global_load_lds_dwordx4 v140, vcc
	s_add_i32 m0, s101, 0x2000
	s_nop 0
	global_load_lds_dwordx4 v146, s[98:99]
	s_add_i32 m0, s101, 0xa000
	s_nop 0
	global_load_lds_dwordx4 v138, vcc
	s_add_i32 m0, s101, 0x4000
	s_nop 0
	global_load_lds_dwordx4 v144, s[98:99]
	s_add_i32 m0, s101, 0xc000
	s_nop 0
	global_load_lds_dwordx4 v136, vcc
	s_add_i32 m0, s101, 0x6000
	s_nop 0
	global_load_lds_dwordx4 v142, s[98:99]
	s_add_i32 m0, s101, 0xe000
	s_nop 0
	global_load_lds_dwordx4 v134, vcc

.LBB0_845:
	s_ashr_i32 s12, s27, 31
	s_lshr_b32 s12, s12, 26
	s_add_i32 s12, s27, s12
	s_ashr_i32 s13, s12, 6
	s_and_b32 s12, s12, 0xffc0
	s_sub_i32 s12, s27, s12
	s_bfe_i32 s14, s12, 0x80000
	s_bfe_u32 s14, s14, 0x4000b
	s_add_i32 s14, s12, s14
	s_lshl_b32 s28, s13, 4
	s_and_b32 s13, s14, 0xf0
	v_mov_b32_e32 v148, v132
	v_mov_b32_e32 v18, v132
	s_sub_i32 s12, s12, s13
	ds_read_b64 v[0:1], v133
	s_bfe_i32 s15, s14, 0x80000
	v_lshlrev_b32_e32 v9, 4, v18
	v_and_b32_e32 v8, 32, v18
	s_sext_i32_i8 s12, s12
	v_lshrrev_b32_e32 v10, 1, v18
	v_bitop3_b32 v8, v9, v8, 48 bitop3:0x6c
	s_sext_i32_i16 s15, s15
	s_add_i32 s28, s28, s12
	v_bfe_u32 v19, v18, 2, 4
	v_and_b32_e32 v20, 32, v10
	v_lshrrev_b32_e32 v21, 1, v8
	v_ashrrev_i32_e32 v22, 3, v18
	s_lshl_b32 s14, s28, 8
	s_lshl_b32 s12, s15, 4
	v_or_b32_e32 v12, v21, v20
	v_and_or_b32 v8, v22, s18, v19
	s_and_b32 s12, s12, 0xffffff00
	s_ashr_i32 s15, s14, 31
	v_and_b32_e32 v11, 0xfffffc00, v9
	v_lshl_or_b32 v128, v8, 10, v12
	v_add_u32_e32 v8, 0x2000, v9
	v_add_u32_e32 v10, 0x4000, v9
	v_add_u32_e32 v9, 0x6000, v9
	s_lshl_b64 s[16:17], s[14:15], 11
	s_ashr_i32 s13, s12, 31
	v_ashrrev_i32_e32 v23, 7, v8
	v_ashrrev_i32_e32 v24, 7, v10
	v_ashrrev_i32_e32 v25, 7, v9
	s_waitcnt lgkmcnt(0)
	v_lshl_add_u64 v[2:3], v[0:1], 0, s[16:17]
	s_lshl_b64 s[16:17], s[12:13], 11
	v_and_or_b32 v8, v23, s18, v19
	v_and_or_b32 v10, v24, s18, v19
	v_and_or_b32 v9, v25, s18, v19
	v_add_u32_e32 v149, 0, v11
	v_lshl_add_u64 v[4:5], v[2:3], 0, s[4:5]
	v_lshl_add_u64 v[0:1], v[0:1], 0, s[16:17]
	v_lshl_or_b32 v8, v8, 10, v12
	v_lshl_or_b32 v10, v10, 10, v12
	v_lshl_or_b32 v12, v9, 10, v12
	v_add_u32_e32 v9, 0x8000, v149
	v_lshlrev_b64 v[14:15], 1, v[128:129]
	v_readfirstlane_b32 s15, v149
	v_lshl_add_u64 v[6:7], v[0:1], 0, s[6:7]
	v_lshl_add_u64 v[16:17], v[4:5], 0, v[14:15]
	s_mov_b32 m0, s15
	v_readfirstlane_b32 s15, v9
	v_mov_b32_e32 v9, v129
	v_add_u32_e32 v11, 0x2000, v149
	global_load_lds_dwordx4 v[16:17], off
	v_lshl_add_u64 v[14:15], v[6:7], 0, v[14:15]
	s_mov_b32 m0, s15
	v_lshlrev_b64 v[8:9], 1, v[8:9]
	v_readfirstlane_b32 s15, v11
	v_add_u32_e32 v11, 0xa000, v149
	global_load_lds_dwordx4 v[14:15], off
	v_lshl_add_u64 v[14:15], v[4:5], 0, v[8:9]
	s_mov_b32 m0, s15
	v_readfirstlane_b32 s15, v11
	global_load_lds_dwordx4 v[14:15], off
	v_lshl_add_u64 v[8:9], v[6:7], 0, v[8:9]
	s_mov_b32 m0, s15
	v_mov_b32_e32 v11, v129
	v_add_u32_e32 v13, 0x4000, v149
	global_load_lds_dwordx4 v[8:9], off
	v_lshlrev_b64 v[8:9], 1, v[10:11]
	v_readfirstlane_b32 s15, v13
	v_lshl_add_u64 v[10:11], v[4:5], 0, v[8:9]
	s_mov_b32 m0, s15
	v_lshl_add_u64 v[8:9], v[6:7], 0, v[8:9]
	global_load_lds_dwordx4 v[10:11], off
	v_add_u32_e32 v10, 0xc000, v149
	v_mov_b32_e32 v13, v129
	v_readfirstlane_b32 s15, v10
	s_mov_b32 m0, s15
	v_add_u32_e32 v10, 0x6000, v149
	global_load_lds_dwordx4 v[8:9], off
	v_lshlrev_b64 v[8:9], 1, v[12:13]
	v_readfirstlane_b32 s15, v10
	v_lshl_add_u64 v[4:5], v[4:5], 0, v[8:9]
	s_mov_b32 m0, s15
	v_and_b32_e32 v26, 15, v18
	global_load_lds_dwordx4 v[4:5], off
	v_lshl_add_u64 v[4:5], v[6:7], 0, v[8:9]
	v_add_u32_e32 v6, 0xe000, v149
	v_lshlrev_b32_e32 v10, 10, v19
	v_readfirstlane_b32 s15, v6
	s_mov_b32 m0, s15
	v_lshlrev_b32_e32 v6, 2, v18
	global_load_lds_dwordx4 v[4:5], off
	v_and_b32_e32 v4, 48, v18
	v_lshlrev_b32_e32 v5, 6, v26
	v_and_b32_e32 v6, 32, v6
	v_bitop3_b32 v150, v5, v6, v4 bitop3:0x36
	v_lshlrev_b32_e32 v5, 7, v18
	v_and_b32_e32 v151, 0x6000, v5
	v_lshlrev_b32_e32 v5, 6, v18
	v_and_b32_e32 v152, 0xffffc000, v5
	v_and_b32_e32 v5, 0x3c0, v5
	v_bitop3_b32 v154, v5, v6, v4 bitop3:0x36
	v_lshlrev_b32_e32 v4, 10, v25
	v_and_or_b32 v4, v4, s19, v21
	v_lshlrev_b32_e32 v6, 10, v24
	v_or3_b32 v128, v4, v10, v20
	v_and_or_b32 v6, v6, s19, v21
	v_lshlrev_b32_e32 v8, 10, v23
	v_lshlrev_b64 v[4:5], 1, v[128:129]
	v_or3_b32 v128, v6, v10, v20
	v_and_or_b32 v8, v8, s19, v21
	v_lshlrev_b32_e32 v11, 10, v22
	v_lshlrev_b64 v[6:7], 1, v[128:129]
	v_or3_b32 v128, v8, v10, v20
	v_and_or_b32 v11, v11, s19, v21
	v_lshlrev_b64 v[8:9], 1, v[128:129]
	v_or3_b32 v128, v11, v10, v20
	s_nop 0
	v_lshl_add_u64 v[0:1], v[0:1], 0, s[8:9]
	v_lshlrev_b64 v[10:11], 1, v[128:129]
	v_lshl_add_u64 v[130:131], v[0:1], 0, v[4:5]
	v_lshl_add_u64 v[134:135], v[0:1], 0, v[6:7]
	v_lshl_add_u64 v[136:137], v[0:1], 0, v[8:9]
	v_lshl_add_u64 v[138:139], v[0:1], 0, v[10:11]
	v_lshl_add_u64 v[0:1], v[2:3], 0, s[10:11]
	v_or_b32_e32 v153, 0x800, v152
	v_or_b32_e32 v155, 0x1000, v152
	v_or_b32_e32 v156, 0x1800, v152
	v_or_b32_e32 v157, 0x2000, v152
	v_or_b32_e32 v158, 0x2800, v152
	v_or_b32_e32 v159, 0x3000, v152
	v_or_b32_e32 v160, 0x3800, v152
	v_lshl_add_u64 v[140:141], v[0:1], 0, v[4:5]
	v_lshl_add_u64 v[142:143], v[0:1], 0, v[6:7]
	v_lshl_add_u64 v[144:145], v[0:1], 0, v[8:9]
	v_lshl_add_u64 v[146:147], v[0:1], 0, v[10:11]
	s_mov_b64 s[16:17], 0
	s_mov_b32 s15, 0
	v_mov_b32_e32 v12, 0
	v_mov_b32_e32 v14, v129
	v_mov_b32_e32 v15, v129
	v_mov_b32_e32 v20, 0
	v_mov_b32_e32 v21, v129
	v_mov_b32_e32 v22, v129
	v_mov_b32_e32 v23, v129
	v_mov_b32_e32 v28, 0
	v_mov_b32_e32 v29, v129
	v_mov_b32_e32 v30, v129
	v_mov_b32_e32 v31, v129
	v_mov_b32_e32 v36, 0
	v_mov_b32_e32 v37, v129
	v_mov_b32_e32 v38, v129
	v_mov_b32_e32 v39, v129
	v_mov_b32_e32 v0, 0
	v_mov_b32_e32 v1, v129
	v_mov_b32_e32 v2, v129
	v_mov_b32_e32 v3, v129
	v_mov_b32_e32 v4, 0
	v_mov_b32_e32 v5, v129
	v_mov_b32_e32 v6, v129
	v_mov_b32_e32 v7, v129
	v_mov_b32_e32 v8, 0
	v_mov_b32_e32 v9, v129
	v_mov_b32_e32 v10, v129
	v_mov_b32_e32 v11, v129
	v_mov_b32_e32 v16, 0
	v_mov_b32_e32 v17, v129
	v_mov_b32_e32 v18, v129
	v_mov_b32_e32 v19, v129
	v_mov_b32_e32 v24, 0
	v_mov_b32_e32 v25, v129
	v_mov_b32_e32 v26, v129
	v_mov_b32_e32 v27, v129
	v_mov_b32_e32 v32, 0
	v_mov_b32_e32 v33, v129
	v_mov_b32_e32 v34, v129
	v_mov_b32_e32 v35, v129
	v_mov_b32_e32 v40, 0
	v_mov_b32_e32 v41, v129
	v_mov_b32_e32 v42, v129
	v_mov_b32_e32 v43, v129
	v_mov_b32_e32 v44, 0
	v_mov_b32_e32 v45, v129
	v_mov_b32_e32 v46, v129
	v_mov_b32_e32 v47, v129
	v_mov_b32_e32 v48, 0
	v_mov_b32_e32 v49, v129
	v_mov_b32_e32 v50, v129
	v_mov_b32_e32 v51, v129
	v_mov_b32_e32 v52, 0
	v_mov_b32_e32 v53, v129
	v_mov_b32_e32 v54, v129
	v_mov_b32_e32 v55, v129
	v_mov_b32_e32 v56, 0
	v_mov_b32_e32 v57, v129
	v_mov_b32_e32 v58, v129
	v_mov_b32_e32 v59, v129
	v_mov_b32_e32 v60, 0
	v_mov_b32_e32 v61, v129
	v_mov_b32_e32 v62, v129
	v_mov_b32_e32 v63, v129
	v_mov_b32_e32 v64, 0
	v_mov_b32_e32 v65, v129
	v_mov_b32_e32 v66, v129
	v_mov_b32_e32 v67, v129
	v_mov_b32_e32 v68, 0
	v_mov_b32_e32 v69, v129
	v_mov_b32_e32 v70, v129
	v_mov_b32_e32 v71, v129
	v_mov_b32_e32 v72, 0
	v_mov_b32_e32 v73, v129
	v_mov_b32_e32 v74, v129
	v_mov_b32_e32 v75, v129
	v_mov_b32_e32 v76, 0
	v_mov_b32_e32 v77, v129
	v_mov_b32_e32 v78, v129
	v_mov_b32_e32 v79, v129
	v_mov_b32_e32 v80, 0
	v_mov_b32_e32 v81, v129
	v_mov_b32_e32 v82, v129
	v_mov_b32_e32 v83, v129
	v_mov_b32_e32 v84, 0
	v_mov_b32_e32 v85, v129
	v_mov_b32_e32 v86, v129
	v_mov_b32_e32 v87, v129
	v_mov_b32_e32 v88, 0
	v_mov_b32_e32 v89, v129
	v_mov_b32_e32 v90, v129
	v_mov_b32_e32 v91, v129
	v_mov_b32_e32 v92, 0
	v_mov_b32_e32 v93, v129
	v_mov_b32_e32 v94, v129
	v_mov_b32_e32 v95, v129
	v_mov_b32_e32 v96, 0
	v_mov_b32_e32 v97, v129
	v_mov_b32_e32 v98, v129
	v_mov_b32_e32 v99, v129
	v_mov_b32_e32 v100, 0
	v_mov_b32_e32 v101, v129
	v_mov_b32_e32 v102, v129
	v_mov_b32_e32 v103, v129
	v_mov_b32_e32 v104, 0
	v_mov_b32_e32 v105, v129
	v_mov_b32_e32 v106, v129
	v_mov_b32_e32 v107, v129
	v_mov_b32_e32 v108, 0
	v_mov_b32_e32 v109, v129
	v_mov_b32_e32 v110, v129
	v_mov_b32_e32 v111, v129
	v_mov_b32_e32 v112, 0
	v_mov_b32_e32 v113, v129
	v_mov_b32_e32 v114, v129
	v_mov_b32_e32 v115, v129
	v_mov_b32_e32 v116, 0
	v_mov_b32_e32 v117, v129
	v_mov_b32_e32 v118, v129
	v_mov_b32_e32 v119, v129
	v_mov_b32_e32 v120, 0
	v_mov_b32_e32 v121, v129
	v_mov_b32_e32 v122, v129
	v_mov_b32_e32 v123, v129
	v_mov_b32_e32 v124, 0
	v_mov_b32_e32 v125, v129
	v_mov_b32_e32 v126, v129
	v_mov_b32_e32 v127, v129
	s_waitcnt vmcnt(0) lgkmcnt(0)
	s_barrier
	v_readfirstlane_b32 s100, v149
	s_and_b32 s29, s15, 0x10000
	s_xor_b32 s30, s29, 0x10000
	s_add_i32 s29, s29, 0
	v_add3_u32 v128, s29, v150, v151
	v_add3_u32 v161, s29, v150, v152
	v_add3_u32 v194, s29, v154, v153
	v_add3_u32 v195, s29, v154, v155
	v_add3_u32 v196, s29, v154, v156
	v_add3_u32 v197, s29, v154, v157
	v_add3_u32 v198, s29, v154, v158
	v_add3_u32 v199, s29, v154, v159
	v_add3_u32 v200, s29, v154, v160
	ds_read_b128 v[178:181], v128 offset:32768
	ds_read_b128 v[162:165], v161
	ds_read_b128 v[166:169], v194
	ds_read_b128 v[170:173], v195
	ds_read_b128 v[174:177], v196
	ds_read_b128 v[182:185], v128 offset:34816
	ds_read_b128 v[186:189], v128 offset:36864
	ds_read_b128 v[190:193], v128 offset:38912
	s_add_i32 s101, s100, s30
	v_readfirstlane_b32 s98, v146
	v_readfirstlane_b32 s99, v147
	v_readfirstlane_b32 vcc_lo, v138
	v_readfirstlane_b32 vcc_hi, v139
	s_sub_u32 s98, s98, 0x1000000
	s_subb_u32 s99, s99, 0
	s_sub_u32 vcc_lo, vcc_lo, 0x1000000
	s_subb_u32 vcc_hi, vcc_hi, 0
	v_subrev_u32_e32 v146, s98, v146
	v_subrev_u32_e32 v138, vcc_lo, v138
	v_subrev_u32_e32 v144, s98, v144
	v_subrev_u32_e32 v136, vcc_lo, v136
	v_subrev_u32_e32 v142, s98, v142
	v_subrev_u32_e32 v134, vcc_lo, v134
	v_subrev_u32_e32 v140, s98, v140
	v_subrev_u32_e32 v130, vcc_lo, v130
	s_mov_b32 m0, s101
	s_nop 0
	global_load_lds_dwordx4 v146, s[98:99]
	s_add_i32 m0, s101, 0x8000
	s_nop 0
	global_load_lds_dwordx4 v138, vcc
	s_add_i32 m0, s101, 0x2000
	s_nop 0
	global_load_lds_dwordx4 v144, s[98:99]
	s_add_i32 m0, s101, 0xa000
	s_nop 0
	global_load_lds_dwordx4 v136, vcc
	s_add_i32 m0, s101, 0x4000
	s_nop 0
	global_load_lds_dwordx4 v142, s[98:99]
	s_add_i32 m0, s101, 0xc000
	s_nop 0
	global_load_lds_dwordx4 v134, vcc
	s_add_i32 m0, s101, 0x6000
	s_nop 0
	global_load_lds_dwordx4 v140, s[98:99]
	s_add_i32 m0, s101, 0xe000
	s_nop 0
	global_load_lds_dwordx4 v130, vcc

.LBB0_1137:
	s_ashr_i32 s10, s23, 31
	s_lshr_b32 s10, s10, 26
	s_add_i32 s10, s23, s10
	s_ashr_i32 s11, s10, 6
	s_and_b32 s10, s10, 0xffc0
	s_sub_i32 s10, s23, s10
	s_bfe_i32 s12, s10, 0x80000
	s_bfe_u32 s12, s12, 0x4000b
	v_mov_b32_e32 v148, v132
	v_mov_b32_e32 v18, v132
	s_add_i32 s12, s10, s12
	ds_read_b64 v[0:1], v133
	s_lshl_b32 s25, s11, 4
	v_lshlrev_b32_e32 v9, 4, v18
	v_and_b32_e32 v8, 32, v18
	s_and_b32 s11, s12, 0xf0
	v_bfe_u32 v19, v18, 2, 4
	v_lshrrev_b32_e32 v10, 1, v18
	v_bitop3_b32 v8, v9, v8, 48 bitop3:0x6c
	v_ashrrev_i32_e32 v22, 3, v18
	s_sub_i32 s10, s10, s11
	v_and_b32_e32 v20, 32, v10
	v_lshrrev_b32_e32 v21, 1, v8
	v_and_or_b32 v8, v22, s14, v19
	s_bfe_i32 s13, s12, 0x80000
	s_sext_i32_i8 s10, s10
	v_or_b32_e32 v12, v21, v20
	v_mul_u32_u24_e32 v8, 0xb00, v8
	s_sext_i32_i16 s13, s13
	s_add_i32 s25, s25, s10
	v_and_b32_e32 v11, 0xfffffc00, v9
	v_or_b32_e32 v128, v12, v8
	v_add_u32_e32 v8, 0x2000, v9
	v_add_u32_e32 v10, 0x4000, v9
	v_add_u32_e32 v9, 0x6000, v9
	s_ashr_i32 s26, s13, 4
	s_lshl_b32 s24, s25, 8
	v_ashrrev_i32_e32 v23, 7, v8
	v_ashrrev_i32_e32 v24, 7, v10
	v_ashrrev_i32_e32 v25, 7, v9
	s_lshl_b32 s10, s26, 8
	s_mul_i32 s12, s25, 0x160000
	s_mul_hi_i32 s13, s24, 0x1600
	v_and_or_b32 v8, v23, s14, v19
	v_and_or_b32 v10, v24, s14, v19
	v_and_or_b32 v9, v25, s14, v19
	s_waitcnt lgkmcnt(0)
	v_lshl_add_u64 v[2:3], v[0:1], 0, s[12:13]
	s_mul_i32 s12, s26, 0x160000
	s_mul_hi_i32 s13, s10, 0x1600
	v_mul_u32_u24_e32 v8, 0xb00, v8
	v_mul_u32_u24_e32 v10, 0xb00, v10
	v_mul_u32_u24_e32 v9, 0xb00, v9
	v_add_u32_e32 v149, 0, v11
	v_lshl_add_u64 v[4:5], v[2:3], 0, s[0:1]
	v_lshl_add_u64 v[0:1], v[0:1], 0, s[12:13]
	v_or_b32_e32 v8, v8, v12
	v_or_b32_e32 v10, v10, v12
	v_or_b32_e32 v12, v9, v12
	v_add_u32_e32 v9, 0x8000, v149
	v_lshlrev_b64 v[14:15], 1, v[128:129]
	v_readfirstlane_b32 s12, v149
	v_lshl_add_u64 v[6:7], v[0:1], 0, s[4:5]
	v_lshl_add_u64 v[16:17], v[4:5], 0, v[14:15]
	s_mov_b32 m0, s12
	v_readfirstlane_b32 s12, v9
	v_mov_b32_e32 v9, v129
	v_add_u32_e32 v11, 0x2000, v149
	global_load_lds_dwordx4 v[16:17], off
	v_lshl_add_u64 v[14:15], v[6:7], 0, v[14:15]
	s_mov_b32 m0, s12
	v_lshlrev_b64 v[8:9], 1, v[8:9]
	v_readfirstlane_b32 s12, v11
	v_add_u32_e32 v11, 0xa000, v149
	global_load_lds_dwordx4 v[14:15], off
	v_lshl_add_u64 v[14:15], v[4:5], 0, v[8:9]
	s_mov_b32 m0, s12
	v_readfirstlane_b32 s12, v11
	global_load_lds_dwordx4 v[14:15], off
	v_lshl_add_u64 v[8:9], v[6:7], 0, v[8:9]
	s_mov_b32 m0, s12
	v_mov_b32_e32 v11, v129
	v_add_u32_e32 v13, 0x4000, v149
	global_load_lds_dwordx4 v[8:9], off
	v_lshlrev_b64 v[8:9], 1, v[10:11]
	v_readfirstlane_b32 s12, v13
	v_lshl_add_u64 v[10:11], v[4:5], 0, v[8:9]
	s_mov_b32 m0, s12
	v_lshl_add_u64 v[8:9], v[6:7], 0, v[8:9]
	global_load_lds_dwordx4 v[10:11], off
	v_add_u32_e32 v10, 0xc000, v149
	v_mov_b32_e32 v13, v129
	v_readfirstlane_b32 s12, v10
	s_mov_b32 m0, s12
	v_add_u32_e32 v10, 0x6000, v149
	global_load_lds_dwordx4 v[8:9], off
	v_lshlrev_b64 v[8:9], 1, v[12:13]
	v_readfirstlane_b32 s12, v10
	v_lshl_add_u64 v[4:5], v[4:5], 0, v[8:9]
	s_mov_b32 m0, s12
	v_and_b32_e32 v26, 15, v18
	global_load_lds_dwordx4 v[4:5], off
	v_lshl_add_u64 v[4:5], v[6:7], 0, v[8:9]
	v_add_u32_e32 v6, 0xe000, v149
	v_lshrrev_b32_e32 v8, 4, v23
	v_readfirstlane_b32 s12, v6
	s_mov_b32 m0, s12
	v_lshlrev_b32_e32 v6, 2, v18
	global_load_lds_dwordx4 v[4:5], off
	v_and_b32_e32 v4, 48, v18
	v_lshlrev_b32_e32 v5, 6, v26
	v_and_b32_e32 v6, 32, v6
	v_bitop3_b32 v150, v5, v6, v4 bitop3:0x36
	v_lshlrev_b32_e32 v5, 7, v18
	v_and_b32_e32 v151, 0x6000, v5
	v_lshlrev_b32_e32 v5, 6, v18
	v_and_b32_e32 v152, 0xffffc000, v5
	v_and_b32_e32 v5, 0x3c0, v5
	v_bitop3_b32 v154, v5, v6, v4 bitop3:0x36
	v_lshrrev_b32_e32 v4, 4, v25
	v_mul_lo_u32 v4, v4, s16
	v_lshrrev_b32_e32 v6, 4, v24
	v_or_b32_e32 v4, v21, v4
	v_mul_lo_u32 v6, v6, s16
	v_mad_u32_u24 v4, v19, s15, v4
	v_or_b32_e32 v6, v21, v6
	v_mul_lo_u32 v8, v8, s16
	v_lshrrev_b32_e32 v10, 4, v22
	v_or_b32_e32 v128, v4, v20
	v_mad_u32_u24 v6, v19, s15, v6
	v_or_b32_e32 v8, v21, v8
	v_mul_lo_u32 v10, v10, s16
	v_lshlrev_b64 v[4:5], 1, v[128:129]
	v_or_b32_e32 v128, v6, v20
	v_mad_u32_u24 v8, v19, s15, v8
	v_or_b32_e32 v10, v21, v10
	v_lshlrev_b64 v[6:7], 1, v[128:129]
	v_or_b32_e32 v128, v8, v20
	v_mad_u32_u24 v10, v19, s15, v10
	v_lshlrev_b64 v[8:9], 1, v[128:129]
	v_or_b32_e32 v128, v10, v20
	s_nop 0
	v_lshl_add_u64 v[0:1], v[0:1], 0, s[6:7]
	v_lshlrev_b64 v[10:11], 1, v[128:129]
	v_lshl_add_u64 v[130:131], v[0:1], 0, v[4:5]
	v_lshl_add_u64 v[134:135], v[0:1], 0, v[6:7]
	v_lshl_add_u64 v[136:137], v[0:1], 0, v[8:9]
	v_lshl_add_u64 v[138:139], v[0:1], 0, v[10:11]
	v_lshl_add_u64 v[0:1], v[2:3], 0, s[8:9]
	s_ashr_i32 s11, s10, 31
	v_or_b32_e32 v153, 0x800, v152
	v_or_b32_e32 v155, 0x1000, v152
	v_or_b32_e32 v156, 0x1800, v152
	v_or_b32_e32 v157, 0x2000, v152
	v_or_b32_e32 v158, 0x2800, v152
	v_or_b32_e32 v159, 0x3000, v152
	v_or_b32_e32 v160, 0x3800, v152
	v_lshl_add_u64 v[140:141], v[0:1], 0, v[4:5]
	v_lshl_add_u64 v[142:143], v[0:1], 0, v[6:7]
	v_lshl_add_u64 v[144:145], v[0:1], 0, v[8:9]
	v_lshl_add_u64 v[146:147], v[0:1], 0, v[10:11]
	s_mov_b64 s[12:13], 0
	s_mov_b32 s26, 0
	v_mov_b32_e32 v12, 0
	v_mov_b32_e32 v14, v129
	v_mov_b32_e32 v15, v129
	v_mov_b32_e32 v20, 0
	v_mov_b32_e32 v21, v129
	v_mov_b32_e32 v22, v129
	v_mov_b32_e32 v23, v129
	v_mov_b32_e32 v28, 0
	v_mov_b32_e32 v29, v129
	v_mov_b32_e32 v30, v129
	v_mov_b32_e32 v31, v129
	v_mov_b32_e32 v36, 0
	v_mov_b32_e32 v37, v129
	v_mov_b32_e32 v38, v129
	v_mov_b32_e32 v39, v129
	v_mov_b32_e32 v0, 0
	v_mov_b32_e32 v1, v129
	v_mov_b32_e32 v2, v129
	v_mov_b32_e32 v3, v129
	v_mov_b32_e32 v4, 0
	v_mov_b32_e32 v5, v129
	v_mov_b32_e32 v6, v129
	v_mov_b32_e32 v7, v129
	v_mov_b32_e32 v8, 0
	v_mov_b32_e32 v9, v129
	v_mov_b32_e32 v10, v129
	v_mov_b32_e32 v11, v129
	v_mov_b32_e32 v16, 0
	v_mov_b32_e32 v17, v129
	v_mov_b32_e32 v18, v129
	v_mov_b32_e32 v19, v129
	v_mov_b32_e32 v24, 0
	v_mov_b32_e32 v25, v129
	v_mov_b32_e32 v26, v129
	v_mov_b32_e32 v27, v129
	v_mov_b32_e32 v32, 0
	v_mov_b32_e32 v33, v129
	v_mov_b32_e32 v34, v129
	v_mov_b32_e32 v35, v129
	v_mov_b32_e32 v40, 0
	v_mov_b32_e32 v41, v129
	v_mov_b32_e32 v42, v129
	v_mov_b32_e32 v43, v129
	v_mov_b32_e32 v44, 0
	v_mov_b32_e32 v45, v129
	v_mov_b32_e32 v46, v129
	v_mov_b32_e32 v47, v129
	v_mov_b32_e32 v48, 0
	v_mov_b32_e32 v49, v129
	v_mov_b32_e32 v50, v129
	v_mov_b32_e32 v51, v129
	v_mov_b32_e32 v52, 0
	v_mov_b32_e32 v53, v129
	v_mov_b32_e32 v54, v129
	v_mov_b32_e32 v55, v129
	v_mov_b32_e32 v56, 0
	v_mov_b32_e32 v57, v129
	v_mov_b32_e32 v58, v129
	v_mov_b32_e32 v59, v129
	v_mov_b32_e32 v60, 0
	v_mov_b32_e32 v61, v129
	v_mov_b32_e32 v62, v129
	v_mov_b32_e32 v63, v129
	v_mov_b32_e32 v64, 0
	v_mov_b32_e32 v65, v129
	v_mov_b32_e32 v66, v129
	v_mov_b32_e32 v67, v129
	v_mov_b32_e32 v68, 0
	v_mov_b32_e32 v69, v129
	v_mov_b32_e32 v70, v129
	v_mov_b32_e32 v71, v129
	v_mov_b32_e32 v72, 0
	v_mov_b32_e32 v73, v129
	v_mov_b32_e32 v74, v129
	v_mov_b32_e32 v75, v129
	v_mov_b32_e32 v76, 0
	v_mov_b32_e32 v77, v129
	v_mov_b32_e32 v78, v129
	v_mov_b32_e32 v79, v129
	v_mov_b32_e32 v80, 0
	v_mov_b32_e32 v81, v129
	v_mov_b32_e32 v82, v129
	v_mov_b32_e32 v83, v129
	v_mov_b32_e32 v84, 0
	v_mov_b32_e32 v85, v129
	v_mov_b32_e32 v86, v129
	v_mov_b32_e32 v87, v129
	v_mov_b32_e32 v88, 0
	v_mov_b32_e32 v89, v129
	v_mov_b32_e32 v90, v129
	v_mov_b32_e32 v91, v129
	v_mov_b32_e32 v92, 0
	v_mov_b32_e32 v93, v129
	v_mov_b32_e32 v94, v129
	v_mov_b32_e32 v95, v129
	v_mov_b32_e32 v96, 0
	v_mov_b32_e32 v97, v129
	v_mov_b32_e32 v98, v129
	v_mov_b32_e32 v99, v129
	v_mov_b32_e32 v100, 0
	v_mov_b32_e32 v101, v129
	v_mov_b32_e32 v102, v129
	v_mov_b32_e32 v103, v129
	v_mov_b32_e32 v104, 0
	v_mov_b32_e32 v105, v129
	v_mov_b32_e32 v106, v129
	v_mov_b32_e32 v107, v129
	v_mov_b32_e32 v108, 0
	v_mov_b32_e32 v109, v129
	v_mov_b32_e32 v110, v129
	v_mov_b32_e32 v111, v129
	v_mov_b32_e32 v112, 0
	v_mov_b32_e32 v113, v129
	v_mov_b32_e32 v114, v129
	v_mov_b32_e32 v115, v129
	v_mov_b32_e32 v116, 0
	v_mov_b32_e32 v117, v129
	v_mov_b32_e32 v118, v129
	v_mov_b32_e32 v119, v129
	v_mov_b32_e32 v120, 0
	v_mov_b32_e32 v121, v129
	v_mov_b32_e32 v122, v129
	v_mov_b32_e32 v123, v129
	v_mov_b32_e32 v124, 0
	v_mov_b32_e32 v125, v129
	v_mov_b32_e32 v126, v129
	v_mov_b32_e32 v127, v129
	s_waitcnt vmcnt(0) lgkmcnt(0)
	s_barrier
	v_readfirstlane_b32 s100, v149
	s_and_b32 s27, s26, 0x10000
	s_xor_b32 s28, s27, 0x10000
	s_add_i32 s27, s27, 0
	v_add3_u32 v128, s27, v150, v151
	v_add3_u32 v161, s27, v150, v152
	v_add3_u32 v194, s27, v154, v153
	v_add3_u32 v195, s27, v154, v155
	v_add3_u32 v196, s27, v154, v156
	v_add3_u32 v197, s27, v154, v157
	v_add3_u32 v198, s27, v154, v158
	v_add3_u32 v199, s27, v154, v159
	v_add3_u32 v200, s27, v154, v160
	ds_read_b128 v[178:181], v128 offset:32768
	ds_read_b128 v[162:165], v161
	ds_read_b128 v[166:169], v194
	ds_read_b128 v[170:173], v195
	ds_read_b128 v[174:177], v196
	ds_read_b128 v[182:185], v128 offset:34816
	ds_read_b128 v[186:189], v128 offset:36864
	ds_read_b128 v[190:193], v128 offset:38912
	s_add_i32 s101, s100, s28
	v_readfirstlane_b32 s98, v146
	v_readfirstlane_b32 s99, v147
	v_readfirstlane_b32 vcc_lo, v138
	v_readfirstlane_b32 vcc_hi, v139
	s_sub_u32 s98, s98, 0x1000000
	s_subb_u32 s99, s99, 0
	s_sub_u32 vcc_lo, vcc_lo, 0x1000000
	s_subb_u32 vcc_hi, vcc_hi, 0
	v_subrev_u32_e32 v146, s98, v146
	v_subrev_u32_e32 v138, vcc_lo, v138
	v_subrev_u32_e32 v144, s98, v144
	v_subrev_u32_e32 v136, vcc_lo, v136
	v_subrev_u32_e32 v142, s98, v142
	v_subrev_u32_e32 v134, vcc_lo, v134
	v_subrev_u32_e32 v140, s98, v140
	v_subrev_u32_e32 v130, vcc_lo, v130
	s_mov_b32 m0, s101
	s_nop 0
	global_load_lds_dwordx4 v146, s[98:99]
	s_add_i32 m0, s101, 0x8000
	s_nop 0
	global_load_lds_dwordx4 v138, vcc
	s_add_i32 m0, s101, 0x2000
	s_nop 0
	global_load_lds_dwordx4 v144, s[98:99]
	s_add_i32 m0, s101, 0xa000
	s_nop 0
	global_load_lds_dwordx4 v136, vcc
	s_add_i32 m0, s101, 0x4000
	s_nop 0
	global_load_lds_dwordx4 v142, s[98:99]
	s_add_i32 m0, s101, 0xc000
	s_nop 0
	global_load_lds_dwordx4 v134, vcc
	s_add_i32 m0, s101, 0x6000
	s_nop 0
	global_load_lds_dwordx4 v140, s[98:99]
	s_add_i32 m0, s101, 0xe000
	s_nop 0
	global_load_lds_dwordx4 v130, vcc
